# non-temporal hint on the residual-epilogue output stores (8 GEMM phases) on top of norm-loop consolidation
# baseline (speedup 1.0000x reference)
; __device__ __forceinline__ u32x4 pack8(const f32x4& a, const f32x4& b) { u32x4 w; w.x = cvt_pk_bf16(a[0], a[1]); w.y = cvt_pk_bf16(a[2], a[3]); w.z = cvt_pk_bf16(b[0], b[1]); w.w = cvt_pk_bf16(b[2], b[3]); return w; }
;     __device__ __forceinline__ void operator()(const f32x4 (&acc)[2][2][4][2], const Unit& u, int wr, int wc, int fr, int fq) const {
;         const int row0 = u.pm * BM + wr * 64 + fr, col0 = u.pn * BM + wc * 32 + 8 * fq;
;         const float* gp = gate + (size_t)(u.pm >> 3) * 12288 + col0;
;         f32x4 gv[2][2];
; #pragma unroll
;         for (int bj = 0; bj < 2; ++bj)
; #pragma unroll
;             for (int n = 0; n < 2; ++n) { gv[bj][n] = *(const f32x4*)(gp + bj * HALF + n * 4); if (cscale) gv[bj][n] = gv[bj][n] * *(const f32x4*)(cscale + col0 + bj * HALF + n * 4); }
;         if constexpr (XIN_F32) {
; #pragma unroll
;             for (int ai = 0; ai < 2; ++ai)
; #pragma unroll
;                 for (int mh = 0; mh < 2; ++mh) { f32x4 xv[2][2][2];
; #pragma unroll
;                     for (int m2 = 0; m2 < 2; ++m2)
; #pragma unroll
;                         for (int bj = 0; bj < 2; ++bj) { const float* p = (const float*)xin + (size_t)(row0 + ai * HALF + (2 * mh + m2) * 16) * 2048 + col0 + bj * HALF; xv[m2][bj][0] = *(const f32x4*)p; xv[m2][bj][1] = *(const f32x4*)(p + 4); }
; #pragma unroll
;                     for (int m2 = 0; m2 < 2; ++m2)
; #pragma unroll
;                         for (int bj = 0; bj < 2; ++bj) { const int m = 2 * mh + m2;
;                             *(u32x4*)(xout + (size_t)(row0 + ai * HALF + m * 16) * 2048 + col0 + bj * HALF) = pack8(xv[m2][bj][0] + gv[bj][0] * acc[ai][bj][m][0], xv[m2][bj][1] + gv[bj][1] * acc[ai][bj][m][1]); }
;                     asm volatile("" ::: "memory"); }
.LBB0_597:
	v_mov_b32_e32 v1, v252
	s_lshl_b32 s0, s75, 8
	v_ashrrev_i32_e32 v34, 1, v1
	s_or_b32 s0, s0, s82
	v_and_b32_e32 v34, -8, v34
	v_add_u32_e32 v198, s0, v34
	s_ashr_i32 s0, s74, 3
	s_mul_hi_i32 s1, s0, 0xc000
	s_mul_i32 s0, s0, 0xc000
	s_add_u32 s40, s63, s0
	s_addc_u32 s41, s80, s1
	s_lshl_b32 s0, s74, 8
	s_add_i32 s0, s0, s81
	v_ashrrev_i32_e32 v199, 31, v198
	v_and_or_b32 v158, v1, 15, s0
	v_readlane_b32 s0, v255, 15
	v_lshlrev_b64 v[156:157], 2, v[198:199]
	v_readlane_b32 s1, v255, 16
	v_ashrrev_i32_e32 v159, 31, v158
	v_lshl_add_u64 v[38:39], s[40:41], 0, v[156:157]
	v_lshl_add_u64 v[156:157], s[0:1], 0, v[156:157]
	v_lshlrev_b64 v[166:167], 13, v[158:159]
	v_lshl_add_u64 v[178:179], v[156:157], 0, v[166:167]
	global_load_dwordx4 v[42:45], v[38:39], off offset:16
	global_load_dwordx4 v[46:49], v[38:39], off
	global_load_dwordx4 v[34:37], v[38:39], off offset:528
	s_nop 0
	global_load_dwordx4 v[38:41], v[38:39], off offset:512
	s_nop 0
	global_load_dwordx4 v[166:169], v[178:179], off offset:16
	global_load_dwordx4 v[170:173], v[178:179], off
	global_load_dwordx4 v[174:177], v[178:179], off offset:528
	s_nop 0
	global_load_dwordx4 v[178:181], v[178:179], off offset:512
	v_or_b32_e32 v200, 16, v158
	v_ashrrev_i32_e32 v201, 31, v200
	v_lshlrev_b64 v[182:183], 13, v[200:201]
	v_lshl_add_u64 v[194:195], v[156:157], 0, v[182:183]
	global_load_dwordx4 v[182:185], v[194:195], off offset:16
	global_load_dwordx4 v[186:189], v[194:195], off
	global_load_dwordx4 v[190:193], v[194:195], off offset:528
	s_nop 0
	global_load_dwordx4 v[194:197], v[194:195], off offset:512
	v_lshlrev_b64 v[202:203], 12, v[158:159]
	s_mov_b64 s[74:75], -1
	s_andn2_b64 vcc, exec, s[8:9]
	s_waitcnt vmcnt(0)
	v_pk_fma_f32 v[138:139], v[138:139], v[42:43], v[166:167]
	v_pk_fma_f32 v[144:145], v[144:145], v[48:49], v[172:173]
	v_pk_fma_f32 v[142:143], v[142:143], v[46:47], v[170:171]
	v_pk_fma_f32 v[168:169], v[140:141], v[44:45], v[168:169]
	v_cvt_pk_bf16_f32 v140, v142, v143
	v_cvt_pk_bf16_f32 v141, v144, v145
	v_cvt_pk_bf16_f32 v142, v138, v139
	v_lshl_add_u64 v[144:145], s[60:61], 0, v[202:203]
	v_lshlrev_b64 v[138:139], 1, v[198:199]
	v_lshl_add_u64 v[144:145], v[144:145], 0, v[138:139]
	v_cvt_pk_bf16_f32 v143, v168, v169
	global_store_dwordx4 v[144:145], v[140:143], off nt
	v_pk_fma_f32 v[136:137], v[136:137], v[40:41], v[180:181]
	v_pk_fma_f32 v[134:135], v[134:135], v[38:39], v[178:179]
	v_pk_fma_f32 v[140:141], v[132:133], v[36:37], v[176:177]
	v_pk_fma_f32 v[132:133], v[130:131], v[34:35], v[174:175]
	v_cvt_pk_bf16_f32 v130, v134, v135
	v_cvt_pk_bf16_f32 v131, v136, v137
	v_pk_fma_f32 v[118:119], v[118:119], v[46:47], v[186:187]
	v_cvt_pk_bf16_f32 v132, v132, v133
	v_cvt_pk_bf16_f32 v133, v140, v141
	global_store_dwordx4 v[144:145], v[130:133], off offset:256 nt
	v_pk_fma_f32 v[120:121], v[120:121], v[48:49], v[188:189]
	v_or_b32_e32 v144, 32, v158
	v_lshlrev_b64 v[130:131], 12, v[200:201]
	v_pk_fma_f32 v[132:133], v[116:117], v[44:45], v[184:185]
	v_pk_fma_f32 v[116:117], v[114:115], v[42:43], v[182:183]
	v_cvt_pk_bf16_f32 v114, v118, v119
	v_lshl_add_u64 v[118:119], s[60:61], 0, v[130:131]
	v_cvt_pk_bf16_f32 v115, v120, v121
	v_lshl_add_u64 v[118:119], v[118:119], 0, v[138:139]
	v_cvt_pk_bf16_f32 v116, v116, v117
	v_cvt_pk_bf16_f32 v117, v132, v133
	global_store_dwordx4 v[118:119], v[114:117], off nt
	v_ashrrev_i32_e32 v145, 31, v144
	v_pk_fma_f32 v[120:121], v[124:125], v[36:37], v[192:193]
	v_pk_fma_f32 v[114:115], v[126:127], v[38:39], v[194:195]
	v_pk_fma_f32 v[116:117], v[128:129], v[40:41], v[196:197]
	v_cvt_pk_bf16_f32 v114, v114, v115
	v_pk_fma_f32 v[122:123], v[122:123], v[34:35], v[190:191]
	v_cvt_pk_bf16_f32 v115, v116, v117
	v_or_b32_e32 v170, 48, v158
	v_cvt_pk_bf16_f32 v116, v122, v123
	v_cvt_pk_bf16_f32 v117, v120, v121
	global_store_dwordx4 v[118:119], v[114:117], off offset:256 nt
	v_ashrrev_i32_e32 v171, 31, v170
	v_lshlrev_b64 v[130:131], 13, v[170:171]
	v_lshlrev_b64 v[114:115], 13, v[144:145]
	v_lshl_add_u64 v[126:127], v[156:157], 0, v[114:115]
	global_load_dwordx4 v[114:117], v[126:127], off offset:16
	global_load_dwordx4 v[118:121], v[126:127], off
	global_load_dwordx4 v[122:125], v[126:127], off offset:528
	s_nop 0
	global_load_dwordx4 v[126:129], v[126:127], off offset:512
	v_lshl_add_u64 v[166:167], v[156:157], 0, v[130:131]
	global_load_dwordx4 v[130:133], v[166:167], off offset:16
	global_load_dwordx4 v[134:137], v[166:167], off
	global_load_dwordx4 v[140:143], v[166:167], off offset:528
	s_nop 0
	global_load_dwordx4 v[166:169], v[166:167], off offset:512
	v_lshlrev_b64 v[144:145], 12, v[144:145]
	s_waitcnt vmcnt(7)
	v_pk_fma_f32 v[116:117], v[100:101], v[44:45], v[116:117]
	s_waitcnt vmcnt(6)
	v_pk_fma_f32 v[102:103], v[102:103], v[46:47], v[118:119]
	v_pk_fma_f32 v[100:101], v[98:99], v[42:43], v[114:115]
	v_cvt_pk_bf16_f32 v98, v102, v103
	v_lshl_add_u64 v[102:103], s[60:61], 0, v[144:145]
	v_pk_fma_f32 v[104:105], v[104:105], v[48:49], v[120:121]
	v_lshl_add_u64 v[102:103], v[102:103], 0, v[138:139]
	v_cvt_pk_bf16_f32 v99, v104, v105
	v_cvt_pk_bf16_f32 v100, v100, v101
	v_cvt_pk_bf16_f32 v101, v116, v117
	global_store_dwordx4 v[102:103], v[98:101], off nt
	s_waitcnt vmcnt(6)
	v_pk_fma_f32 v[104:105], v[108:109], v[36:37], v[124:125]
	v_pk_fma_f32 v[106:107], v[106:107], v[34:35], v[122:123]
	s_waitcnt vmcnt(5)
	v_pk_fma_f32 v[98:99], v[110:111], v[38:39], v[126:127]
	v_pk_fma_f32 v[100:101], v[112:113], v[40:41], v[128:129]
	v_cvt_pk_bf16_f32 v98, v98, v99
	s_waitcnt vmcnt(3)
; __device__ __forceinline__ u32x4 pack8(const f32x4& a, const f32x4& b) { u32x4 w; w.x = cvt_pk_bf16(a[0], a[1]); w.y = cvt_pk_bf16(a[2], a[3]); w.z = cvt_pk_bf16(b[0], b[1]); w.w = cvt_pk_bf16(b[2], b[3]); return w; }
; #define PG8_BAR __builtin_amdgcn_s_barrier()
;     __device__ __forceinline__ void operator()(const f32x4 (&acc)[2][2][4][2], const Unit& u, int wr, int wc, int fr, int fq) const {
;     ...
;         if constexpr (XIN_F32) {
; #pragma unroll
;             for (int ai = 0; ai < 2; ++ai)
; #pragma unroll
;                 for (int mh = 0; mh < 2; ++mh) { f32x4 xv[2][2][2];
; #pragma unroll
;                     for (int m2 = 0; m2 < 2; ++m2)
; #pragma unroll
;                         for (int bj = 0; bj < 2; ++bj) { const float* p = (const float*)xin + (size_t)(row0 + ai * HALF + (2 * mh + m2) * 16) * 2048 + col0 + bj * HALF; xv[m2][bj][0] = *(const f32x4*)p; xv[m2][bj][1] = *(const f32x4*)(p + 4); }
; #pragma unroll
;                     for (int m2 = 0; m2 < 2; ++m2)
; #pragma unroll
;                         for (int bj = 0; bj < 2; ++bj) { const int m = 2 * mh + m2;
;                             *(u32x4*)(xout + (size_t)(row0 + ai * HALF + m * 16) * 2048 + col0 + bj * HALF) = pack8(xv[m2][bj][0] + gv[bj][0] * acc[ai][bj][m][0], xv[m2][bj][1] + gv[bj][1] * acc[ai][bj][m][1]); }
;                     asm volatile("" ::: "memory"); }
; template <class Epi, class Sched, bool ALIGN_EPI = true, bool SP2 = true, bool FULLLINE = false, bool NOSTAGE = false, bool FP8 = false>
; __device__ __forceinline__ void gemm_phase(PG8_LAS unsigned char* lds, const Gemm g, const Sched& S, const Epi& E) {
;     ...
;         if (!has_next) break;
; #pragma unroll
;         for (int a = 0; a < 2; ++a)
; #pragma unroll
;             for (int b = 0; b < 2; ++b)
; #pragma unroll
;                 for (int m = 0; m < 4; ++m)
; #pragma unroll
;                     for (int n = 0; n < 2; ++n) acc[a][b][m][n] = (f32x4){0.f, 0.f, 0.f, 0.f};
;         cur = nxt; cA = nA; cB = nB; ++ui;
;         if constexpr (ALIGN_EPI) { if (wr == 1) PG8_BAR; }
	v_pk_fma_f32 v[86:87], v[86:87], v[46:47], v[134:135]
	v_cvt_pk_bf16_f32 v99, v100, v101
	v_cvt_pk_bf16_f32 v100, v106, v107
	v_cvt_pk_bf16_f32 v101, v104, v105
	global_store_dwordx4 v[102:103], v[98:101], off offset:256 nt
	v_pk_fma_f32 v[88:89], v[88:89], v[48:49], v[136:137]
	v_add_u32_e32 v114, 0x80, v158
	v_lshlrev_b64 v[98:99], 12, v[170:171]
	v_pk_fma_f32 v[100:101], v[84:85], v[44:45], v[132:133]
	v_pk_fma_f32 v[84:85], v[82:83], v[42:43], v[130:131]
	v_cvt_pk_bf16_f32 v82, v86, v87
	v_lshl_add_u64 v[86:87], s[60:61], 0, v[98:99]
	v_cvt_pk_bf16_f32 v83, v88, v89
	v_lshl_add_u64 v[86:87], v[86:87], 0, v[138:139]
	v_cvt_pk_bf16_f32 v84, v84, v85
	v_cvt_pk_bf16_f32 v85, v100, v101
	global_store_dwordx4 v[86:87], v[82:85], off nt
	v_ashrrev_i32_e32 v115, 31, v114
	s_waitcnt vmcnt(4)
	v_pk_fma_f32 v[88:89], v[92:93], v[36:37], v[142:143]
	s_waitcnt vmcnt(3)
	v_pk_fma_f32 v[82:83], v[94:95], v[38:39], v[166:167]
	v_pk_fma_f32 v[84:85], v[96:97], v[40:41], v[168:169]
	v_cvt_pk_bf16_f32 v82, v82, v83
	v_pk_fma_f32 v[90:91], v[90:91], v[34:35], v[140:141]
	v_cvt_pk_bf16_f32 v83, v84, v85
	v_add_u32_e32 v116, 0x90, v158
	v_cvt_pk_bf16_f32 v84, v90, v91
	v_cvt_pk_bf16_f32 v85, v88, v89
	global_store_dwordx4 v[86:87], v[82:85], off offset:256 nt
	v_ashrrev_i32_e32 v117, 31, v116
	v_lshlrev_b64 v[98:99], 13, v[116:117]
	v_lshlrev_b64 v[82:83], 13, v[114:115]
	v_lshl_add_u64 v[94:95], v[156:157], 0, v[82:83]
	global_load_dwordx4 v[82:85], v[94:95], off offset:16
	global_load_dwordx4 v[86:89], v[94:95], off
	global_load_dwordx4 v[90:93], v[94:95], off offset:528
	s_nop 0
	global_load_dwordx4 v[94:97], v[94:95], off offset:512
	v_lshl_add_u64 v[110:111], v[156:157], 0, v[98:99]
	global_load_dwordx4 v[98:101], v[110:111], off offset:16
	global_load_dwordx4 v[102:105], v[110:111], off
	global_load_dwordx4 v[106:109], v[110:111], off offset:528
	s_nop 0
	global_load_dwordx4 v[110:113], v[110:111], off offset:512
	v_lshlrev_b64 v[114:115], 12, v[114:115]
	s_waitcnt vmcnt(7)
	v_pk_fma_f32 v[84:85], v[68:69], v[44:45], v[84:85]
	s_waitcnt vmcnt(6)
	v_pk_fma_f32 v[70:71], v[70:71], v[46:47], v[86:87]
	v_pk_fma_f32 v[68:69], v[66:67], v[42:43], v[82:83]
	v_cvt_pk_bf16_f32 v66, v70, v71
	v_lshl_add_u64 v[70:71], s[60:61], 0, v[114:115]
	v_pk_fma_f32 v[72:73], v[72:73], v[48:49], v[88:89]
	v_lshl_add_u64 v[70:71], v[70:71], 0, v[138:139]
	v_cvt_pk_bf16_f32 v67, v72, v73
	v_cvt_pk_bf16_f32 v68, v68, v69
	v_cvt_pk_bf16_f32 v69, v84, v85
	global_store_dwordx4 v[70:71], v[66:69], off nt
	s_waitcnt vmcnt(6)
	v_pk_fma_f32 v[72:73], v[76:77], v[36:37], v[92:93]
	v_pk_fma_f32 v[74:75], v[74:75], v[34:35], v[90:91]
	s_waitcnt vmcnt(5)
	v_pk_fma_f32 v[66:67], v[78:79], v[38:39], v[94:95]
	v_pk_fma_f32 v[68:69], v[80:81], v[40:41], v[96:97]
	v_cvt_pk_bf16_f32 v66, v66, v67
	s_waitcnt vmcnt(3)
	v_pk_fma_f32 v[54:55], v[54:55], v[46:47], v[102:103]
	v_cvt_pk_bf16_f32 v67, v68, v69
	v_cvt_pk_bf16_f32 v68, v74, v75
	v_cvt_pk_bf16_f32 v69, v72, v73
	global_store_dwordx4 v[70:71], v[66:69], off offset:256 nt
	v_pk_fma_f32 v[56:57], v[56:57], v[48:49], v[104:105]
	v_add_u32_e32 v82, 0xa0, v158
	v_lshlrev_b64 v[66:67], 12, v[116:117]
	v_pk_fma_f32 v[68:69], v[52:53], v[44:45], v[100:101]
	v_pk_fma_f32 v[52:53], v[50:51], v[42:43], v[98:99]
	v_cvt_pk_bf16_f32 v50, v54, v55
	v_lshl_add_u64 v[54:55], s[60:61], 0, v[66:67]
	v_cvt_pk_bf16_f32 v51, v56, v57
	v_lshl_add_u64 v[54:55], v[54:55], 0, v[138:139]
	v_cvt_pk_bf16_f32 v52, v52, v53
	v_cvt_pk_bf16_f32 v53, v68, v69
	global_store_dwordx4 v[54:55], v[50:53], off nt
	v_ashrrev_i32_e32 v83, 31, v82
	s_waitcnt vmcnt(4)
	v_pk_fma_f32 v[56:57], v[60:61], v[36:37], v[108:109]
	s_waitcnt vmcnt(3)
	v_pk_fma_f32 v[50:51], v[62:63], v[38:39], v[110:111]
	v_pk_fma_f32 v[52:53], v[64:65], v[40:41], v[112:113]
	v_cvt_pk_bf16_f32 v50, v50, v51
	v_pk_fma_f32 v[58:59], v[58:59], v[34:35], v[106:107]
	v_cvt_pk_bf16_f32 v51, v52, v53
	v_add_u32_e32 v84, 0xb0, v158
	v_cvt_pk_bf16_f32 v52, v58, v59
	v_cvt_pk_bf16_f32 v53, v56, v57
	global_store_dwordx4 v[54:55], v[50:53], off offset:256 nt
	v_ashrrev_i32_e32 v85, 31, v84
	s_nop 0
	v_lshlrev_b64 v[50:51], 13, v[82:83]
	v_lshl_add_u64 v[50:51], v[156:157], 0, v[50:51]
	global_load_dwordx4 v[58:61], v[50:51], off offset:16
	global_load_dwordx4 v[62:65], v[50:51], off
	global_load_dwordx4 v[66:69], v[50:51], off offset:528
	global_load_dwordx4 v[70:73], v[50:51], off offset:512
	v_lshlrev_b64 v[50:51], 13, v[84:85]
	v_lshl_add_u64 v[54:55], v[156:157], 0, v[50:51]
	global_load_dwordx4 v[74:77], v[54:55], off offset:16
	global_load_dwordx4 v[78:81], v[54:55], off
	global_load_dwordx4 v[50:53], v[54:55], off offset:528
	s_nop 0
	global_load_dwordx4 v[54:57], v[54:55], off offset:512
	v_lshlrev_b64 v[82:83], 12, v[82:83]
	s_waitcnt vmcnt(7)
	v_pk_fma_f32 v[60:61], v[20:21], v[44:45], v[60:61]
	s_waitcnt vmcnt(6)
	v_pk_fma_f32 v[22:23], v[22:23], v[46:47], v[62:63]
	v_pk_fma_f32 v[20:21], v[18:19], v[42:43], v[58:59]
	v_cvt_pk_bf16_f32 v18, v22, v23
	v_lshl_add_u64 v[22:23], s[60:61], 0, v[82:83]
	v_pk_fma_f32 v[24:25], v[24:25], v[48:49], v[64:65]
	v_lshl_add_u64 v[22:23], v[22:23], 0, v[138:139]
	v_cvt_pk_bf16_f32 v19, v24, v25
	v_cvt_pk_bf16_f32 v20, v20, v21
	v_cvt_pk_bf16_f32 v21, v60, v61
	global_store_dwordx4 v[22:23], v[18:21], off nt
	s_waitcnt vmcnt(6)
	v_pk_fma_f32 v[24:25], v[28:29], v[36:37], v[68:69]
	v_pk_fma_f32 v[26:27], v[26:27], v[34:35], v[66:67]
	s_waitcnt vmcnt(5)
	v_pk_fma_f32 v[18:19], v[30:31], v[38:39], v[70:71]
	v_pk_fma_f32 v[20:21], v[32:33], v[40:41], v[72:73]
	v_cvt_pk_bf16_f32 v18, v18, v19
	s_waitcnt vmcnt(3)
	v_pk_fma_f32 v[14:15], v[14:15], v[46:47], v[78:79]
	v_cvt_pk_bf16_f32 v19, v20, v21
	v_cvt_pk_bf16_f32 v20, v26, v27
	v_cvt_pk_bf16_f32 v21, v24, v25
	global_store_dwordx4 v[22:23], v[18:21], off offset:256 nt
	v_pk_fma_f32 v[16:17], v[16:17], v[48:49], v[80:81]
	s_waitcnt vmcnt(2)
	v_pk_fma_f32 v[8:9], v[8:9], v[40:41], v[56:57]
	v_lshlrev_b64 v[18:19], 12, v[84:85]
	v_pk_fma_f32 v[20:21], v[12:13], v[44:45], v[76:77]
	v_pk_fma_f32 v[12:13], v[10:11], v[42:43], v[74:75]
	v_cvt_pk_bf16_f32 v10, v14, v15
	v_lshl_add_u64 v[14:15], s[60:61], 0, v[18:19]
	v_cvt_pk_bf16_f32 v11, v16, v17
	v_lshl_add_u64 v[14:15], v[14:15], 0, v[138:139]
	v_cvt_pk_bf16_f32 v12, v12, v13
	v_cvt_pk_bf16_f32 v13, v20, v21
	global_store_dwordx4 v[14:15], v[10:13], off nt
	v_pk_fma_f32 v[6:7], v[6:7], v[38:39], v[54:55]
	s_nop 0
	v_pk_fma_f32 v[10:11], v[4:5], v[36:37], v[52:53]
	v_pk_fma_f32 v[4:5], v[2:3], v[34:35], v[50:51]
	v_cvt_pk_bf16_f32 v2, v6, v7
	v_cvt_pk_bf16_f32 v3, v8, v9
	s_nop 0
	v_cvt_pk_bf16_f32 v4, v4, v5
	v_cvt_pk_bf16_f32 v5, v10, v11
	global_store_dwordx4 v[14:15], v[2:5], off offset:256 nt
	s_cbranch_vccnz .LBB0_586
	s_and_b64 vcc, exec, s[6:7]
	s_cbranch_vccnz .LBB0_585
	s_barrier
	s_branch .LBB0_585

; __device__ __forceinline__ u32x4 pack8(const f32x4& a, const f32x4& b) { u32x4 w; w.x = cvt_pk_bf16(a[0], a[1]); w.y = cvt_pk_bf16(a[2], a[3]); w.z = cvt_pk_bf16(b[0], b[1]); w.w = cvt_pk_bf16(b[2], b[3]); return w; }
;     __device__ __forceinline__ void operator()(const f32x4 (&acc)[2][2][4][2], const Unit& u, int wr, int wc, int fr, int fq) const {
;         const int row0 = u.pm * BM + wr * 64 + fr, col0 = u.pn * BM + wc * 32 + 8 * fq;
;         const float* gp = gate + (size_t)(u.pm >> 3) * 12288 + col0;
;         f32x4 gv[2][2];
; #pragma unroll
;         for (int bj = 0; bj < 2; ++bj)
; #pragma unroll
;             for (int n = 0; n < 2; ++n) { gv[bj][n] = *(const f32x4*)(gp + bj * HALF + n * 4); if (cscale) gv[bj][n] = gv[bj][n] * *(const f32x4*)(cscale + col0 + bj * HALF + n * 4); }
;     ...
;             for (int ai = 0; ai < 2; ++ai) { u32x4 xw[4][2];
; #pragma unroll
;                 for (int m = 0; m < 4; ++m)
; #pragma unroll
;                     for (int bj = 0; bj < 2; ++bj) xw[m][bj] = *(const u32x4*)((const bf16_t*)xin + (size_t)(row0 + ai * HALF + m * 16) * 2048 + col0 + bj * HALF);
; #pragma unroll
;                 for (int m = 0; m < 4; ++m)
; #pragma unroll
;                     for (int bj = 0; bj < 2; ++bj) { const u32x4 w = xw[m][bj];
;                         const f32x4 x0 = (f32x4){__builtin_bit_cast(float, w.x << 16), __builtin_bit_cast(float, w.x & 0xffff0000u), __builtin_bit_cast(float, w.y << 16), __builtin_bit_cast(float, w.y & 0xffff0000u)};
;                         const f32x4 x1 = (f32x4){__builtin_bit_cast(float, w.z << 16), __builtin_bit_cast(float, w.z & 0xffff0000u), __builtin_bit_cast(float, w.w << 16), __builtin_bit_cast(float, w.w & 0xffff0000u)};
;                         *(u32x4*)(xout + (size_t)(row0 + ai * HALF + m * 16) * 2048 + col0 + bj * HALF) = pack8(x0 + gv[bj][0] * acc[ai][bj][m][0], x1 + gv[bj][1] * acc[ai][bj][m][1]); }
.LBB0_873:
	v_mov_b32_e32 v140, v252
	s_lshl_b32 s0, s84, 8
	v_ashrrev_i32_e32 v74, 1, v140
	s_or_b32 s0, s0, s74
	v_and_b32_e32 v74, -8, v74
	v_add_u32_e32 v138, s0, v74
	s_ashr_i32 s0, s83, 3
	s_mul_hi_i32 s1, s0, 0xc000
	s_mul_i32 s0, s0, 0xc000
	s_add_u32 s40, s55, s0
	s_addc_u32 s41, s62, s1
	s_lshl_b32 s0, s83, 8
	s_add_i32 s0, s0, s63
	v_ashrrev_i32_e32 v139, 31, v138
	v_and_or_b32 v140, v140, 15, s0
	v_lshlrev_b64 v[180:181], 1, v[138:139]
	v_ashrrev_i32_e32 v141, 31, v140
	v_lshl_add_u64 v[182:183], s[60:61], 0, v[180:181]
	v_lshlrev_b64 v[184:185], 12, v[140:141]
	v_lshl_add_u64 v[82:83], v[138:139], 2, s[40:41]
	v_lshl_add_u64 v[138:139], v[182:183], 0, v[184:185]
	global_load_dwordx4 v[90:93], v[82:83], off offset:16
	global_load_dwordx4 v[94:97], v[82:83], off
	global_load_dwordx4 v[74:77], v[82:83], off offset:528
	s_nop 0
	global_load_dwordx4 v[82:85], v[82:83], off offset:512
	s_nop 0
	global_load_dwordx4 v[196:199], v[138:139], off
	global_load_dwordx4 v[200:203], v[138:139], off offset:256
	v_or_b32_e32 v138, 16, v140
	v_ashrrev_i32_e32 v139, 31, v138
	v_lshlrev_b64 v[190:191], 12, v[138:139]
	v_lshl_add_u64 v[138:139], v[182:183], 0, v[190:191]
	global_load_dwordx4 v[166:169], v[138:139], off
	global_load_dwordx4 v[162:165], v[138:139], off offset:256
	v_or_b32_e32 v138, 32, v140
	v_ashrrev_i32_e32 v139, 31, v138
	v_lshlrev_b64 v[188:189], 12, v[138:139]
	v_lshl_add_u64 v[138:139], v[182:183], 0, v[188:189]
	global_load_dwordx4 v[158:161], v[138:139], off
	global_load_dwordx4 v[154:157], v[138:139], off offset:256
	v_or_b32_e32 v138, 48, v140
	v_ashrrev_i32_e32 v139, 31, v138
	v_lshlrev_b64 v[186:187], 12, v[138:139]
	v_lshl_add_u64 v[138:139], v[182:183], 0, v[186:187]
	global_load_dwordx4 v[150:153], v[138:139], off
	s_nop 0
	global_load_dwordx4 v[138:141], v[138:139], off offset:256
	s_mov_b64 s[40:41], 0x80000
	s_mov_b64 s[70:71], -1
	s_and_b64 vcc, exec, s[8:9]
	s_waitcnt vmcnt(0)
	v_lshlrev_b32_e32 v204, 16, v196
	v_and_b32_e32 v205, 0xffff0000, v196
	v_lshlrev_b32_e32 v196, 16, v197
	v_and_b32_e32 v197, 0xffff0000, v197
	v_lshlrev_b32_e32 v206, 16, v198
	v_and_b32_e32 v207, 0xffff0000, v198
	v_lshlrev_b32_e32 v198, 16, v199
	v_and_b32_e32 v199, 0xffff0000, v199
	v_pk_fma_f32 v[146:147], v[146:147], v[94:95], v[204:205]
	v_pk_fma_f32 v[148:149], v[148:149], v[96:97], v[196:197]
	v_pk_fma_f32 v[196:197], v[144:145], v[92:93], v[198:199]
	v_pk_fma_f32 v[144:145], v[142:143], v[90:91], v[206:207]
	v_cvt_pk_bf16_f32 v142, v146, v147
	v_lshl_add_u64 v[146:147], s[60:61], 0, v[184:185]
	v_cvt_pk_bf16_f32 v143, v148, v149
	v_cvt_pk_bf16_f32 v144, v144, v145
	v_cvt_pk_bf16_f32 v145, v196, v197
	v_lshl_add_u64 v[146:147], v[146:147], 0, v[180:181]
	global_store_dwordx4 v[146:147], v[142:145], off nt
	v_lshlrev_b32_e32 v148, 16, v202
	v_and_b32_e32 v149, 0xffff0000, v202
	v_lshlrev_b32_e32 v142, 16, v200
	v_and_b32_e32 v143, 0xffff0000, v200
	v_lshlrev_b32_e32 v144, 16, v201
	v_and_b32_e32 v145, 0xffff0000, v201
	v_lshlrev_b32_e32 v196, 16, v203
	v_and_b32_e32 v197, 0xffff0000, v203
	v_pk_fma_f32 v[136:137], v[136:137], v[84:85], v[144:145]
	v_pk_fma_f32 v[134:135], v[134:135], v[82:83], v[142:143]
	v_pk_fma_f32 v[142:143], v[132:133], v[76:77], v[196:197]
	v_pk_fma_f32 v[132:133], v[130:131], v[74:75], v[148:149]
	v_cvt_pk_bf16_f32 v130, v134, v135
	v_cvt_pk_bf16_f32 v131, v136, v137
	v_lshlrev_b32_e32 v134, 16, v168
	v_cvt_pk_bf16_f32 v132, v132, v133
	v_cvt_pk_bf16_f32 v133, v142, v143
	global_store_dwordx4 v[146:147], v[130:133], off offset:256 nt
	v_and_b32_e32 v135, 0xffff0000, v168
	v_lshlrev_b32_e32 v136, 16, v169
	v_lshlrev_b32_e32 v130, 16, v166
	v_and_b32_e32 v131, 0xffff0000, v166
	v_and_b32_e32 v137, 0xffff0000, v169
	v_pk_fma_f32 v[126:127], v[126:127], v[94:95], v[130:131]
	v_lshlrev_b32_e32 v132, 16, v167
	v_and_b32_e32 v133, 0xffff0000, v167
	v_pk_fma_f32 v[130:131], v[124:125], v[92:93], v[136:137]
	v_pk_fma_f32 v[124:125], v[122:123], v[90:91], v[134:135]
	v_cvt_pk_bf16_f32 v122, v126, v127
	v_lshl_add_u64 v[126:127], s[60:61], 0, v[190:191]
	v_pk_fma_f32 v[128:129], v[128:129], v[96:97], v[132:133]
	v_lshl_add_u64 v[126:127], v[126:127], 0, v[180:181]
	v_cvt_pk_bf16_f32 v123, v128, v129
	v_cvt_pk_bf16_f32 v124, v124, v125
	v_cvt_pk_bf16_f32 v125, v130, v131
	global_store_dwordx4 v[126:127], v[122:125], off nt
	v_lshlrev_b32_e32 v128, 16, v164
	v_and_b32_e32 v129, 0xffff0000, v164
	v_lshlrev_b32_e32 v122, 16, v162
	v_and_b32_e32 v123, 0xffff0000, v162
	v_lshlrev_b32_e32 v124, 16, v163
	v_and_b32_e32 v125, 0xffff0000, v163
	v_lshlrev_b32_e32 v130, 16, v165
	v_and_b32_e32 v131, 0xffff0000, v165
	v_pk_fma_f32 v[120:121], v[120:121], v[84:85], v[124:125]
	v_pk_fma_f32 v[118:119], v[118:119], v[82:83], v[122:123]
	v_pk_fma_f32 v[122:123], v[116:117], v[76:77], v[130:131]
	v_pk_fma_f32 v[116:117], v[114:115], v[74:75], v[128:129]
	v_cvt_pk_bf16_f32 v114, v118, v119
	v_cvt_pk_bf16_f32 v115, v120, v121
	v_lshlrev_b32_e32 v118, 16, v160
	v_cvt_pk_bf16_f32 v116, v116, v117
	v_cvt_pk_bf16_f32 v117, v122, v123
	global_store_dwordx4 v[126:127], v[114:117], off offset:256 nt
	v_and_b32_e32 v119, 0xffff0000, v160
	v_lshlrev_b32_e32 v120, 16, v161
	v_lshlrev_b32_e32 v114, 16, v158
	v_and_b32_e32 v115, 0xffff0000, v158
	v_and_b32_e32 v121, 0xffff0000, v161
	v_pk_fma_f32 v[110:111], v[110:111], v[94:95], v[114:115]
	v_lshlrev_b32_e32 v116, 16, v159
	v_and_b32_e32 v117, 0xffff0000, v159
	v_pk_fma_f32 v[114:115], v[108:109], v[92:93], v[120:121]
	v_pk_fma_f32 v[108:109], v[106:107], v[90:91], v[118:119]
	v_cvt_pk_bf16_f32 v106, v110, v111
	v_lshl_add_u64 v[110:111], s[60:61], 0, v[188:189]
	v_pk_fma_f32 v[112:113], v[112:113], v[96:97], v[116:117]
; __device__ __forceinline__ u32x4 pack8(const f32x4& a, const f32x4& b) { u32x4 w; w.x = cvt_pk_bf16(a[0], a[1]); w.y = cvt_pk_bf16(a[2], a[3]); w.z = cvt_pk_bf16(b[0], b[1]); w.w = cvt_pk_bf16(b[2], b[3]); return w; }
;     __device__ __forceinline__ void operator()(const f32x4 (&acc)[2][2][4][2], const Unit& u, int wr, int wc, int fr, int fq) const {
;     ...
;             for (int ai = 0; ai < 2; ++ai) { u32x4 xw[4][2];
; #pragma unroll
;                 for (int m = 0; m < 4; ++m)
; #pragma unroll
;                     for (int bj = 0; bj < 2; ++bj) xw[m][bj] = *(const u32x4*)((const bf16_t*)xin + (size_t)(row0 + ai * HALF + m * 16) * 2048 + col0 + bj * HALF);
; #pragma unroll
;                 for (int m = 0; m < 4; ++m)
; #pragma unroll
;                     for (int bj = 0; bj < 2; ++bj) { const u32x4 w = xw[m][bj];
;                         const f32x4 x0 = (f32x4){__builtin_bit_cast(float, w.x << 16), __builtin_bit_cast(float, w.x & 0xffff0000u), __builtin_bit_cast(float, w.y << 16), __builtin_bit_cast(float, w.y & 0xffff0000u)};
;                         const f32x4 x1 = (f32x4){__builtin_bit_cast(float, w.z << 16), __builtin_bit_cast(float, w.z & 0xffff0000u), __builtin_bit_cast(float, w.w << 16), __builtin_bit_cast(float, w.w & 0xffff0000u)};
;                         *(u32x4*)(xout + (size_t)(row0 + ai * HALF + m * 16) * 2048 + col0 + bj * HALF) = pack8(x0 + gv[bj][0] * acc[ai][bj][m][0], x1 + gv[bj][1] * acc[ai][bj][m][1]); }
	v_lshl_add_u64 v[110:111], v[110:111], 0, v[180:181]
	v_cvt_pk_bf16_f32 v107, v112, v113
	v_cvt_pk_bf16_f32 v108, v108, v109
	v_cvt_pk_bf16_f32 v109, v114, v115
	global_store_dwordx4 v[110:111], v[106:109], off nt
	v_lshlrev_b32_e32 v112, 16, v156
	v_and_b32_e32 v113, 0xffff0000, v156
	v_lshlrev_b32_e32 v106, 16, v154
	v_and_b32_e32 v107, 0xffff0000, v154
	v_lshlrev_b32_e32 v108, 16, v155
	v_and_b32_e32 v109, 0xffff0000, v155
	v_lshlrev_b32_e32 v114, 16, v157
	v_and_b32_e32 v115, 0xffff0000, v157
	v_pk_fma_f32 v[104:105], v[104:105], v[84:85], v[108:109]
	v_pk_fma_f32 v[102:103], v[102:103], v[82:83], v[106:107]
	v_pk_fma_f32 v[106:107], v[100:101], v[76:77], v[114:115]
	v_pk_fma_f32 v[100:101], v[98:99], v[74:75], v[112:113]
	v_cvt_pk_bf16_f32 v98, v102, v103
	v_cvt_pk_bf16_f32 v99, v104, v105
	v_lshlrev_b32_e32 v102, 16, v152
	v_cvt_pk_bf16_f32 v100, v100, v101
	v_cvt_pk_bf16_f32 v101, v106, v107
	global_store_dwordx4 v[110:111], v[98:101], off offset:256 nt
	v_and_b32_e32 v103, 0xffff0000, v152
	v_lshlrev_b32_e32 v104, 16, v153
	v_lshlrev_b32_e32 v98, 16, v150
	v_and_b32_e32 v99, 0xffff0000, v150
	v_and_b32_e32 v105, 0xffff0000, v153
	v_pk_fma_f32 v[86:87], v[86:87], v[94:95], v[98:99]
	v_lshlrev_b32_e32 v100, 16, v151
	v_and_b32_e32 v101, 0xffff0000, v151
	v_pk_fma_f32 v[98:99], v[80:81], v[92:93], v[104:105]
	v_pk_fma_f32 v[80:81], v[78:79], v[90:91], v[102:103]
	v_cvt_pk_bf16_f32 v78, v86, v87
	v_lshl_add_u64 v[86:87], s[60:61], 0, v[186:187]
	v_pk_fma_f32 v[88:89], v[88:89], v[96:97], v[100:101]
	v_lshl_add_u64 v[86:87], v[86:87], 0, v[180:181]
	v_cvt_pk_bf16_f32 v79, v88, v89
	v_cvt_pk_bf16_f32 v80, v80, v81
	v_cvt_pk_bf16_f32 v81, v98, v99
	global_store_dwordx4 v[86:87], v[78:81], off nt
	v_lshlrev_b32_e32 v88, 16, v140
	v_and_b32_e32 v89, 0xffff0000, v140
	v_lshlrev_b32_e32 v78, 16, v138
	v_and_b32_e32 v79, 0xffff0000, v138
	v_lshlrev_b32_e32 v98, 16, v141
	v_and_b32_e32 v99, 0xffff0000, v141
	v_lshlrev_b32_e32 v80, 16, v139
	v_and_b32_e32 v81, 0xffff0000, v139
	v_pk_fma_f32 v[70:71], v[70:71], v[82:83], v[78:79]
	v_pk_fma_f32 v[78:79], v[68:69], v[76:77], v[98:99]
	v_pk_fma_f32 v[68:69], v[66:67], v[74:75], v[88:89]
	v_pk_fma_f32 v[72:73], v[72:73], v[84:85], v[80:81]
	v_cvt_pk_bf16_f32 v66, v70, v71
	v_lshl_add_u64 v[80:81], v[184:185], 0, s[40:41]
	v_cvt_pk_bf16_f32 v67, v72, v73
	v_cvt_pk_bf16_f32 v68, v68, v69
	v_cvt_pk_bf16_f32 v69, v78, v79
	global_store_dwordx4 v[86:87], v[66:69], off offset:256 nt
	s_mov_b64 s[40:41], 0x90000
	v_lshl_add_u64 v[118:119], v[184:185], 0, s[40:41]
	v_lshl_add_u64 v[66:67], v[182:183], 0, v[80:81]
	global_load_dwordx4 v[86:89], v[66:67], off
	global_load_dwordx4 v[98:101], v[66:67], off offset:256
	v_lshl_add_u64 v[66:67], v[182:183], 0, v[118:119]
	global_load_dwordx4 v[102:105], v[66:67], off
	global_load_dwordx4 v[106:109], v[66:67], off offset:256
	s_mov_b64 s[40:41], 0xa0000
	v_lshl_add_u64 v[120:121], v[184:185], 0, s[40:41]
	v_lshl_add_u64 v[66:67], v[182:183], 0, v[120:121]
	global_load_dwordx4 v[110:113], v[66:67], off
	global_load_dwordx4 v[114:117], v[66:67], off offset:256
	v_lshl_add_u64 v[78:79], v[184:185], 0, s[30:31]
	v_lshl_add_u64 v[66:67], v[182:183], 0, v[78:79]
	global_load_dwordx4 v[70:73], v[66:67], off
	s_nop 0
	global_load_dwordx4 v[66:69], v[66:67], off offset:256
	s_waitcnt vmcnt(7)
	v_lshlrev_b32_e32 v122, 16, v86
	v_and_b32_e32 v123, 0xffff0000, v86
	v_lshlrev_b32_e32 v86, 16, v87
	v_and_b32_e32 v87, 0xffff0000, v87
	v_lshlrev_b32_e32 v124, 16, v88
	v_and_b32_e32 v125, 0xffff0000, v88
	v_lshlrev_b32_e32 v88, 16, v89
	v_and_b32_e32 v89, 0xffff0000, v89
	v_pk_fma_f32 v[62:63], v[62:63], v[94:95], v[122:123]
	v_pk_fma_f32 v[64:65], v[64:65], v[96:97], v[86:87]
	v_pk_fma_f32 v[86:87], v[60:61], v[92:93], v[88:89]
	v_pk_fma_f32 v[60:61], v[58:59], v[90:91], v[124:125]
	v_cvt_pk_bf16_f32 v58, v62, v63
	v_lshl_add_u64 v[62:63], s[60:61], 0, v[80:81]
	v_cvt_pk_bf16_f32 v59, v64, v65
	v_cvt_pk_bf16_f32 v60, v60, v61
	v_cvt_pk_bf16_f32 v61, v86, v87
	v_lshl_add_u64 v[62:63], v[62:63], 0, v[180:181]
	global_store_dwordx4 v[62:63], v[58:61], off nt
	s_waitcnt vmcnt(7)
	v_lshlrev_b32_e32 v64, 16, v100
	v_and_b32_e32 v65, 0xffff0000, v100
	v_lshlrev_b32_e32 v58, 16, v98
	v_and_b32_e32 v59, 0xffff0000, v98
	v_lshlrev_b32_e32 v60, 16, v99
	v_and_b32_e32 v61, 0xffff0000, v99
	v_lshlrev_b32_e32 v80, 16, v101
	v_and_b32_e32 v81, 0xffff0000, v101
	v_pk_fma_f32 v[56:57], v[56:57], v[84:85], v[60:61]
	v_pk_fma_f32 v[54:55], v[54:55], v[82:83], v[58:59]
	v_pk_fma_f32 v[58:59], v[52:53], v[76:77], v[80:81]
	v_pk_fma_f32 v[52:53], v[50:51], v[74:75], v[64:65]
	v_cvt_pk_bf16_f32 v50, v54, v55
	v_cvt_pk_bf16_f32 v51, v56, v57
	s_waitcnt vmcnt(6)
; __device__ __forceinline__ u32x4 pack8(const f32x4& a, const f32x4& b) { u32x4 w; w.x = cvt_pk_bf16(a[0], a[1]); w.y = cvt_pk_bf16(a[2], a[3]); w.z = cvt_pk_bf16(b[0], b[1]); w.w = cvt_pk_bf16(b[2], b[3]); return w; }
; #define PG8_BAR __builtin_amdgcn_s_barrier()
;     __device__ __forceinline__ void operator()(const f32x4 (&acc)[2][2][4][2], const Unit& u, int wr, int wc, int fr, int fq) const {
;     ...
;             for (int ai = 0; ai < 2; ++ai) { u32x4 xw[4][2];
; #pragma unroll
;                 for (int m = 0; m < 4; ++m)
; #pragma unroll
;                     for (int bj = 0; bj < 2; ++bj) xw[m][bj] = *(const u32x4*)((const bf16_t*)xin + (size_t)(row0 + ai * HALF + m * 16) * 2048 + col0 + bj * HALF);
; #pragma unroll
;                 for (int m = 0; m < 4; ++m)
; #pragma unroll
;                     for (int bj = 0; bj < 2; ++bj) { const u32x4 w = xw[m][bj];
;                         const f32x4 x0 = (f32x4){__builtin_bit_cast(float, w.x << 16), __builtin_bit_cast(float, w.x & 0xffff0000u), __builtin_bit_cast(float, w.y << 16), __builtin_bit_cast(float, w.y & 0xffff0000u)};
;                         const f32x4 x1 = (f32x4){__builtin_bit_cast(float, w.z << 16), __builtin_bit_cast(float, w.z & 0xffff0000u), __builtin_bit_cast(float, w.w << 16), __builtin_bit_cast(float, w.w & 0xffff0000u)};
;                         *(u32x4*)(xout + (size_t)(row0 + ai * HALF + m * 16) * 2048 + col0 + bj * HALF) = pack8(x0 + gv[bj][0] * acc[ai][bj][m][0], x1 + gv[bj][1] * acc[ai][bj][m][1]); }
;                 asm volatile("" ::: "memory"); }
; template <class Epi, class Sched, bool ALIGN_EPI = true, bool SP2 = true, bool FULLLINE = false, bool NOSTAGE = false, bool FP8 = false>
; __device__ __forceinline__ void gemm_phase(PG8_LAS unsigned char* lds, const Gemm g, const Sched& S, const Epi& E) {
;     ...
;         if (!has_next) break;
; #pragma unroll
;         for (int a = 0; a < 2; ++a)
; #pragma unroll
;             for (int b = 0; b < 2; ++b)
; #pragma unroll
;                 for (int m = 0; m < 4; ++m)
; #pragma unroll
;                     for (int n = 0; n < 2; ++n) acc[a][b][m][n] = (f32x4){0.f, 0.f, 0.f, 0.f};
;         cur = nxt; cA = nA; cB = nB; ++ui;
;         if constexpr (ALIGN_EPI) { if (wr == 1) PG8_BAR; }
	v_lshlrev_b32_e32 v54, 16, v104
	v_cvt_pk_bf16_f32 v52, v52, v53
	v_cvt_pk_bf16_f32 v53, v58, v59
	global_store_dwordx4 v[62:63], v[50:53], off offset:256 nt
	v_and_b32_e32 v55, 0xffff0000, v104
	v_lshlrev_b32_e32 v56, 16, v105
	v_lshlrev_b32_e32 v50, 16, v102
	v_and_b32_e32 v51, 0xffff0000, v102
	v_and_b32_e32 v57, 0xffff0000, v105
	v_pk_fma_f32 v[46:47], v[46:47], v[94:95], v[50:51]
	v_lshlrev_b32_e32 v52, 16, v103
	v_and_b32_e32 v53, 0xffff0000, v103
	v_pk_fma_f32 v[50:51], v[44:45], v[92:93], v[56:57]
	v_pk_fma_f32 v[44:45], v[42:43], v[90:91], v[54:55]
	v_cvt_pk_bf16_f32 v42, v46, v47
	v_lshl_add_u64 v[46:47], s[60:61], 0, v[118:119]
	v_pk_fma_f32 v[48:49], v[48:49], v[96:97], v[52:53]
	v_lshl_add_u64 v[46:47], v[46:47], 0, v[180:181]
	v_cvt_pk_bf16_f32 v43, v48, v49
	v_cvt_pk_bf16_f32 v44, v44, v45
	v_cvt_pk_bf16_f32 v45, v50, v51
	global_store_dwordx4 v[46:47], v[42:45], off nt
	s_waitcnt vmcnt(7)
	v_lshlrev_b32_e32 v48, 16, v108
	v_and_b32_e32 v49, 0xffff0000, v108
	v_lshlrev_b32_e32 v42, 16, v106
	v_and_b32_e32 v43, 0xffff0000, v106
	v_lshlrev_b32_e32 v44, 16, v107
	v_and_b32_e32 v45, 0xffff0000, v107
	v_lshlrev_b32_e32 v50, 16, v109
	v_and_b32_e32 v51, 0xffff0000, v109
	v_pk_fma_f32 v[40:41], v[40:41], v[84:85], v[44:45]
	v_pk_fma_f32 v[38:39], v[38:39], v[82:83], v[42:43]
	v_pk_fma_f32 v[42:43], v[36:37], v[76:77], v[50:51]
	v_pk_fma_f32 v[36:37], v[34:35], v[74:75], v[48:49]
	v_cvt_pk_bf16_f32 v34, v38, v39
	v_cvt_pk_bf16_f32 v35, v40, v41
	s_waitcnt vmcnt(6)
	v_lshlrev_b32_e32 v38, 16, v112
	v_cvt_pk_bf16_f32 v36, v36, v37
	v_cvt_pk_bf16_f32 v37, v42, v43
	global_store_dwordx4 v[46:47], v[34:37], off offset:256 nt
	v_and_b32_e32 v39, 0xffff0000, v112
	v_lshlrev_b32_e32 v40, 16, v113
	v_lshlrev_b32_e32 v34, 16, v110
	v_and_b32_e32 v35, 0xffff0000, v110
	v_and_b32_e32 v41, 0xffff0000, v113
	v_pk_fma_f32 v[30:31], v[30:31], v[94:95], v[34:35]
	v_lshlrev_b32_e32 v36, 16, v111
	v_and_b32_e32 v37, 0xffff0000, v111
	v_pk_fma_f32 v[34:35], v[28:29], v[92:93], v[40:41]
	v_pk_fma_f32 v[28:29], v[26:27], v[90:91], v[38:39]
	v_cvt_pk_bf16_f32 v26, v30, v31
	v_lshl_add_u64 v[30:31], s[60:61], 0, v[120:121]
	v_pk_fma_f32 v[32:33], v[32:33], v[96:97], v[36:37]
	v_lshl_add_u64 v[30:31], v[30:31], 0, v[180:181]
	v_cvt_pk_bf16_f32 v27, v32, v33
	v_cvt_pk_bf16_f32 v28, v28, v29
	v_cvt_pk_bf16_f32 v29, v34, v35
	global_store_dwordx4 v[30:31], v[26:29], off nt
	s_waitcnt vmcnt(7)
	v_lshlrev_b32_e32 v32, 16, v116
	v_and_b32_e32 v33, 0xffff0000, v116
	v_lshlrev_b32_e32 v26, 16, v114
	v_and_b32_e32 v27, 0xffff0000, v114
	v_lshlrev_b32_e32 v28, 16, v115
	v_and_b32_e32 v29, 0xffff0000, v115
	v_lshlrev_b32_e32 v34, 16, v117
	v_and_b32_e32 v35, 0xffff0000, v117
	v_pk_fma_f32 v[24:25], v[24:25], v[84:85], v[28:29]
	v_pk_fma_f32 v[22:23], v[22:23], v[82:83], v[26:27]
	v_pk_fma_f32 v[26:27], v[20:21], v[76:77], v[34:35]
	v_pk_fma_f32 v[20:21], v[18:19], v[74:75], v[32:33]
	v_cvt_pk_bf16_f32 v18, v22, v23
	v_cvt_pk_bf16_f32 v19, v24, v25
	s_waitcnt vmcnt(6)
	v_lshlrev_b32_e32 v22, 16, v72
	v_cvt_pk_bf16_f32 v20, v20, v21
	v_cvt_pk_bf16_f32 v21, v26, v27
	global_store_dwordx4 v[30:31], v[18:21], off offset:256 nt
	v_and_b32_e32 v23, 0xffff0000, v72
	v_lshlrev_b32_e32 v24, 16, v73
	v_lshlrev_b32_e32 v18, 16, v70
	v_and_b32_e32 v19, 0xffff0000, v70
	v_and_b32_e32 v25, 0xffff0000, v73
	v_pk_fma_f32 v[14:15], v[14:15], v[94:95], v[18:19]
	v_lshlrev_b32_e32 v20, 16, v71
	v_and_b32_e32 v21, 0xffff0000, v71
	v_pk_fma_f32 v[18:19], v[12:13], v[92:93], v[24:25]
	v_pk_fma_f32 v[12:13], v[10:11], v[90:91], v[22:23]
	v_cvt_pk_bf16_f32 v10, v14, v15
	v_lshl_add_u64 v[14:15], s[60:61], 0, v[78:79]
	v_pk_fma_f32 v[16:17], v[16:17], v[96:97], v[20:21]
	v_lshl_add_u64 v[14:15], v[14:15], 0, v[180:181]
	v_cvt_pk_bf16_f32 v11, v16, v17
	v_cvt_pk_bf16_f32 v12, v12, v13
	v_cvt_pk_bf16_f32 v13, v18, v19
	global_store_dwordx4 v[14:15], v[10:13], off nt
	s_waitcnt vmcnt(7)
	v_lshlrev_b32_e32 v16, 16, v68
	v_and_b32_e32 v17, 0xffff0000, v68
	v_lshlrev_b32_e32 v10, 16, v66
	v_and_b32_e32 v11, 0xffff0000, v66
	v_lshlrev_b32_e32 v18, 16, v69
	v_and_b32_e32 v19, 0xffff0000, v69
	v_lshlrev_b32_e32 v12, 16, v67
	v_and_b32_e32 v13, 0xffff0000, v67
	v_pk_fma_f32 v[6:7], v[6:7], v[82:83], v[10:11]
	v_pk_fma_f32 v[10:11], v[4:5], v[76:77], v[18:19]
	v_pk_fma_f32 v[4:5], v[2:3], v[74:75], v[16:17]
	v_pk_fma_f32 v[8:9], v[8:9], v[84:85], v[12:13]
	v_cvt_pk_bf16_f32 v2, v6, v7
	s_nop 0
	v_cvt_pk_bf16_f32 v3, v8, v9
	v_cvt_pk_bf16_f32 v4, v4, v5
	v_cvt_pk_bf16_f32 v5, v10, v11
	global_store_dwordx4 v[14:15], v[2:5], off offset:256 nt
	s_cbranch_vccnz .LBB0_858
	s_and_b64 vcc, exec, s[6:7]
	s_cbranch_vccnz .LBB0_857
	s_barrier
	s_branch .LBB0_857

; __device__ __forceinline__ u32x4 pack8(const f32x4& a, const f32x4& b) { u32x4 w; w.x = cvt_pk_bf16(a[0], a[1]); w.y = cvt_pk_bf16(a[2], a[3]); w.z = cvt_pk_bf16(b[0], b[1]); w.w = cvt_pk_bf16(b[2], b[3]); return w; }
;     __device__ __forceinline__ void operator()(const f32x4 (&acc)[2][2][4][2], const Unit& u, int wr, int wc, int fr, int fq) const {
;         const int row0 = u.pm * BM + wr * 64 + fr, col0 = u.pn * BM + wc * 32 + 8 * fq;
;         const float* gp = gate + (size_t)(u.pm >> 3) * 12288 + col0;
;         f32x4 gv[2][2];
; #pragma unroll
;         for (int bj = 0; bj < 2; ++bj)
; #pragma unroll
;             for (int n = 0; n < 2; ++n) { gv[bj][n] = *(const f32x4*)(gp + bj * HALF + n * 4); if (cscale) gv[bj][n] = gv[bj][n] * *(const f32x4*)(cscale + col0 + bj * HALF + n * 4); }
;     ...
;             for (int ai = 0; ai < 2; ++ai) { u32x4 xw[4][2];
; #pragma unroll
;                 for (int m = 0; m < 4; ++m)
; #pragma unroll
;                     for (int bj = 0; bj < 2; ++bj) xw[m][bj] = *(const u32x4*)((const bf16_t*)xin + (size_t)(row0 + ai * HALF + m * 16) * 2048 + col0 + bj * HALF);
; #pragma unroll
;                 for (int m = 0; m < 4; ++m)
; #pragma unroll
;                     for (int bj = 0; bj < 2; ++bj) { const u32x4 w = xw[m][bj];
;                         const f32x4 x0 = (f32x4){__builtin_bit_cast(float, w.x << 16), __builtin_bit_cast(float, w.x & 0xffff0000u), __builtin_bit_cast(float, w.y << 16), __builtin_bit_cast(float, w.y & 0xffff0000u)};
;                         const f32x4 x1 = (f32x4){__builtin_bit_cast(float, w.z << 16), __builtin_bit_cast(float, w.z & 0xffff0000u), __builtin_bit_cast(float, w.w << 16), __builtin_bit_cast(float, w.w & 0xffff0000u)};
;                         *(u32x4*)(xout + (size_t)(row0 + ai * HALF + m * 16) * 2048 + col0 + bj * HALF) = pack8(x0 + gv[bj][0] * acc[ai][bj][m][0], x1 + gv[bj][1] * acc[ai][bj][m][1]); }
.LBB0_1211:
	v_mov_b32_e32 v140, v252
	s_lshl_b32 s0, s75, 8
	v_ashrrev_i32_e32 v74, 1, v140
	s_or_b32 s0, s0, s82
	v_and_b32_e32 v74, -8, v74
	v_add_u32_e32 v138, s0, v74
	s_ashr_i32 s0, s74, 3
	s_mul_hi_i32 s1, s0, 0xc000
	s_mul_i32 s0, s0, 0xc000
	s_add_u32 s0, s63, s0
	s_addc_u32 s1, s80, s1
	v_ashrrev_i32_e32 v139, 31, v138
	v_lshl_add_u64 v[82:83], v[138:139], 2, s[0:1]
	s_lshl_b32 s0, s74, 8
	s_add_i32 s0, s0, s81
	v_and_or_b32 v140, v140, 15, s0
	v_lshlrev_b64 v[180:181], 1, v[138:139]
	v_ashrrev_i32_e32 v141, 31, v140
	v_lshl_add_u64 v[182:183], s[60:61], 0, v[180:181]
	v_lshlrev_b64 v[184:185], 12, v[140:141]
	v_lshl_add_u64 v[138:139], v[182:183], 0, v[184:185]
	global_load_dwordx4 v[90:93], v[82:83], off offset:16
	global_load_dwordx4 v[94:97], v[82:83], off
	global_load_dwordx4 v[74:77], v[82:83], off offset:528
	s_nop 0
	global_load_dwordx4 v[82:85], v[82:83], off offset:512
	s_nop 0
	global_load_dwordx4 v[196:199], v[138:139], off
	global_load_dwordx4 v[200:203], v[138:139], off offset:256
	v_or_b32_e32 v138, 16, v140
	v_ashrrev_i32_e32 v139, 31, v138
	v_lshlrev_b64 v[190:191], 12, v[138:139]
	v_lshl_add_u64 v[138:139], v[182:183], 0, v[190:191]
	global_load_dwordx4 v[166:169], v[138:139], off
	global_load_dwordx4 v[162:165], v[138:139], off offset:256
	v_or_b32_e32 v138, 32, v140
	v_ashrrev_i32_e32 v139, 31, v138
	v_lshlrev_b64 v[188:189], 12, v[138:139]
	v_lshl_add_u64 v[138:139], v[182:183], 0, v[188:189]
	global_load_dwordx4 v[158:161], v[138:139], off
	global_load_dwordx4 v[154:157], v[138:139], off offset:256
	v_or_b32_e32 v138, 48, v140
	v_ashrrev_i32_e32 v139, 31, v138
	v_lshlrev_b64 v[186:187], 12, v[138:139]
	v_lshl_add_u64 v[138:139], v[182:183], 0, v[186:187]
	global_load_dwordx4 v[150:153], v[138:139], off
	s_nop 0
	global_load_dwordx4 v[138:141], v[138:139], off offset:256
	s_mov_b64 s[0:1], 0x90000
	s_mov_b64 s[74:75], -1
	s_andn2_b64 vcc, exec, s[8:9]
	s_waitcnt vmcnt(0)
	v_lshlrev_b32_e32 v204, 16, v196
	v_and_b32_e32 v205, 0xffff0000, v196
	v_lshlrev_b32_e32 v196, 16, v197
	v_and_b32_e32 v197, 0xffff0000, v197
	v_lshlrev_b32_e32 v206, 16, v198
	v_and_b32_e32 v207, 0xffff0000, v198
	v_lshlrev_b32_e32 v198, 16, v199
	v_and_b32_e32 v199, 0xffff0000, v199
	v_pk_fma_f32 v[146:147], v[146:147], v[94:95], v[204:205]
	v_pk_fma_f32 v[148:149], v[148:149], v[96:97], v[196:197]
	v_pk_fma_f32 v[196:197], v[144:145], v[92:93], v[198:199]
	v_pk_fma_f32 v[144:145], v[142:143], v[90:91], v[206:207]
	v_cvt_pk_bf16_f32 v142, v146, v147
	v_lshl_add_u64 v[146:147], s[60:61], 0, v[184:185]
	v_cvt_pk_bf16_f32 v143, v148, v149
	v_cvt_pk_bf16_f32 v144, v144, v145
	v_cvt_pk_bf16_f32 v145, v196, v197
	v_lshl_add_u64 v[146:147], v[146:147], 0, v[180:181]
	global_store_dwordx4 v[146:147], v[142:145], off nt
	v_lshlrev_b32_e32 v148, 16, v202
	v_and_b32_e32 v149, 0xffff0000, v202
	v_lshlrev_b32_e32 v142, 16, v200
	v_and_b32_e32 v143, 0xffff0000, v200
	v_lshlrev_b32_e32 v144, 16, v201
	v_and_b32_e32 v145, 0xffff0000, v201
	v_lshlrev_b32_e32 v196, 16, v203
	v_and_b32_e32 v197, 0xffff0000, v203
	v_pk_fma_f32 v[136:137], v[136:137], v[84:85], v[144:145]
	v_pk_fma_f32 v[134:135], v[134:135], v[82:83], v[142:143]
	v_pk_fma_f32 v[142:143], v[132:133], v[76:77], v[196:197]
	v_pk_fma_f32 v[132:133], v[130:131], v[74:75], v[148:149]
	v_cvt_pk_bf16_f32 v130, v134, v135
	v_cvt_pk_bf16_f32 v131, v136, v137
	v_lshlrev_b32_e32 v134, 16, v168
	v_cvt_pk_bf16_f32 v132, v132, v133
	v_cvt_pk_bf16_f32 v133, v142, v143
	global_store_dwordx4 v[146:147], v[130:133], off offset:256 nt
	v_and_b32_e32 v135, 0xffff0000, v168
	v_lshlrev_b32_e32 v136, 16, v169
	v_lshlrev_b32_e32 v130, 16, v166
	v_and_b32_e32 v131, 0xffff0000, v166
	v_and_b32_e32 v137, 0xffff0000, v169
	v_pk_fma_f32 v[126:127], v[126:127], v[94:95], v[130:131]
	v_lshlrev_b32_e32 v132, 16, v167
	v_and_b32_e32 v133, 0xffff0000, v167
	v_pk_fma_f32 v[130:131], v[124:125], v[92:93], v[136:137]
	v_pk_fma_f32 v[124:125], v[122:123], v[90:91], v[134:135]
	v_cvt_pk_bf16_f32 v122, v126, v127
	v_lshl_add_u64 v[126:127], s[60:61], 0, v[190:191]
	v_pk_fma_f32 v[128:129], v[128:129], v[96:97], v[132:133]
	v_lshl_add_u64 v[126:127], v[126:127], 0, v[180:181]
	v_cvt_pk_bf16_f32 v123, v128, v129
	v_cvt_pk_bf16_f32 v124, v124, v125
	v_cvt_pk_bf16_f32 v125, v130, v131
	global_store_dwordx4 v[126:127], v[122:125], off nt
	v_lshlrev_b32_e32 v128, 16, v164
	v_and_b32_e32 v129, 0xffff0000, v164
	v_lshlrev_b32_e32 v122, 16, v162
	v_and_b32_e32 v123, 0xffff0000, v162
	v_lshlrev_b32_e32 v124, 16, v163
	v_and_b32_e32 v125, 0xffff0000, v163
	v_lshlrev_b32_e32 v130, 16, v165
	v_and_b32_e32 v131, 0xffff0000, v165
	v_pk_fma_f32 v[120:121], v[120:121], v[84:85], v[124:125]
	v_pk_fma_f32 v[118:119], v[118:119], v[82:83], v[122:123]
	v_pk_fma_f32 v[122:123], v[116:117], v[76:77], v[130:131]
	v_pk_fma_f32 v[116:117], v[114:115], v[74:75], v[128:129]
	v_cvt_pk_bf16_f32 v114, v118, v119
	v_cvt_pk_bf16_f32 v115, v120, v121
	v_lshlrev_b32_e32 v118, 16, v160
	v_cvt_pk_bf16_f32 v116, v116, v117
	v_cvt_pk_bf16_f32 v117, v122, v123
	global_store_dwordx4 v[126:127], v[114:117], off offset:256 nt
	v_and_b32_e32 v119, 0xffff0000, v160
	v_lshlrev_b32_e32 v120, 16, v161
	v_lshlrev_b32_e32 v114, 16, v158
	v_and_b32_e32 v115, 0xffff0000, v158
	v_and_b32_e32 v121, 0xffff0000, v161
	v_pk_fma_f32 v[110:111], v[110:111], v[94:95], v[114:115]
	v_lshlrev_b32_e32 v116, 16, v159
	v_and_b32_e32 v117, 0xffff0000, v159
	v_pk_fma_f32 v[114:115], v[108:109], v[92:93], v[120:121]
	v_pk_fma_f32 v[108:109], v[106:107], v[90:91], v[118:119]
	v_cvt_pk_bf16_f32 v106, v110, v111
	v_lshl_add_u64 v[110:111], s[60:61], 0, v[188:189]
	v_pk_fma_f32 v[112:113], v[112:113], v[96:97], v[116:117]
; __device__ __forceinline__ u32x4 pack8(const f32x4& a, const f32x4& b) { u32x4 w; w.x = cvt_pk_bf16(a[0], a[1]); w.y = cvt_pk_bf16(a[2], a[3]); w.z = cvt_pk_bf16(b[0], b[1]); w.w = cvt_pk_bf16(b[2], b[3]); return w; }
;     __device__ __forceinline__ void operator()(const f32x4 (&acc)[2][2][4][2], const Unit& u, int wr, int wc, int fr, int fq) const {
;     ...
;             for (int ai = 0; ai < 2; ++ai) { u32x4 xw[4][2];
; #pragma unroll
;                 for (int m = 0; m < 4; ++m)
; #pragma unroll
;                     for (int bj = 0; bj < 2; ++bj) xw[m][bj] = *(const u32x4*)((const bf16_t*)xin + (size_t)(row0 + ai * HALF + m * 16) * 2048 + col0 + bj * HALF);
; #pragma unroll
;                 for (int m = 0; m < 4; ++m)
; #pragma unroll
;                     for (int bj = 0; bj < 2; ++bj) { const u32x4 w = xw[m][bj];
;                         const f32x4 x0 = (f32x4){__builtin_bit_cast(float, w.x << 16), __builtin_bit_cast(float, w.x & 0xffff0000u), __builtin_bit_cast(float, w.y << 16), __builtin_bit_cast(float, w.y & 0xffff0000u)};
;                         const f32x4 x1 = (f32x4){__builtin_bit_cast(float, w.z << 16), __builtin_bit_cast(float, w.z & 0xffff0000u), __builtin_bit_cast(float, w.w << 16), __builtin_bit_cast(float, w.w & 0xffff0000u)};
;                         *(u32x4*)(xout + (size_t)(row0 + ai * HALF + m * 16) * 2048 + col0 + bj * HALF) = pack8(x0 + gv[bj][0] * acc[ai][bj][m][0], x1 + gv[bj][1] * acc[ai][bj][m][1]); }
	v_lshl_add_u64 v[110:111], v[110:111], 0, v[180:181]
	v_cvt_pk_bf16_f32 v107, v112, v113
	v_cvt_pk_bf16_f32 v108, v108, v109
	v_cvt_pk_bf16_f32 v109, v114, v115
	global_store_dwordx4 v[110:111], v[106:109], off nt
	v_lshlrev_b32_e32 v112, 16, v156
	v_and_b32_e32 v113, 0xffff0000, v156
	v_lshlrev_b32_e32 v106, 16, v154
	v_and_b32_e32 v107, 0xffff0000, v154
	v_lshlrev_b32_e32 v108, 16, v155
	v_and_b32_e32 v109, 0xffff0000, v155
	v_lshlrev_b32_e32 v114, 16, v157
	v_and_b32_e32 v115, 0xffff0000, v157
	v_pk_fma_f32 v[104:105], v[104:105], v[84:85], v[108:109]
	v_pk_fma_f32 v[102:103], v[102:103], v[82:83], v[106:107]
	v_pk_fma_f32 v[106:107], v[100:101], v[76:77], v[114:115]
	v_pk_fma_f32 v[100:101], v[98:99], v[74:75], v[112:113]
	v_cvt_pk_bf16_f32 v98, v102, v103
	v_cvt_pk_bf16_f32 v99, v104, v105
	v_lshlrev_b32_e32 v102, 16, v152
	v_cvt_pk_bf16_f32 v100, v100, v101
	v_cvt_pk_bf16_f32 v101, v106, v107
	global_store_dwordx4 v[110:111], v[98:101], off offset:256 nt
	v_and_b32_e32 v103, 0xffff0000, v152
	v_lshlrev_b32_e32 v104, 16, v153
	v_lshlrev_b32_e32 v98, 16, v150
	v_and_b32_e32 v99, 0xffff0000, v150
	v_and_b32_e32 v105, 0xffff0000, v153
	v_pk_fma_f32 v[86:87], v[86:87], v[94:95], v[98:99]
	v_lshlrev_b32_e32 v100, 16, v151
	v_and_b32_e32 v101, 0xffff0000, v151
	v_pk_fma_f32 v[98:99], v[80:81], v[92:93], v[104:105]
	v_pk_fma_f32 v[80:81], v[78:79], v[90:91], v[102:103]
	v_cvt_pk_bf16_f32 v78, v86, v87
	v_lshl_add_u64 v[86:87], s[60:61], 0, v[186:187]
	v_pk_fma_f32 v[88:89], v[88:89], v[96:97], v[100:101]
	v_lshl_add_u64 v[86:87], v[86:87], 0, v[180:181]
	v_cvt_pk_bf16_f32 v79, v88, v89
	v_cvt_pk_bf16_f32 v80, v80, v81
	v_cvt_pk_bf16_f32 v81, v98, v99
	global_store_dwordx4 v[86:87], v[78:81], off nt
	v_lshlrev_b32_e32 v88, 16, v140
	v_and_b32_e32 v89, 0xffff0000, v140
	v_lshlrev_b32_e32 v78, 16, v138
	v_and_b32_e32 v79, 0xffff0000, v138
	v_lshlrev_b32_e32 v98, 16, v141
	v_and_b32_e32 v99, 0xffff0000, v141
	v_lshlrev_b32_e32 v80, 16, v139
	v_and_b32_e32 v81, 0xffff0000, v139
	v_pk_fma_f32 v[70:71], v[70:71], v[82:83], v[78:79]
	v_pk_fma_f32 v[78:79], v[68:69], v[76:77], v[98:99]
	v_pk_fma_f32 v[68:69], v[66:67], v[74:75], v[88:89]
	v_pk_fma_f32 v[72:73], v[72:73], v[84:85], v[80:81]
	v_cvt_pk_bf16_f32 v66, v70, v71
	v_lshl_add_u64 v[80:81], v[184:185], 0, s[30:31]
	v_cvt_pk_bf16_f32 v67, v72, v73
	v_cvt_pk_bf16_f32 v68, v68, v69
	v_cvt_pk_bf16_f32 v69, v78, v79
	global_store_dwordx4 v[86:87], v[66:69], off offset:256 nt
	v_lshl_add_u64 v[118:119], v[184:185], 0, s[0:1]
	s_mov_b64 s[0:1], 0xa0000
	v_lshl_add_u64 v[66:67], v[182:183], 0, v[80:81]
	global_load_dwordx4 v[86:89], v[66:67], off
	global_load_dwordx4 v[98:101], v[66:67], off offset:256
	v_lshl_add_u64 v[66:67], v[182:183], 0, v[118:119]
	global_load_dwordx4 v[102:105], v[66:67], off
	global_load_dwordx4 v[106:109], v[66:67], off offset:256
	v_lshl_add_u64 v[120:121], v[184:185], 0, s[0:1]
	v_lshl_add_u64 v[66:67], v[182:183], 0, v[120:121]
	global_load_dwordx4 v[110:113], v[66:67], off
	global_load_dwordx4 v[114:117], v[66:67], off offset:256
	s_mov_b64 s[0:1], 0xb0000
	v_lshl_add_u64 v[78:79], v[184:185], 0, s[0:1]
	v_lshl_add_u64 v[66:67], v[182:183], 0, v[78:79]
	global_load_dwordx4 v[70:73], v[66:67], off
	s_nop 0
	global_load_dwordx4 v[66:69], v[66:67], off offset:256
	s_waitcnt vmcnt(7)
	v_lshlrev_b32_e32 v122, 16, v86
	v_and_b32_e32 v123, 0xffff0000, v86
	v_lshlrev_b32_e32 v86, 16, v87
	v_and_b32_e32 v87, 0xffff0000, v87
	v_lshlrev_b32_e32 v124, 16, v88
	v_and_b32_e32 v125, 0xffff0000, v88
	v_lshlrev_b32_e32 v88, 16, v89
	v_and_b32_e32 v89, 0xffff0000, v89
	v_pk_fma_f32 v[62:63], v[62:63], v[94:95], v[122:123]
	v_pk_fma_f32 v[64:65], v[64:65], v[96:97], v[86:87]
	v_pk_fma_f32 v[86:87], v[60:61], v[92:93], v[88:89]
	v_pk_fma_f32 v[60:61], v[58:59], v[90:91], v[124:125]
	v_cvt_pk_bf16_f32 v58, v62, v63
	v_lshl_add_u64 v[62:63], s[60:61], 0, v[80:81]
	v_cvt_pk_bf16_f32 v59, v64, v65
	v_cvt_pk_bf16_f32 v60, v60, v61
	v_cvt_pk_bf16_f32 v61, v86, v87
	v_lshl_add_u64 v[62:63], v[62:63], 0, v[180:181]
	global_store_dwordx4 v[62:63], v[58:61], off nt
	s_waitcnt vmcnt(7)
	v_lshlrev_b32_e32 v64, 16, v100
	v_and_b32_e32 v65, 0xffff0000, v100
	v_lshlrev_b32_e32 v58, 16, v98
	v_and_b32_e32 v59, 0xffff0000, v98
	v_lshlrev_b32_e32 v60, 16, v99
	v_and_b32_e32 v61, 0xffff0000, v99
	v_lshlrev_b32_e32 v80, 16, v101
	v_and_b32_e32 v81, 0xffff0000, v101
	v_pk_fma_f32 v[56:57], v[56:57], v[84:85], v[60:61]
	v_pk_fma_f32 v[54:55], v[54:55], v[82:83], v[58:59]
	v_pk_fma_f32 v[58:59], v[52:53], v[76:77], v[80:81]
	v_pk_fma_f32 v[52:53], v[50:51], v[74:75], v[64:65]
	v_cvt_pk_bf16_f32 v50, v54, v55
	v_cvt_pk_bf16_f32 v51, v56, v57
	s_waitcnt vmcnt(6)
; __device__ __forceinline__ u32x4 pack8(const f32x4& a, const f32x4& b) { u32x4 w; w.x = cvt_pk_bf16(a[0], a[1]); w.y = cvt_pk_bf16(a[2], a[3]); w.z = cvt_pk_bf16(b[0], b[1]); w.w = cvt_pk_bf16(b[2], b[3]); return w; }
; #define PG8_BAR __builtin_amdgcn_s_barrier()
;     __device__ __forceinline__ void operator()(const f32x4 (&acc)[2][2][4][2], const Unit& u, int wr, int wc, int fr, int fq) const {
;     ...
;             for (int ai = 0; ai < 2; ++ai) { u32x4 xw[4][2];
; #pragma unroll
;                 for (int m = 0; m < 4; ++m)
; #pragma unroll
;                     for (int bj = 0; bj < 2; ++bj) xw[m][bj] = *(const u32x4*)((const bf16_t*)xin + (size_t)(row0 + ai * HALF + m * 16) * 2048 + col0 + bj * HALF);
; #pragma unroll
;                 for (int m = 0; m < 4; ++m)
; #pragma unroll
;                     for (int bj = 0; bj < 2; ++bj) { const u32x4 w = xw[m][bj];
;                         const f32x4 x0 = (f32x4){__builtin_bit_cast(float, w.x << 16), __builtin_bit_cast(float, w.x & 0xffff0000u), __builtin_bit_cast(float, w.y << 16), __builtin_bit_cast(float, w.y & 0xffff0000u)};
;                         const f32x4 x1 = (f32x4){__builtin_bit_cast(float, w.z << 16), __builtin_bit_cast(float, w.z & 0xffff0000u), __builtin_bit_cast(float, w.w << 16), __builtin_bit_cast(float, w.w & 0xffff0000u)};
;                         *(u32x4*)(xout + (size_t)(row0 + ai * HALF + m * 16) * 2048 + col0 + bj * HALF) = pack8(x0 + gv[bj][0] * acc[ai][bj][m][0], x1 + gv[bj][1] * acc[ai][bj][m][1]); }
;                 asm volatile("" ::: "memory"); }
; template <class Epi, class Sched, bool ALIGN_EPI = true, bool SP2 = true, bool FULLLINE = false, bool NOSTAGE = false, bool FP8 = false>
; __device__ __forceinline__ void gemm_phase(PG8_LAS unsigned char* lds, const Gemm g, const Sched& S, const Epi& E) {
;     ...
;         if (!has_next) break;
; #pragma unroll
;         for (int a = 0; a < 2; ++a)
; #pragma unroll
;             for (int b = 0; b < 2; ++b)
; #pragma unroll
;                 for (int m = 0; m < 4; ++m)
; #pragma unroll
;                     for (int n = 0; n < 2; ++n) acc[a][b][m][n] = (f32x4){0.f, 0.f, 0.f, 0.f};
;         cur = nxt; cA = nA; cB = nB; ++ui;
;         if constexpr (ALIGN_EPI) { if (wr == 1) PG8_BAR; }
	v_lshlrev_b32_e32 v54, 16, v104
	v_cvt_pk_bf16_f32 v52, v52, v53
	v_cvt_pk_bf16_f32 v53, v58, v59
	global_store_dwordx4 v[62:63], v[50:53], off offset:256 nt
	v_and_b32_e32 v55, 0xffff0000, v104
	v_lshlrev_b32_e32 v56, 16, v105
	v_lshlrev_b32_e32 v50, 16, v102
	v_and_b32_e32 v51, 0xffff0000, v102
	v_and_b32_e32 v57, 0xffff0000, v105
	v_pk_fma_f32 v[46:47], v[46:47], v[94:95], v[50:51]
	v_lshlrev_b32_e32 v52, 16, v103
	v_and_b32_e32 v53, 0xffff0000, v103
	v_pk_fma_f32 v[50:51], v[44:45], v[92:93], v[56:57]
	v_pk_fma_f32 v[44:45], v[42:43], v[90:91], v[54:55]
	v_cvt_pk_bf16_f32 v42, v46, v47
	v_lshl_add_u64 v[46:47], s[60:61], 0, v[118:119]
	v_pk_fma_f32 v[48:49], v[48:49], v[96:97], v[52:53]
	v_lshl_add_u64 v[46:47], v[46:47], 0, v[180:181]
	v_cvt_pk_bf16_f32 v43, v48, v49
	v_cvt_pk_bf16_f32 v44, v44, v45
	v_cvt_pk_bf16_f32 v45, v50, v51
	global_store_dwordx4 v[46:47], v[42:45], off nt
	s_waitcnt vmcnt(7)
	v_lshlrev_b32_e32 v48, 16, v108
	v_and_b32_e32 v49, 0xffff0000, v108
	v_lshlrev_b32_e32 v42, 16, v106
	v_and_b32_e32 v43, 0xffff0000, v106
	v_lshlrev_b32_e32 v44, 16, v107
	v_and_b32_e32 v45, 0xffff0000, v107
	v_lshlrev_b32_e32 v50, 16, v109
	v_and_b32_e32 v51, 0xffff0000, v109
	v_pk_fma_f32 v[40:41], v[40:41], v[84:85], v[44:45]
	v_pk_fma_f32 v[38:39], v[38:39], v[82:83], v[42:43]
	v_pk_fma_f32 v[42:43], v[36:37], v[76:77], v[50:51]
	v_pk_fma_f32 v[36:37], v[34:35], v[74:75], v[48:49]
	v_cvt_pk_bf16_f32 v34, v38, v39
	v_cvt_pk_bf16_f32 v35, v40, v41
	s_waitcnt vmcnt(6)
	v_lshlrev_b32_e32 v38, 16, v112
	v_cvt_pk_bf16_f32 v36, v36, v37
	v_cvt_pk_bf16_f32 v37, v42, v43
	global_store_dwordx4 v[46:47], v[34:37], off offset:256 nt
	v_and_b32_e32 v39, 0xffff0000, v112
	v_lshlrev_b32_e32 v40, 16, v113
	v_lshlrev_b32_e32 v34, 16, v110
	v_and_b32_e32 v35, 0xffff0000, v110
	v_and_b32_e32 v41, 0xffff0000, v113
	v_pk_fma_f32 v[30:31], v[30:31], v[94:95], v[34:35]
	v_lshlrev_b32_e32 v36, 16, v111
	v_and_b32_e32 v37, 0xffff0000, v111
	v_pk_fma_f32 v[34:35], v[28:29], v[92:93], v[40:41]
	v_pk_fma_f32 v[28:29], v[26:27], v[90:91], v[38:39]
	v_cvt_pk_bf16_f32 v26, v30, v31
	v_lshl_add_u64 v[30:31], s[60:61], 0, v[120:121]
	v_pk_fma_f32 v[32:33], v[32:33], v[96:97], v[36:37]
	v_lshl_add_u64 v[30:31], v[30:31], 0, v[180:181]
	v_cvt_pk_bf16_f32 v27, v32, v33
	v_cvt_pk_bf16_f32 v28, v28, v29
	v_cvt_pk_bf16_f32 v29, v34, v35
	global_store_dwordx4 v[30:31], v[26:29], off nt
	s_waitcnt vmcnt(7)
	v_lshlrev_b32_e32 v32, 16, v116
	v_and_b32_e32 v33, 0xffff0000, v116
	v_lshlrev_b32_e32 v26, 16, v114
	v_and_b32_e32 v27, 0xffff0000, v114
	v_lshlrev_b32_e32 v28, 16, v115
	v_and_b32_e32 v29, 0xffff0000, v115
	v_lshlrev_b32_e32 v34, 16, v117
	v_and_b32_e32 v35, 0xffff0000, v117
	v_pk_fma_f32 v[24:25], v[24:25], v[84:85], v[28:29]
	v_pk_fma_f32 v[22:23], v[22:23], v[82:83], v[26:27]
	v_pk_fma_f32 v[26:27], v[20:21], v[76:77], v[34:35]
	v_pk_fma_f32 v[20:21], v[18:19], v[74:75], v[32:33]
	v_cvt_pk_bf16_f32 v18, v22, v23
	v_cvt_pk_bf16_f32 v19, v24, v25
	s_waitcnt vmcnt(6)
	v_lshlrev_b32_e32 v22, 16, v72
	v_cvt_pk_bf16_f32 v20, v20, v21
	v_cvt_pk_bf16_f32 v21, v26, v27
	global_store_dwordx4 v[30:31], v[18:21], off offset:256 nt
	v_and_b32_e32 v23, 0xffff0000, v72
	v_lshlrev_b32_e32 v24, 16, v73
	v_lshlrev_b32_e32 v18, 16, v70
	v_and_b32_e32 v19, 0xffff0000, v70
	v_and_b32_e32 v25, 0xffff0000, v73
	v_pk_fma_f32 v[14:15], v[14:15], v[94:95], v[18:19]
	v_lshlrev_b32_e32 v20, 16, v71
	v_and_b32_e32 v21, 0xffff0000, v71
	v_pk_fma_f32 v[18:19], v[12:13], v[92:93], v[24:25]
	v_pk_fma_f32 v[12:13], v[10:11], v[90:91], v[22:23]
	v_cvt_pk_bf16_f32 v10, v14, v15
	v_lshl_add_u64 v[14:15], s[60:61], 0, v[78:79]
	v_pk_fma_f32 v[16:17], v[16:17], v[96:97], v[20:21]
	v_lshl_add_u64 v[14:15], v[14:15], 0, v[180:181]
	v_cvt_pk_bf16_f32 v11, v16, v17
	v_cvt_pk_bf16_f32 v12, v12, v13
	v_cvt_pk_bf16_f32 v13, v18, v19
	global_store_dwordx4 v[14:15], v[10:13], off nt
	s_waitcnt vmcnt(7)
	v_lshlrev_b32_e32 v16, 16, v68
	v_and_b32_e32 v17, 0xffff0000, v68
	v_lshlrev_b32_e32 v10, 16, v66
	v_and_b32_e32 v11, 0xffff0000, v66
	v_lshlrev_b32_e32 v18, 16, v69
	v_and_b32_e32 v19, 0xffff0000, v69
	v_lshlrev_b32_e32 v12, 16, v67
	v_and_b32_e32 v13, 0xffff0000, v67
	v_pk_fma_f32 v[6:7], v[6:7], v[82:83], v[10:11]
	v_pk_fma_f32 v[10:11], v[4:5], v[76:77], v[18:19]
	v_pk_fma_f32 v[4:5], v[2:3], v[74:75], v[16:17]
	v_pk_fma_f32 v[8:9], v[8:9], v[84:85], v[12:13]
	v_cvt_pk_bf16_f32 v2, v6, v7
	s_nop 0
	v_cvt_pk_bf16_f32 v3, v8, v9
	v_cvt_pk_bf16_f32 v4, v4, v5
	v_cvt_pk_bf16_f32 v5, v10, v11
	global_store_dwordx4 v[14:15], v[2:5], off offset:256 nt
	s_cbranch_vccnz .LBB0_1200
	s_and_b64 vcc, exec, s[6:7]
	s_cbranch_vccnz .LBB0_1199
	s_barrier
	s_branch .LBB0_1199

; __device__ __forceinline__ u32x4 pack8(const f32x4& a, const f32x4& b) { u32x4 w; w.x = cvt_pk_bf16(a[0], a[1]); w.y = cvt_pk_bf16(a[2], a[3]); w.z = cvt_pk_bf16(b[0], b[1]); w.w = cvt_pk_bf16(b[2], b[3]); return w; }
;     __device__ __forceinline__ void operator()(const f32x4 (&acc)[2][2][4][2], const Unit& u, int wr, int wc, int fr, int fq) const {
;         const int row0 = u.pm * BM + wr * 64 + fr, col0 = u.pn * BM + wc * 32 + 8 * fq;
;         const float* gp = gate + (size_t)(u.pm >> 3) * 12288 + col0;
;         f32x4 gv[2][2];
; #pragma unroll
;         for (int bj = 0; bj < 2; ++bj)
; #pragma unroll
;             for (int n = 0; n < 2; ++n) { gv[bj][n] = *(const f32x4*)(gp + bj * HALF + n * 4); if (cscale) gv[bj][n] = gv[bj][n] * *(const f32x4*)(cscale + col0 + bj * HALF + n * 4); }
;     ...
;             for (int ai = 0; ai < 2; ++ai) { u32x4 xw[4][2];
; #pragma unroll
;                 for (int m = 0; m < 4; ++m)
; #pragma unroll
;                     for (int bj = 0; bj < 2; ++bj) xw[m][bj] = *(const u32x4*)((const bf16_t*)xin + (size_t)(row0 + ai * HALF + m * 16) * 2048 + col0 + bj * HALF);
; #pragma unroll
;                 for (int m = 0; m < 4; ++m)
; #pragma unroll
;                     for (int bj = 0; bj < 2; ++bj) { const u32x4 w = xw[m][bj];
;                         const f32x4 x0 = (f32x4){__builtin_bit_cast(float, w.x << 16), __builtin_bit_cast(float, w.x & 0xffff0000u), __builtin_bit_cast(float, w.y << 16), __builtin_bit_cast(float, w.y & 0xffff0000u)};
;                         const f32x4 x1 = (f32x4){__builtin_bit_cast(float, w.z << 16), __builtin_bit_cast(float, w.z & 0xffff0000u), __builtin_bit_cast(float, w.w << 16), __builtin_bit_cast(float, w.w & 0xffff0000u)};
;                         *(u32x4*)(xout + (size_t)(row0 + ai * HALF + m * 16) * 2048 + col0 + bj * HALF) = pack8(x0 + gv[bj][0] * acc[ai][bj][m][0], x1 + gv[bj][1] * acc[ai][bj][m][1]); }
.LBB0_1487:
	v_mov_b32_e32 v140, v252
	s_lshl_b32 s0, s84, 8
	v_ashrrev_i32_e32 v74, 1, v140
	s_or_b32 s0, s0, s74
	v_and_b32_e32 v74, -8, v74
	v_add_u32_e32 v138, s0, v74
	s_ashr_i32 s0, s83, 3
	s_mul_hi_i32 s1, s0, 0xc000
	s_mul_i32 s0, s0, 0xc000
	s_add_u32 s0, s55, s0
	s_addc_u32 s1, s62, s1
	v_ashrrev_i32_e32 v139, 31, v138
	v_lshl_add_u64 v[82:83], v[138:139], 2, s[0:1]
	s_lshl_b32 s0, s83, 8
	s_add_i32 s0, s0, s63
	v_and_or_b32 v140, v140, 15, s0
	v_lshlrev_b64 v[180:181], 1, v[138:139]
	v_ashrrev_i32_e32 v141, 31, v140
	v_lshl_add_u64 v[182:183], s[60:61], 0, v[180:181]
	v_lshlrev_b64 v[184:185], 12, v[140:141]
	v_lshl_add_u64 v[138:139], v[182:183], 0, v[184:185]
	global_load_dwordx4 v[90:93], v[82:83], off offset:16
	global_load_dwordx4 v[94:97], v[82:83], off
	global_load_dwordx4 v[74:77], v[82:83], off offset:528
	s_nop 0
	global_load_dwordx4 v[82:85], v[82:83], off offset:512
	s_nop 0
	global_load_dwordx4 v[196:199], v[138:139], off
	global_load_dwordx4 v[200:203], v[138:139], off offset:256
	v_or_b32_e32 v138, 16, v140
	v_ashrrev_i32_e32 v139, 31, v138
	v_lshlrev_b64 v[190:191], 12, v[138:139]
	v_lshl_add_u64 v[138:139], v[182:183], 0, v[190:191]
	global_load_dwordx4 v[166:169], v[138:139], off
	global_load_dwordx4 v[162:165], v[138:139], off offset:256
	v_or_b32_e32 v138, 32, v140
	v_ashrrev_i32_e32 v139, 31, v138
	v_lshlrev_b64 v[188:189], 12, v[138:139]
	v_lshl_add_u64 v[138:139], v[182:183], 0, v[188:189]
	global_load_dwordx4 v[158:161], v[138:139], off
	global_load_dwordx4 v[154:157], v[138:139], off offset:256
	v_or_b32_e32 v138, 48, v140
	v_ashrrev_i32_e32 v139, 31, v138
	v_lshlrev_b64 v[186:187], 12, v[138:139]
	v_lshl_add_u64 v[138:139], v[182:183], 0, v[186:187]
	global_load_dwordx4 v[150:153], v[138:139], off
	s_nop 0
	global_load_dwordx4 v[138:141], v[138:139], off offset:256
	s_mov_b64 s[0:1], 0x80000
	s_mov_b64 s[70:71], -1
	s_and_b64 vcc, exec, s[8:9]
	s_waitcnt vmcnt(0)
	v_lshlrev_b32_e32 v204, 16, v196
	v_and_b32_e32 v205, 0xffff0000, v196
	v_lshlrev_b32_e32 v196, 16, v197
	v_and_b32_e32 v197, 0xffff0000, v197
	v_lshlrev_b32_e32 v206, 16, v198
	v_and_b32_e32 v207, 0xffff0000, v198
	v_lshlrev_b32_e32 v198, 16, v199
	v_and_b32_e32 v199, 0xffff0000, v199
	v_pk_fma_f32 v[146:147], v[146:147], v[94:95], v[204:205]
	v_pk_fma_f32 v[148:149], v[148:149], v[96:97], v[196:197]
	v_pk_fma_f32 v[196:197], v[144:145], v[92:93], v[198:199]
	v_pk_fma_f32 v[144:145], v[142:143], v[90:91], v[206:207]
	v_cvt_pk_bf16_f32 v142, v146, v147
	v_lshl_add_u64 v[146:147], s[60:61], 0, v[184:185]
	v_cvt_pk_bf16_f32 v143, v148, v149
	v_cvt_pk_bf16_f32 v144, v144, v145
	v_cvt_pk_bf16_f32 v145, v196, v197
	v_lshl_add_u64 v[146:147], v[146:147], 0, v[180:181]
	global_store_dwordx4 v[146:147], v[142:145], off nt
	v_lshlrev_b32_e32 v148, 16, v202
	v_and_b32_e32 v149, 0xffff0000, v202
	v_lshlrev_b32_e32 v142, 16, v200
	v_and_b32_e32 v143, 0xffff0000, v200
	v_lshlrev_b32_e32 v144, 16, v201
	v_and_b32_e32 v145, 0xffff0000, v201
	v_lshlrev_b32_e32 v196, 16, v203
	v_and_b32_e32 v197, 0xffff0000, v203
	v_pk_fma_f32 v[136:137], v[136:137], v[84:85], v[144:145]
	v_pk_fma_f32 v[134:135], v[134:135], v[82:83], v[142:143]
	v_pk_fma_f32 v[142:143], v[132:133], v[76:77], v[196:197]
	v_pk_fma_f32 v[132:133], v[130:131], v[74:75], v[148:149]
	v_cvt_pk_bf16_f32 v130, v134, v135
	v_cvt_pk_bf16_f32 v131, v136, v137
	v_lshlrev_b32_e32 v134, 16, v168
	v_cvt_pk_bf16_f32 v132, v132, v133
	v_cvt_pk_bf16_f32 v133, v142, v143
	global_store_dwordx4 v[146:147], v[130:133], off offset:256 nt
	v_and_b32_e32 v135, 0xffff0000, v168
	v_lshlrev_b32_e32 v136, 16, v169
	v_lshlrev_b32_e32 v130, 16, v166
	v_and_b32_e32 v131, 0xffff0000, v166
	v_and_b32_e32 v137, 0xffff0000, v169
	v_pk_fma_f32 v[126:127], v[126:127], v[94:95], v[130:131]
	v_lshlrev_b32_e32 v132, 16, v167
	v_and_b32_e32 v133, 0xffff0000, v167
	v_pk_fma_f32 v[130:131], v[124:125], v[92:93], v[136:137]
	v_pk_fma_f32 v[124:125], v[122:123], v[90:91], v[134:135]
	v_cvt_pk_bf16_f32 v122, v126, v127
	v_lshl_add_u64 v[126:127], s[60:61], 0, v[190:191]
	v_pk_fma_f32 v[128:129], v[128:129], v[96:97], v[132:133]
	v_lshl_add_u64 v[126:127], v[126:127], 0, v[180:181]
	v_cvt_pk_bf16_f32 v123, v128, v129
	v_cvt_pk_bf16_f32 v124, v124, v125
	v_cvt_pk_bf16_f32 v125, v130, v131
	global_store_dwordx4 v[126:127], v[122:125], off nt
	v_lshlrev_b32_e32 v128, 16, v164
	v_and_b32_e32 v129, 0xffff0000, v164
	v_lshlrev_b32_e32 v122, 16, v162
	v_and_b32_e32 v123, 0xffff0000, v162
	v_lshlrev_b32_e32 v124, 16, v163
	v_and_b32_e32 v125, 0xffff0000, v163
	v_lshlrev_b32_e32 v130, 16, v165
	v_and_b32_e32 v131, 0xffff0000, v165
	v_pk_fma_f32 v[120:121], v[120:121], v[84:85], v[124:125]
	v_pk_fma_f32 v[118:119], v[118:119], v[82:83], v[122:123]
	v_pk_fma_f32 v[122:123], v[116:117], v[76:77], v[130:131]
	v_pk_fma_f32 v[116:117], v[114:115], v[74:75], v[128:129]
	v_cvt_pk_bf16_f32 v114, v118, v119
	v_cvt_pk_bf16_f32 v115, v120, v121
	v_lshlrev_b32_e32 v118, 16, v160
	v_cvt_pk_bf16_f32 v116, v116, v117
	v_cvt_pk_bf16_f32 v117, v122, v123
	global_store_dwordx4 v[126:127], v[114:117], off offset:256 nt
	v_and_b32_e32 v119, 0xffff0000, v160
	v_lshlrev_b32_e32 v120, 16, v161
	v_lshlrev_b32_e32 v114, 16, v158
	v_and_b32_e32 v115, 0xffff0000, v158
	v_and_b32_e32 v121, 0xffff0000, v161
	v_pk_fma_f32 v[110:111], v[110:111], v[94:95], v[114:115]
	v_lshlrev_b32_e32 v116, 16, v159
	v_and_b32_e32 v117, 0xffff0000, v159
	v_pk_fma_f32 v[114:115], v[108:109], v[92:93], v[120:121]
	v_pk_fma_f32 v[108:109], v[106:107], v[90:91], v[118:119]
	v_cvt_pk_bf16_f32 v106, v110, v111
	v_lshl_add_u64 v[110:111], s[60:61], 0, v[188:189]
	v_pk_fma_f32 v[112:113], v[112:113], v[96:97], v[116:117]
; __device__ __forceinline__ u32x4 pack8(const f32x4& a, const f32x4& b) { u32x4 w; w.x = cvt_pk_bf16(a[0], a[1]); w.y = cvt_pk_bf16(a[2], a[3]); w.z = cvt_pk_bf16(b[0], b[1]); w.w = cvt_pk_bf16(b[2], b[3]); return w; }
;     __device__ __forceinline__ void operator()(const f32x4 (&acc)[2][2][4][2], const Unit& u, int wr, int wc, int fr, int fq) const {
;     ...
;             for (int ai = 0; ai < 2; ++ai) { u32x4 xw[4][2];
; #pragma unroll
;                 for (int m = 0; m < 4; ++m)
; #pragma unroll
;                     for (int bj = 0; bj < 2; ++bj) xw[m][bj] = *(const u32x4*)((const bf16_t*)xin + (size_t)(row0 + ai * HALF + m * 16) * 2048 + col0 + bj * HALF);
; #pragma unroll
;                 for (int m = 0; m < 4; ++m)
; #pragma unroll
;                     for (int bj = 0; bj < 2; ++bj) { const u32x4 w = xw[m][bj];
;                         const f32x4 x0 = (f32x4){__builtin_bit_cast(float, w.x << 16), __builtin_bit_cast(float, w.x & 0xffff0000u), __builtin_bit_cast(float, w.y << 16), __builtin_bit_cast(float, w.y & 0xffff0000u)};
;                         const f32x4 x1 = (f32x4){__builtin_bit_cast(float, w.z << 16), __builtin_bit_cast(float, w.z & 0xffff0000u), __builtin_bit_cast(float, w.w << 16), __builtin_bit_cast(float, w.w & 0xffff0000u)};
;                         *(u32x4*)(xout + (size_t)(row0 + ai * HALF + m * 16) * 2048 + col0 + bj * HALF) = pack8(x0 + gv[bj][0] * acc[ai][bj][m][0], x1 + gv[bj][1] * acc[ai][bj][m][1]); }
	v_lshl_add_u64 v[110:111], v[110:111], 0, v[180:181]
	v_cvt_pk_bf16_f32 v107, v112, v113
	v_cvt_pk_bf16_f32 v108, v108, v109
	v_cvt_pk_bf16_f32 v109, v114, v115
	global_store_dwordx4 v[110:111], v[106:109], off nt
	v_lshlrev_b32_e32 v112, 16, v156
	v_and_b32_e32 v113, 0xffff0000, v156
	v_lshlrev_b32_e32 v106, 16, v154
	v_and_b32_e32 v107, 0xffff0000, v154
	v_lshlrev_b32_e32 v108, 16, v155
	v_and_b32_e32 v109, 0xffff0000, v155
	v_lshlrev_b32_e32 v114, 16, v157
	v_and_b32_e32 v115, 0xffff0000, v157
	v_pk_fma_f32 v[104:105], v[104:105], v[84:85], v[108:109]
	v_pk_fma_f32 v[102:103], v[102:103], v[82:83], v[106:107]
	v_pk_fma_f32 v[106:107], v[100:101], v[76:77], v[114:115]
	v_pk_fma_f32 v[100:101], v[98:99], v[74:75], v[112:113]
	v_cvt_pk_bf16_f32 v98, v102, v103
	v_cvt_pk_bf16_f32 v99, v104, v105
	v_lshlrev_b32_e32 v102, 16, v152
	v_cvt_pk_bf16_f32 v100, v100, v101
	v_cvt_pk_bf16_f32 v101, v106, v107
	global_store_dwordx4 v[110:111], v[98:101], off offset:256 nt
	v_and_b32_e32 v103, 0xffff0000, v152
	v_lshlrev_b32_e32 v104, 16, v153
	v_lshlrev_b32_e32 v98, 16, v150
	v_and_b32_e32 v99, 0xffff0000, v150
	v_and_b32_e32 v105, 0xffff0000, v153
	v_pk_fma_f32 v[86:87], v[86:87], v[94:95], v[98:99]
	v_lshlrev_b32_e32 v100, 16, v151
	v_and_b32_e32 v101, 0xffff0000, v151
	v_pk_fma_f32 v[98:99], v[80:81], v[92:93], v[104:105]
	v_pk_fma_f32 v[80:81], v[78:79], v[90:91], v[102:103]
	v_cvt_pk_bf16_f32 v78, v86, v87
	v_lshl_add_u64 v[86:87], s[60:61], 0, v[186:187]
	v_pk_fma_f32 v[88:89], v[88:89], v[96:97], v[100:101]
	v_lshl_add_u64 v[86:87], v[86:87], 0, v[180:181]
	v_cvt_pk_bf16_f32 v79, v88, v89
	v_cvt_pk_bf16_f32 v80, v80, v81
	v_cvt_pk_bf16_f32 v81, v98, v99
	global_store_dwordx4 v[86:87], v[78:81], off nt
	v_lshlrev_b32_e32 v88, 16, v140
	v_and_b32_e32 v89, 0xffff0000, v140
	v_lshlrev_b32_e32 v78, 16, v138
	v_and_b32_e32 v79, 0xffff0000, v138
	v_lshlrev_b32_e32 v98, 16, v141
	v_and_b32_e32 v99, 0xffff0000, v141
	v_lshlrev_b32_e32 v80, 16, v139
	v_and_b32_e32 v81, 0xffff0000, v139
	v_pk_fma_f32 v[70:71], v[70:71], v[82:83], v[78:79]
	v_pk_fma_f32 v[78:79], v[68:69], v[76:77], v[98:99]
	v_pk_fma_f32 v[68:69], v[66:67], v[74:75], v[88:89]
	v_pk_fma_f32 v[72:73], v[72:73], v[84:85], v[80:81]
	v_cvt_pk_bf16_f32 v66, v70, v71
	v_lshl_add_u64 v[80:81], v[184:185], 0, s[0:1]
	v_cvt_pk_bf16_f32 v67, v72, v73
	v_cvt_pk_bf16_f32 v68, v68, v69
	v_cvt_pk_bf16_f32 v69, v78, v79
	global_store_dwordx4 v[86:87], v[66:69], off offset:256 nt
	s_mov_b64 s[0:1], 0x90000
	v_lshl_add_u64 v[118:119], v[184:185], 0, s[0:1]
	v_lshl_add_u64 v[66:67], v[182:183], 0, v[80:81]
	global_load_dwordx4 v[86:89], v[66:67], off
	global_load_dwordx4 v[98:101], v[66:67], off offset:256
	v_lshl_add_u64 v[66:67], v[182:183], 0, v[118:119]
	global_load_dwordx4 v[102:105], v[66:67], off
	global_load_dwordx4 v[106:109], v[66:67], off offset:256
	s_mov_b64 s[0:1], 0xa0000
	v_lshl_add_u64 v[120:121], v[184:185], 0, s[0:1]
	v_lshl_add_u64 v[66:67], v[182:183], 0, v[120:121]
	global_load_dwordx4 v[110:113], v[66:67], off
	global_load_dwordx4 v[114:117], v[66:67], off offset:256
	v_lshl_add_u64 v[78:79], v[184:185], 0, s[30:31]
	v_lshl_add_u64 v[66:67], v[182:183], 0, v[78:79]
	global_load_dwordx4 v[70:73], v[66:67], off
	s_nop 0
	global_load_dwordx4 v[66:69], v[66:67], off offset:256
	s_waitcnt vmcnt(7)
	v_lshlrev_b32_e32 v122, 16, v86
	v_and_b32_e32 v123, 0xffff0000, v86
	v_lshlrev_b32_e32 v86, 16, v87
	v_and_b32_e32 v87, 0xffff0000, v87
	v_lshlrev_b32_e32 v124, 16, v88
	v_and_b32_e32 v125, 0xffff0000, v88
	v_lshlrev_b32_e32 v88, 16, v89
	v_and_b32_e32 v89, 0xffff0000, v89
	v_pk_fma_f32 v[62:63], v[62:63], v[94:95], v[122:123]
	v_pk_fma_f32 v[64:65], v[64:65], v[96:97], v[86:87]
	v_pk_fma_f32 v[86:87], v[60:61], v[92:93], v[88:89]
	v_pk_fma_f32 v[60:61], v[58:59], v[90:91], v[124:125]
	v_cvt_pk_bf16_f32 v58, v62, v63
	v_lshl_add_u64 v[62:63], s[60:61], 0, v[80:81]
	v_cvt_pk_bf16_f32 v59, v64, v65
	v_cvt_pk_bf16_f32 v60, v60, v61
	v_cvt_pk_bf16_f32 v61, v86, v87
	v_lshl_add_u64 v[62:63], v[62:63], 0, v[180:181]
	global_store_dwordx4 v[62:63], v[58:61], off nt
	s_waitcnt vmcnt(7)
	v_lshlrev_b32_e32 v64, 16, v100
	v_and_b32_e32 v65, 0xffff0000, v100
	v_lshlrev_b32_e32 v58, 16, v98
	v_and_b32_e32 v59, 0xffff0000, v98
	v_lshlrev_b32_e32 v60, 16, v99
	v_and_b32_e32 v61, 0xffff0000, v99
	v_lshlrev_b32_e32 v80, 16, v101
	v_and_b32_e32 v81, 0xffff0000, v101
	v_pk_fma_f32 v[56:57], v[56:57], v[84:85], v[60:61]
	v_pk_fma_f32 v[54:55], v[54:55], v[82:83], v[58:59]
	v_pk_fma_f32 v[58:59], v[52:53], v[76:77], v[80:81]
	v_pk_fma_f32 v[52:53], v[50:51], v[74:75], v[64:65]
	v_cvt_pk_bf16_f32 v50, v54, v55
	v_cvt_pk_bf16_f32 v51, v56, v57
	s_waitcnt vmcnt(6)
; __device__ __forceinline__ u32x4 pack8(const f32x4& a, const f32x4& b) { u32x4 w; w.x = cvt_pk_bf16(a[0], a[1]); w.y = cvt_pk_bf16(a[2], a[3]); w.z = cvt_pk_bf16(b[0], b[1]); w.w = cvt_pk_bf16(b[2], b[3]); return w; }
; #define PG8_BAR __builtin_amdgcn_s_barrier()
;     __device__ __forceinline__ void operator()(const f32x4 (&acc)[2][2][4][2], const Unit& u, int wr, int wc, int fr, int fq) const {
;     ...
;             for (int ai = 0; ai < 2; ++ai) { u32x4 xw[4][2];
; #pragma unroll
;                 for (int m = 0; m < 4; ++m)
; #pragma unroll
;                     for (int bj = 0; bj < 2; ++bj) xw[m][bj] = *(const u32x4*)((const bf16_t*)xin + (size_t)(row0 + ai * HALF + m * 16) * 2048 + col0 + bj * HALF);
; #pragma unroll
;                 for (int m = 0; m < 4; ++m)
; #pragma unroll
;                     for (int bj = 0; bj < 2; ++bj) { const u32x4 w = xw[m][bj];
;                         const f32x4 x0 = (f32x4){__builtin_bit_cast(float, w.x << 16), __builtin_bit_cast(float, w.x & 0xffff0000u), __builtin_bit_cast(float, w.y << 16), __builtin_bit_cast(float, w.y & 0xffff0000u)};
;                         const f32x4 x1 = (f32x4){__builtin_bit_cast(float, w.z << 16), __builtin_bit_cast(float, w.z & 0xffff0000u), __builtin_bit_cast(float, w.w << 16), __builtin_bit_cast(float, w.w & 0xffff0000u)};
;                         *(u32x4*)(xout + (size_t)(row0 + ai * HALF + m * 16) * 2048 + col0 + bj * HALF) = pack8(x0 + gv[bj][0] * acc[ai][bj][m][0], x1 + gv[bj][1] * acc[ai][bj][m][1]); }
;                 asm volatile("" ::: "memory"); }
; template <class Epi, class Sched, bool ALIGN_EPI = true, bool SP2 = true, bool FULLLINE = false, bool NOSTAGE = false, bool FP8 = false>
; __device__ __forceinline__ void gemm_phase(PG8_LAS unsigned char* lds, const Gemm g, const Sched& S, const Epi& E) {
;     ...
;         if (!has_next) break;
; #pragma unroll
;         for (int a = 0; a < 2; ++a)
; #pragma unroll
;             for (int b = 0; b < 2; ++b)
; #pragma unroll
;                 for (int m = 0; m < 4; ++m)
; #pragma unroll
;                     for (int n = 0; n < 2; ++n) acc[a][b][m][n] = (f32x4){0.f, 0.f, 0.f, 0.f};
;         cur = nxt; cA = nA; cB = nB; ++ui;
;         if constexpr (ALIGN_EPI) { if (wr == 1) PG8_BAR; }
	v_lshlrev_b32_e32 v54, 16, v104
	v_cvt_pk_bf16_f32 v52, v52, v53
	v_cvt_pk_bf16_f32 v53, v58, v59
	global_store_dwordx4 v[62:63], v[50:53], off offset:256 nt
	v_and_b32_e32 v55, 0xffff0000, v104
	v_lshlrev_b32_e32 v56, 16, v105
	v_lshlrev_b32_e32 v50, 16, v102
	v_and_b32_e32 v51, 0xffff0000, v102
	v_and_b32_e32 v57, 0xffff0000, v105
	v_pk_fma_f32 v[46:47], v[46:47], v[94:95], v[50:51]
	v_lshlrev_b32_e32 v52, 16, v103
	v_and_b32_e32 v53, 0xffff0000, v103
	v_pk_fma_f32 v[50:51], v[44:45], v[92:93], v[56:57]
	v_pk_fma_f32 v[44:45], v[42:43], v[90:91], v[54:55]
	v_cvt_pk_bf16_f32 v42, v46, v47
	v_lshl_add_u64 v[46:47], s[60:61], 0, v[118:119]
	v_pk_fma_f32 v[48:49], v[48:49], v[96:97], v[52:53]
	v_lshl_add_u64 v[46:47], v[46:47], 0, v[180:181]
	v_cvt_pk_bf16_f32 v43, v48, v49
	v_cvt_pk_bf16_f32 v44, v44, v45
	v_cvt_pk_bf16_f32 v45, v50, v51
	global_store_dwordx4 v[46:47], v[42:45], off nt
	s_waitcnt vmcnt(7)
	v_lshlrev_b32_e32 v48, 16, v108
	v_and_b32_e32 v49, 0xffff0000, v108
	v_lshlrev_b32_e32 v42, 16, v106
	v_and_b32_e32 v43, 0xffff0000, v106
	v_lshlrev_b32_e32 v44, 16, v107
	v_and_b32_e32 v45, 0xffff0000, v107
	v_lshlrev_b32_e32 v50, 16, v109
	v_and_b32_e32 v51, 0xffff0000, v109
	v_pk_fma_f32 v[40:41], v[40:41], v[84:85], v[44:45]
	v_pk_fma_f32 v[38:39], v[38:39], v[82:83], v[42:43]
	v_pk_fma_f32 v[42:43], v[36:37], v[76:77], v[50:51]
	v_pk_fma_f32 v[36:37], v[34:35], v[74:75], v[48:49]
	v_cvt_pk_bf16_f32 v34, v38, v39
	v_cvt_pk_bf16_f32 v35, v40, v41
	s_waitcnt vmcnt(6)
	v_lshlrev_b32_e32 v38, 16, v112
	v_cvt_pk_bf16_f32 v36, v36, v37
	v_cvt_pk_bf16_f32 v37, v42, v43
	global_store_dwordx4 v[46:47], v[34:37], off offset:256 nt
	v_and_b32_e32 v39, 0xffff0000, v112
	v_lshlrev_b32_e32 v40, 16, v113
	v_lshlrev_b32_e32 v34, 16, v110
	v_and_b32_e32 v35, 0xffff0000, v110
	v_and_b32_e32 v41, 0xffff0000, v113
	v_pk_fma_f32 v[30:31], v[30:31], v[94:95], v[34:35]
	v_lshlrev_b32_e32 v36, 16, v111
	v_and_b32_e32 v37, 0xffff0000, v111
	v_pk_fma_f32 v[34:35], v[28:29], v[92:93], v[40:41]
	v_pk_fma_f32 v[28:29], v[26:27], v[90:91], v[38:39]
	v_cvt_pk_bf16_f32 v26, v30, v31
	v_lshl_add_u64 v[30:31], s[60:61], 0, v[120:121]
	v_pk_fma_f32 v[32:33], v[32:33], v[96:97], v[36:37]
	v_lshl_add_u64 v[30:31], v[30:31], 0, v[180:181]
	v_cvt_pk_bf16_f32 v27, v32, v33
	v_cvt_pk_bf16_f32 v28, v28, v29
	v_cvt_pk_bf16_f32 v29, v34, v35
	global_store_dwordx4 v[30:31], v[26:29], off nt
	s_waitcnt vmcnt(7)
	v_lshlrev_b32_e32 v32, 16, v116
	v_and_b32_e32 v33, 0xffff0000, v116
	v_lshlrev_b32_e32 v26, 16, v114
	v_and_b32_e32 v27, 0xffff0000, v114
	v_lshlrev_b32_e32 v28, 16, v115
	v_and_b32_e32 v29, 0xffff0000, v115
	v_lshlrev_b32_e32 v34, 16, v117
	v_and_b32_e32 v35, 0xffff0000, v117
	v_pk_fma_f32 v[24:25], v[24:25], v[84:85], v[28:29]
	v_pk_fma_f32 v[22:23], v[22:23], v[82:83], v[26:27]
	v_pk_fma_f32 v[26:27], v[20:21], v[76:77], v[34:35]
	v_pk_fma_f32 v[20:21], v[18:19], v[74:75], v[32:33]
	v_cvt_pk_bf16_f32 v18, v22, v23
	v_cvt_pk_bf16_f32 v19, v24, v25
	s_waitcnt vmcnt(6)
	v_lshlrev_b32_e32 v22, 16, v72
	v_cvt_pk_bf16_f32 v20, v20, v21
	v_cvt_pk_bf16_f32 v21, v26, v27
	global_store_dwordx4 v[30:31], v[18:21], off offset:256 nt
	v_and_b32_e32 v23, 0xffff0000, v72
	v_lshlrev_b32_e32 v24, 16, v73
	v_lshlrev_b32_e32 v18, 16, v70
	v_and_b32_e32 v19, 0xffff0000, v70
	v_and_b32_e32 v25, 0xffff0000, v73
	v_pk_fma_f32 v[14:15], v[14:15], v[94:95], v[18:19]
	v_lshlrev_b32_e32 v20, 16, v71
	v_and_b32_e32 v21, 0xffff0000, v71
	v_pk_fma_f32 v[18:19], v[12:13], v[92:93], v[24:25]
	v_pk_fma_f32 v[12:13], v[10:11], v[90:91], v[22:23]
	v_cvt_pk_bf16_f32 v10, v14, v15
	v_lshl_add_u64 v[14:15], s[60:61], 0, v[78:79]
	v_pk_fma_f32 v[16:17], v[16:17], v[96:97], v[20:21]
	v_lshl_add_u64 v[14:15], v[14:15], 0, v[180:181]
	v_cvt_pk_bf16_f32 v11, v16, v17
	v_cvt_pk_bf16_f32 v12, v12, v13
	v_cvt_pk_bf16_f32 v13, v18, v19
	global_store_dwordx4 v[14:15], v[10:13], off nt
	s_waitcnt vmcnt(7)
	v_lshlrev_b32_e32 v16, 16, v68
	v_and_b32_e32 v17, 0xffff0000, v68
	v_lshlrev_b32_e32 v10, 16, v66
	v_and_b32_e32 v11, 0xffff0000, v66
	v_lshlrev_b32_e32 v18, 16, v69
	v_and_b32_e32 v19, 0xffff0000, v69
	v_lshlrev_b32_e32 v12, 16, v67
	v_and_b32_e32 v13, 0xffff0000, v67
	v_pk_fma_f32 v[6:7], v[6:7], v[82:83], v[10:11]
	v_pk_fma_f32 v[10:11], v[4:5], v[76:77], v[18:19]
	v_pk_fma_f32 v[4:5], v[2:3], v[74:75], v[16:17]
	v_pk_fma_f32 v[8:9], v[8:9], v[84:85], v[12:13]
	v_cvt_pk_bf16_f32 v2, v6, v7
	s_nop 0
	v_cvt_pk_bf16_f32 v3, v8, v9
	v_cvt_pk_bf16_f32 v4, v4, v5
	v_cvt_pk_bf16_f32 v5, v10, v11
	global_store_dwordx4 v[14:15], v[2:5], off offset:256 nt
	s_cbranch_vccnz .LBB0_1472
	s_and_b64 vcc, exec, s[6:7]
	s_cbranch_vccnz .LBB0_1471
	s_barrier
	s_branch .LBB0_1471

; __device__ __forceinline__ u32x4 pack8(const f32x4& a, const f32x4& b) { u32x4 w; w.x = cvt_pk_bf16(a[0], a[1]); w.y = cvt_pk_bf16(a[2], a[3]); w.z = cvt_pk_bf16(b[0], b[1]); w.w = cvt_pk_bf16(b[2], b[3]); return w; }
;     __device__ __forceinline__ void operator()(const f32x4 (&acc)[2][2][4][2], const Unit& u, int wr, int wc, int fr, int fq) const {
;         const int row0 = u.pm * BM + wr * 64 + fr, col0 = u.pn * BM + wc * 32 + 8 * fq;
;         const float* gp = gate + (size_t)(u.pm >> 3) * 12288 + col0;
;         f32x4 gv[2][2];
; #pragma unroll
;         for (int bj = 0; bj < 2; ++bj)
; #pragma unroll
;             for (int n = 0; n < 2; ++n) { gv[bj][n] = *(const f32x4*)(gp + bj * HALF + n * 4); if (cscale) gv[bj][n] = gv[bj][n] * *(const f32x4*)(cscale + col0 + bj * HALF + n * 4); }
;     ...
;             for (int ai = 0; ai < 2; ++ai) { u32x4 xw[4][2];
; #pragma unroll
;                 for (int m = 0; m < 4; ++m)
; #pragma unroll
;                     for (int bj = 0; bj < 2; ++bj) xw[m][bj] = *(const u32x4*)((const bf16_t*)xin + (size_t)(row0 + ai * HALF + m * 16) * 2048 + col0 + bj * HALF);
; #pragma unroll
;                 for (int m = 0; m < 4; ++m)
; #pragma unroll
;                     for (int bj = 0; bj < 2; ++bj) { const u32x4 w = xw[m][bj];
;                         const f32x4 x0 = (f32x4){__builtin_bit_cast(float, w.x << 16), __builtin_bit_cast(float, w.x & 0xffff0000u), __builtin_bit_cast(float, w.y << 16), __builtin_bit_cast(float, w.y & 0xffff0000u)};
;                         const f32x4 x1 = (f32x4){__builtin_bit_cast(float, w.z << 16), __builtin_bit_cast(float, w.z & 0xffff0000u), __builtin_bit_cast(float, w.w << 16), __builtin_bit_cast(float, w.w & 0xffff0000u)};
;                         *(u32x4*)(xout + (size_t)(row0 + ai * HALF + m * 16) * 2048 + col0 + bj * HALF) = pack8(x0 + gv[bj][0] * acc[ai][bj][m][0], x1 + gv[bj][1] * acc[ai][bj][m][1]); }
.LBB0_2100:
	v_mov_b32_e32 v140, v252
	s_lshl_b32 s0, s73, 8
	v_ashrrev_i32_e32 v74, 1, v140
	s_or_b32 s0, s0, s80
	v_and_b32_e32 v74, -8, v74
	v_add_u32_e32 v138, s0, v74
	s_ashr_i32 s0, s72, 3
	s_mul_hi_i32 s1, s0, 0xc000
	s_mul_i32 s0, s0, 0xc000
	s_add_u32 s0, s63, s0
	s_addc_u32 s1, s78, s1
	v_ashrrev_i32_e32 v139, 31, v138
	v_lshl_add_u64 v[82:83], v[138:139], 2, s[0:1]
	s_lshl_b32 s0, s72, 8
	s_add_i32 s0, s0, s79
	v_and_or_b32 v140, v140, 15, s0
	v_lshlrev_b64 v[180:181], 1, v[138:139]
	v_ashrrev_i32_e32 v141, 31, v140
	v_lshl_add_u64 v[182:183], s[60:61], 0, v[180:181]
	v_lshlrev_b64 v[184:185], 12, v[140:141]
	v_lshl_add_u64 v[138:139], v[182:183], 0, v[184:185]
	global_load_dwordx4 v[90:93], v[82:83], off offset:16
	global_load_dwordx4 v[94:97], v[82:83], off
	global_load_dwordx4 v[74:77], v[82:83], off offset:528
	s_nop 0
	global_load_dwordx4 v[82:85], v[82:83], off offset:512
	s_nop 0
	global_load_dwordx4 v[196:199], v[138:139], off
	global_load_dwordx4 v[200:203], v[138:139], off offset:256
	v_or_b32_e32 v138, 16, v140
	v_ashrrev_i32_e32 v139, 31, v138
	v_lshlrev_b64 v[190:191], 12, v[138:139]
	v_lshl_add_u64 v[138:139], v[182:183], 0, v[190:191]
	global_load_dwordx4 v[166:169], v[138:139], off
	global_load_dwordx4 v[162:165], v[138:139], off offset:256
	v_or_b32_e32 v138, 32, v140
	v_ashrrev_i32_e32 v139, 31, v138
	v_lshlrev_b64 v[188:189], 12, v[138:139]
	v_lshl_add_u64 v[138:139], v[182:183], 0, v[188:189]
	global_load_dwordx4 v[158:161], v[138:139], off
	global_load_dwordx4 v[154:157], v[138:139], off offset:256
	v_or_b32_e32 v138, 48, v140
	v_ashrrev_i32_e32 v139, 31, v138
	v_lshlrev_b64 v[186:187], 12, v[138:139]
	v_lshl_add_u64 v[138:139], v[182:183], 0, v[186:187]
	global_load_dwordx4 v[150:153], v[138:139], off
	s_nop 0
	global_load_dwordx4 v[138:141], v[138:139], off offset:256
	s_mov_b64 s[0:1], 0x90000
	s_mov_b64 s[72:73], -1
	s_andn2_b64 vcc, exec, s[8:9]
	s_waitcnt vmcnt(0)
	v_lshlrev_b32_e32 v204, 16, v196
	v_and_b32_e32 v205, 0xffff0000, v196
	v_lshlrev_b32_e32 v196, 16, v197
	v_and_b32_e32 v197, 0xffff0000, v197
	v_lshlrev_b32_e32 v206, 16, v198
	v_and_b32_e32 v207, 0xffff0000, v198
	v_lshlrev_b32_e32 v198, 16, v199
	v_and_b32_e32 v199, 0xffff0000, v199
	v_pk_fma_f32 v[146:147], v[146:147], v[94:95], v[204:205]
	v_pk_fma_f32 v[148:149], v[148:149], v[96:97], v[196:197]
	v_pk_fma_f32 v[196:197], v[144:145], v[92:93], v[198:199]
	v_pk_fma_f32 v[144:145], v[142:143], v[90:91], v[206:207]
	v_cvt_pk_bf16_f32 v142, v146, v147
	v_lshl_add_u64 v[146:147], s[60:61], 0, v[184:185]
	v_cvt_pk_bf16_f32 v143, v148, v149
	v_cvt_pk_bf16_f32 v144, v144, v145
	v_cvt_pk_bf16_f32 v145, v196, v197
	v_lshl_add_u64 v[146:147], v[146:147], 0, v[180:181]
	global_store_dwordx4 v[146:147], v[142:145], off nt
	v_lshlrev_b32_e32 v148, 16, v202
	v_and_b32_e32 v149, 0xffff0000, v202
	v_lshlrev_b32_e32 v142, 16, v200
	v_and_b32_e32 v143, 0xffff0000, v200
	v_lshlrev_b32_e32 v144, 16, v201
	v_and_b32_e32 v145, 0xffff0000, v201
	v_lshlrev_b32_e32 v196, 16, v203
	v_and_b32_e32 v197, 0xffff0000, v203
	v_pk_fma_f32 v[136:137], v[136:137], v[84:85], v[144:145]
	v_pk_fma_f32 v[134:135], v[134:135], v[82:83], v[142:143]
	v_pk_fma_f32 v[142:143], v[132:133], v[76:77], v[196:197]
	v_pk_fma_f32 v[132:133], v[130:131], v[74:75], v[148:149]
	v_cvt_pk_bf16_f32 v130, v134, v135
	v_cvt_pk_bf16_f32 v131, v136, v137
	v_lshlrev_b32_e32 v134, 16, v168
	v_cvt_pk_bf16_f32 v132, v132, v133
	v_cvt_pk_bf16_f32 v133, v142, v143
	global_store_dwordx4 v[146:147], v[130:133], off offset:256 nt
	v_and_b32_e32 v135, 0xffff0000, v168
	v_lshlrev_b32_e32 v136, 16, v169
	v_lshlrev_b32_e32 v130, 16, v166
	v_and_b32_e32 v131, 0xffff0000, v166
	v_and_b32_e32 v137, 0xffff0000, v169
	v_pk_fma_f32 v[126:127], v[126:127], v[94:95], v[130:131]
	v_lshlrev_b32_e32 v132, 16, v167
	v_and_b32_e32 v133, 0xffff0000, v167
	v_pk_fma_f32 v[130:131], v[124:125], v[92:93], v[136:137]
	v_pk_fma_f32 v[124:125], v[122:123], v[90:91], v[134:135]
	v_cvt_pk_bf16_f32 v122, v126, v127
	v_lshl_add_u64 v[126:127], s[60:61], 0, v[190:191]
	v_pk_fma_f32 v[128:129], v[128:129], v[96:97], v[132:133]
	v_lshl_add_u64 v[126:127], v[126:127], 0, v[180:181]
	v_cvt_pk_bf16_f32 v123, v128, v129
	v_cvt_pk_bf16_f32 v124, v124, v125
	v_cvt_pk_bf16_f32 v125, v130, v131
	global_store_dwordx4 v[126:127], v[122:125], off nt
	v_lshlrev_b32_e32 v128, 16, v164
	v_and_b32_e32 v129, 0xffff0000, v164
	v_lshlrev_b32_e32 v122, 16, v162
	v_and_b32_e32 v123, 0xffff0000, v162
	v_lshlrev_b32_e32 v124, 16, v163
	v_and_b32_e32 v125, 0xffff0000, v163
	v_lshlrev_b32_e32 v130, 16, v165
	v_and_b32_e32 v131, 0xffff0000, v165
	v_pk_fma_f32 v[120:121], v[120:121], v[84:85], v[124:125]
	v_pk_fma_f32 v[118:119], v[118:119], v[82:83], v[122:123]
	v_pk_fma_f32 v[122:123], v[116:117], v[76:77], v[130:131]
	v_pk_fma_f32 v[116:117], v[114:115], v[74:75], v[128:129]
	v_cvt_pk_bf16_f32 v114, v118, v119
	v_cvt_pk_bf16_f32 v115, v120, v121
	v_lshlrev_b32_e32 v118, 16, v160
	v_cvt_pk_bf16_f32 v116, v116, v117
	v_cvt_pk_bf16_f32 v117, v122, v123
	global_store_dwordx4 v[126:127], v[114:117], off offset:256 nt
	v_and_b32_e32 v119, 0xffff0000, v160
	v_lshlrev_b32_e32 v120, 16, v161
	v_lshlrev_b32_e32 v114, 16, v158
	v_and_b32_e32 v115, 0xffff0000, v158
	v_and_b32_e32 v121, 0xffff0000, v161
	v_pk_fma_f32 v[110:111], v[110:111], v[94:95], v[114:115]
	v_lshlrev_b32_e32 v116, 16, v159
	v_and_b32_e32 v117, 0xffff0000, v159
	v_pk_fma_f32 v[114:115], v[108:109], v[92:93], v[120:121]
	v_pk_fma_f32 v[108:109], v[106:107], v[90:91], v[118:119]
	v_cvt_pk_bf16_f32 v106, v110, v111
	v_lshl_add_u64 v[110:111], s[60:61], 0, v[188:189]
	v_pk_fma_f32 v[112:113], v[112:113], v[96:97], v[116:117]
; __device__ __forceinline__ u32x4 pack8(const f32x4& a, const f32x4& b) { u32x4 w; w.x = cvt_pk_bf16(a[0], a[1]); w.y = cvt_pk_bf16(a[2], a[3]); w.z = cvt_pk_bf16(b[0], b[1]); w.w = cvt_pk_bf16(b[2], b[3]); return w; }
;     __device__ __forceinline__ void operator()(const f32x4 (&acc)[2][2][4][2], const Unit& u, int wr, int wc, int fr, int fq) const {
;     ...
;             for (int ai = 0; ai < 2; ++ai) { u32x4 xw[4][2];
; #pragma unroll
;                 for (int m = 0; m < 4; ++m)
; #pragma unroll
;                     for (int bj = 0; bj < 2; ++bj) xw[m][bj] = *(const u32x4*)((const bf16_t*)xin + (size_t)(row0 + ai * HALF + m * 16) * 2048 + col0 + bj * HALF);
; #pragma unroll
;                 for (int m = 0; m < 4; ++m)
; #pragma unroll
;                     for (int bj = 0; bj < 2; ++bj) { const u32x4 w = xw[m][bj];
;                         const f32x4 x0 = (f32x4){__builtin_bit_cast(float, w.x << 16), __builtin_bit_cast(float, w.x & 0xffff0000u), __builtin_bit_cast(float, w.y << 16), __builtin_bit_cast(float, w.y & 0xffff0000u)};
;                         const f32x4 x1 = (f32x4){__builtin_bit_cast(float, w.z << 16), __builtin_bit_cast(float, w.z & 0xffff0000u), __builtin_bit_cast(float, w.w << 16), __builtin_bit_cast(float, w.w & 0xffff0000u)};
;                         *(u32x4*)(xout + (size_t)(row0 + ai * HALF + m * 16) * 2048 + col0 + bj * HALF) = pack8(x0 + gv[bj][0] * acc[ai][bj][m][0], x1 + gv[bj][1] * acc[ai][bj][m][1]); }
	v_lshl_add_u64 v[110:111], v[110:111], 0, v[180:181]
	v_cvt_pk_bf16_f32 v107, v112, v113
	v_cvt_pk_bf16_f32 v108, v108, v109
	v_cvt_pk_bf16_f32 v109, v114, v115
	global_store_dwordx4 v[110:111], v[106:109], off nt
	v_lshlrev_b32_e32 v112, 16, v156
	v_and_b32_e32 v113, 0xffff0000, v156
	v_lshlrev_b32_e32 v106, 16, v154
	v_and_b32_e32 v107, 0xffff0000, v154
	v_lshlrev_b32_e32 v108, 16, v155
	v_and_b32_e32 v109, 0xffff0000, v155
	v_lshlrev_b32_e32 v114, 16, v157
	v_and_b32_e32 v115, 0xffff0000, v157
	v_pk_fma_f32 v[104:105], v[104:105], v[84:85], v[108:109]
	v_pk_fma_f32 v[102:103], v[102:103], v[82:83], v[106:107]
	v_pk_fma_f32 v[106:107], v[100:101], v[76:77], v[114:115]
	v_pk_fma_f32 v[100:101], v[98:99], v[74:75], v[112:113]
	v_cvt_pk_bf16_f32 v98, v102, v103
	v_cvt_pk_bf16_f32 v99, v104, v105
	v_lshlrev_b32_e32 v102, 16, v152
	v_cvt_pk_bf16_f32 v100, v100, v101
	v_cvt_pk_bf16_f32 v101, v106, v107
	global_store_dwordx4 v[110:111], v[98:101], off offset:256 nt
	v_and_b32_e32 v103, 0xffff0000, v152
	v_lshlrev_b32_e32 v104, 16, v153
	v_lshlrev_b32_e32 v98, 16, v150
	v_and_b32_e32 v99, 0xffff0000, v150
	v_and_b32_e32 v105, 0xffff0000, v153
	v_pk_fma_f32 v[86:87], v[86:87], v[94:95], v[98:99]
	v_lshlrev_b32_e32 v100, 16, v151
	v_and_b32_e32 v101, 0xffff0000, v151
	v_pk_fma_f32 v[98:99], v[80:81], v[92:93], v[104:105]
	v_pk_fma_f32 v[80:81], v[78:79], v[90:91], v[102:103]
	v_cvt_pk_bf16_f32 v78, v86, v87
	v_lshl_add_u64 v[86:87], s[60:61], 0, v[186:187]
	v_pk_fma_f32 v[88:89], v[88:89], v[96:97], v[100:101]
	v_lshl_add_u64 v[86:87], v[86:87], 0, v[180:181]
	v_cvt_pk_bf16_f32 v79, v88, v89
	v_cvt_pk_bf16_f32 v80, v80, v81
	v_cvt_pk_bf16_f32 v81, v98, v99
	global_store_dwordx4 v[86:87], v[78:81], off nt
	v_lshlrev_b32_e32 v88, 16, v140
	v_and_b32_e32 v89, 0xffff0000, v140
	v_lshlrev_b32_e32 v78, 16, v138
	v_and_b32_e32 v79, 0xffff0000, v138
	v_lshlrev_b32_e32 v98, 16, v141
	v_and_b32_e32 v99, 0xffff0000, v141
	v_lshlrev_b32_e32 v80, 16, v139
	v_and_b32_e32 v81, 0xffff0000, v139
	v_pk_fma_f32 v[70:71], v[70:71], v[82:83], v[78:79]
	v_pk_fma_f32 v[78:79], v[68:69], v[76:77], v[98:99]
	v_pk_fma_f32 v[68:69], v[66:67], v[74:75], v[88:89]
	v_pk_fma_f32 v[72:73], v[72:73], v[84:85], v[80:81]
	v_cvt_pk_bf16_f32 v66, v70, v71
	v_lshl_add_u64 v[80:81], v[184:185], 0, s[30:31]
	v_cvt_pk_bf16_f32 v67, v72, v73
	v_cvt_pk_bf16_f32 v68, v68, v69
	v_cvt_pk_bf16_f32 v69, v78, v79
	global_store_dwordx4 v[86:87], v[66:69], off offset:256 nt
	v_lshl_add_u64 v[118:119], v[184:185], 0, s[0:1]
	s_mov_b64 s[0:1], 0xa0000
	v_lshl_add_u64 v[66:67], v[182:183], 0, v[80:81]
	global_load_dwordx4 v[86:89], v[66:67], off
	global_load_dwordx4 v[98:101], v[66:67], off offset:256
	v_lshl_add_u64 v[66:67], v[182:183], 0, v[118:119]
	global_load_dwordx4 v[102:105], v[66:67], off
	global_load_dwordx4 v[106:109], v[66:67], off offset:256
	v_lshl_add_u64 v[120:121], v[184:185], 0, s[0:1]
	v_lshl_add_u64 v[66:67], v[182:183], 0, v[120:121]
	global_load_dwordx4 v[110:113], v[66:67], off
	global_load_dwordx4 v[114:117], v[66:67], off offset:256
	s_mov_b64 s[0:1], 0xb0000
	v_lshl_add_u64 v[78:79], v[184:185], 0, s[0:1]
	v_lshl_add_u64 v[66:67], v[182:183], 0, v[78:79]
	global_load_dwordx4 v[70:73], v[66:67], off
	s_nop 0
	global_load_dwordx4 v[66:69], v[66:67], off offset:256
	s_waitcnt vmcnt(7)
	v_lshlrev_b32_e32 v122, 16, v86
	v_and_b32_e32 v123, 0xffff0000, v86
	v_lshlrev_b32_e32 v86, 16, v87
	v_and_b32_e32 v87, 0xffff0000, v87
	v_lshlrev_b32_e32 v124, 16, v88
	v_and_b32_e32 v125, 0xffff0000, v88
	v_lshlrev_b32_e32 v88, 16, v89
	v_and_b32_e32 v89, 0xffff0000, v89
	v_pk_fma_f32 v[62:63], v[62:63], v[94:95], v[122:123]
	v_pk_fma_f32 v[64:65], v[64:65], v[96:97], v[86:87]
	v_pk_fma_f32 v[86:87], v[60:61], v[92:93], v[88:89]
	v_pk_fma_f32 v[60:61], v[58:59], v[90:91], v[124:125]
	v_cvt_pk_bf16_f32 v58, v62, v63
	v_lshl_add_u64 v[62:63], s[60:61], 0, v[80:81]
	v_cvt_pk_bf16_f32 v59, v64, v65
	v_cvt_pk_bf16_f32 v60, v60, v61
	v_cvt_pk_bf16_f32 v61, v86, v87
	v_lshl_add_u64 v[62:63], v[62:63], 0, v[180:181]
	global_store_dwordx4 v[62:63], v[58:61], off nt
	s_waitcnt vmcnt(7)
	v_lshlrev_b32_e32 v64, 16, v100
	v_and_b32_e32 v65, 0xffff0000, v100
	v_lshlrev_b32_e32 v58, 16, v98
	v_and_b32_e32 v59, 0xffff0000, v98
	v_lshlrev_b32_e32 v60, 16, v99
	v_and_b32_e32 v61, 0xffff0000, v99
	v_lshlrev_b32_e32 v80, 16, v101
	v_and_b32_e32 v81, 0xffff0000, v101
	v_pk_fma_f32 v[56:57], v[56:57], v[84:85], v[60:61]
	v_pk_fma_f32 v[54:55], v[54:55], v[82:83], v[58:59]
	v_pk_fma_f32 v[58:59], v[52:53], v[76:77], v[80:81]
	v_pk_fma_f32 v[52:53], v[50:51], v[74:75], v[64:65]
	v_cvt_pk_bf16_f32 v50, v54, v55
	v_cvt_pk_bf16_f32 v51, v56, v57
	s_waitcnt vmcnt(6)
; __device__ __forceinline__ u32x4 pack8(const f32x4& a, const f32x4& b) { u32x4 w; w.x = cvt_pk_bf16(a[0], a[1]); w.y = cvt_pk_bf16(a[2], a[3]); w.z = cvt_pk_bf16(b[0], b[1]); w.w = cvt_pk_bf16(b[2], b[3]); return w; }
; #define PG8_BAR __builtin_amdgcn_s_barrier()
;     __device__ __forceinline__ void operator()(const f32x4 (&acc)[2][2][4][2], const Unit& u, int wr, int wc, int fr, int fq) const {
;     ...
;             for (int ai = 0; ai < 2; ++ai) { u32x4 xw[4][2];
; #pragma unroll
;                 for (int m = 0; m < 4; ++m)
; #pragma unroll
;                     for (int bj = 0; bj < 2; ++bj) xw[m][bj] = *(const u32x4*)((const bf16_t*)xin + (size_t)(row0 + ai * HALF + m * 16) * 2048 + col0 + bj * HALF);
; #pragma unroll
;                 for (int m = 0; m < 4; ++m)
; #pragma unroll
;                     for (int bj = 0; bj < 2; ++bj) { const u32x4 w = xw[m][bj];
;                         const f32x4 x0 = (f32x4){__builtin_bit_cast(float, w.x << 16), __builtin_bit_cast(float, w.x & 0xffff0000u), __builtin_bit_cast(float, w.y << 16), __builtin_bit_cast(float, w.y & 0xffff0000u)};
;                         const f32x4 x1 = (f32x4){__builtin_bit_cast(float, w.z << 16), __builtin_bit_cast(float, w.z & 0xffff0000u), __builtin_bit_cast(float, w.w << 16), __builtin_bit_cast(float, w.w & 0xffff0000u)};
;                         *(u32x4*)(xout + (size_t)(row0 + ai * HALF + m * 16) * 2048 + col0 + bj * HALF) = pack8(x0 + gv[bj][0] * acc[ai][bj][m][0], x1 + gv[bj][1] * acc[ai][bj][m][1]); }
;                 asm volatile("" ::: "memory"); }
; template <class Epi, class Sched, bool ALIGN_EPI = true, bool SP2 = true, bool FULLLINE = false, bool NOSTAGE = false, bool FP8 = false>
; __device__ __forceinline__ void gemm_phase(PG8_LAS unsigned char* lds, const Gemm g, const Sched& S, const Epi& E) {
;     ...
;         if (!has_next) break;
; #pragma unroll
;         for (int a = 0; a < 2; ++a)
; #pragma unroll
;             for (int b = 0; b < 2; ++b)
; #pragma unroll
;                 for (int m = 0; m < 4; ++m)
; #pragma unroll
;                     for (int n = 0; n < 2; ++n) acc[a][b][m][n] = (f32x4){0.f, 0.f, 0.f, 0.f};
;         cur = nxt; cA = nA; cB = nB; ++ui;
;         if constexpr (ALIGN_EPI) { if (wr == 1) PG8_BAR; }
	v_lshlrev_b32_e32 v54, 16, v104
	v_cvt_pk_bf16_f32 v52, v52, v53
	v_cvt_pk_bf16_f32 v53, v58, v59
	global_store_dwordx4 v[62:63], v[50:53], off offset:256 nt
	v_and_b32_e32 v55, 0xffff0000, v104
	v_lshlrev_b32_e32 v56, 16, v105
	v_lshlrev_b32_e32 v50, 16, v102
	v_and_b32_e32 v51, 0xffff0000, v102
	v_and_b32_e32 v57, 0xffff0000, v105
	v_pk_fma_f32 v[46:47], v[46:47], v[94:95], v[50:51]
	v_lshlrev_b32_e32 v52, 16, v103
	v_and_b32_e32 v53, 0xffff0000, v103
	v_pk_fma_f32 v[50:51], v[44:45], v[92:93], v[56:57]
	v_pk_fma_f32 v[44:45], v[42:43], v[90:91], v[54:55]
	v_cvt_pk_bf16_f32 v42, v46, v47
	v_lshl_add_u64 v[46:47], s[60:61], 0, v[118:119]
	v_pk_fma_f32 v[48:49], v[48:49], v[96:97], v[52:53]
	v_lshl_add_u64 v[46:47], v[46:47], 0, v[180:181]
	v_cvt_pk_bf16_f32 v43, v48, v49
	v_cvt_pk_bf16_f32 v44, v44, v45
	v_cvt_pk_bf16_f32 v45, v50, v51
	global_store_dwordx4 v[46:47], v[42:45], off nt
	s_waitcnt vmcnt(7)
	v_lshlrev_b32_e32 v48, 16, v108
	v_and_b32_e32 v49, 0xffff0000, v108
	v_lshlrev_b32_e32 v42, 16, v106
	v_and_b32_e32 v43, 0xffff0000, v106
	v_lshlrev_b32_e32 v44, 16, v107
	v_and_b32_e32 v45, 0xffff0000, v107
	v_lshlrev_b32_e32 v50, 16, v109
	v_and_b32_e32 v51, 0xffff0000, v109
	v_pk_fma_f32 v[40:41], v[40:41], v[84:85], v[44:45]
	v_pk_fma_f32 v[38:39], v[38:39], v[82:83], v[42:43]
	v_pk_fma_f32 v[42:43], v[36:37], v[76:77], v[50:51]
	v_pk_fma_f32 v[36:37], v[34:35], v[74:75], v[48:49]
	v_cvt_pk_bf16_f32 v34, v38, v39
	v_cvt_pk_bf16_f32 v35, v40, v41
	s_waitcnt vmcnt(6)
	v_lshlrev_b32_e32 v38, 16, v112
	v_cvt_pk_bf16_f32 v36, v36, v37
	v_cvt_pk_bf16_f32 v37, v42, v43
	global_store_dwordx4 v[46:47], v[34:37], off offset:256 nt
	v_and_b32_e32 v39, 0xffff0000, v112
	v_lshlrev_b32_e32 v40, 16, v113
	v_lshlrev_b32_e32 v34, 16, v110
	v_and_b32_e32 v35, 0xffff0000, v110
	v_and_b32_e32 v41, 0xffff0000, v113
	v_pk_fma_f32 v[30:31], v[30:31], v[94:95], v[34:35]
	v_lshlrev_b32_e32 v36, 16, v111
	v_and_b32_e32 v37, 0xffff0000, v111
	v_pk_fma_f32 v[34:35], v[28:29], v[92:93], v[40:41]
	v_pk_fma_f32 v[28:29], v[26:27], v[90:91], v[38:39]
	v_cvt_pk_bf16_f32 v26, v30, v31
	v_lshl_add_u64 v[30:31], s[60:61], 0, v[120:121]
	v_pk_fma_f32 v[32:33], v[32:33], v[96:97], v[36:37]
	v_lshl_add_u64 v[30:31], v[30:31], 0, v[180:181]
	v_cvt_pk_bf16_f32 v27, v32, v33
	v_cvt_pk_bf16_f32 v28, v28, v29
	v_cvt_pk_bf16_f32 v29, v34, v35
	global_store_dwordx4 v[30:31], v[26:29], off nt
	s_waitcnt vmcnt(7)
	v_lshlrev_b32_e32 v32, 16, v116
	v_and_b32_e32 v33, 0xffff0000, v116
	v_lshlrev_b32_e32 v26, 16, v114
	v_and_b32_e32 v27, 0xffff0000, v114
	v_lshlrev_b32_e32 v28, 16, v115
	v_and_b32_e32 v29, 0xffff0000, v115
	v_lshlrev_b32_e32 v34, 16, v117
	v_and_b32_e32 v35, 0xffff0000, v117
	v_pk_fma_f32 v[24:25], v[24:25], v[84:85], v[28:29]
	v_pk_fma_f32 v[22:23], v[22:23], v[82:83], v[26:27]
	v_pk_fma_f32 v[26:27], v[20:21], v[76:77], v[34:35]
	v_pk_fma_f32 v[20:21], v[18:19], v[74:75], v[32:33]
	v_cvt_pk_bf16_f32 v18, v22, v23
	v_cvt_pk_bf16_f32 v19, v24, v25
	s_waitcnt vmcnt(6)
	v_lshlrev_b32_e32 v22, 16, v72
	v_cvt_pk_bf16_f32 v20, v20, v21
	v_cvt_pk_bf16_f32 v21, v26, v27
	global_store_dwordx4 v[30:31], v[18:21], off offset:256 nt
	v_and_b32_e32 v23, 0xffff0000, v72
	v_lshlrev_b32_e32 v24, 16, v73
	v_lshlrev_b32_e32 v18, 16, v70
	v_and_b32_e32 v19, 0xffff0000, v70
	v_and_b32_e32 v25, 0xffff0000, v73
	v_pk_fma_f32 v[14:15], v[14:15], v[94:95], v[18:19]
	v_lshlrev_b32_e32 v20, 16, v71
	v_and_b32_e32 v21, 0xffff0000, v71
	v_pk_fma_f32 v[18:19], v[12:13], v[92:93], v[24:25]
	v_pk_fma_f32 v[12:13], v[10:11], v[90:91], v[22:23]
	v_cvt_pk_bf16_f32 v10, v14, v15
	v_lshl_add_u64 v[14:15], s[60:61], 0, v[78:79]
	v_pk_fma_f32 v[16:17], v[16:17], v[96:97], v[20:21]
	v_lshl_add_u64 v[14:15], v[14:15], 0, v[180:181]
	v_cvt_pk_bf16_f32 v11, v16, v17
	v_cvt_pk_bf16_f32 v12, v12, v13
	v_cvt_pk_bf16_f32 v13, v18, v19
	global_store_dwordx4 v[14:15], v[10:13], off nt
	s_waitcnt vmcnt(7)
	v_lshlrev_b32_e32 v16, 16, v68
	v_and_b32_e32 v17, 0xffff0000, v68
	v_lshlrev_b32_e32 v10, 16, v66
	v_and_b32_e32 v11, 0xffff0000, v66
	v_lshlrev_b32_e32 v18, 16, v69
	v_and_b32_e32 v19, 0xffff0000, v69
	v_lshlrev_b32_e32 v12, 16, v67
	v_and_b32_e32 v13, 0xffff0000, v67
	v_pk_fma_f32 v[6:7], v[6:7], v[82:83], v[10:11]
	v_pk_fma_f32 v[10:11], v[4:5], v[76:77], v[18:19]
	v_pk_fma_f32 v[4:5], v[2:3], v[74:75], v[16:17]
	v_pk_fma_f32 v[8:9], v[8:9], v[84:85], v[12:13]
	v_cvt_pk_bf16_f32 v2, v6, v7
	s_nop 0
	v_cvt_pk_bf16_f32 v3, v8, v9
	v_cvt_pk_bf16_f32 v4, v4, v5
	v_cvt_pk_bf16_f32 v5, v10, v11
	global_store_dwordx4 v[14:15], v[2:5], off offset:256 nt
	s_cbranch_vccnz .LBB0_2089
	s_and_b64 vcc, exec, s[6:7]
	s_cbranch_vccnz .LBB0_2088
	s_barrier
	s_branch .LBB0_2088

; __device__ __forceinline__ u32x4 pack8(const f32x4& a, const f32x4& b) { u32x4 w; w.x = cvt_pk_bf16(a[0], a[1]); w.y = cvt_pk_bf16(a[2], a[3]); w.z = cvt_pk_bf16(b[0], b[1]); w.w = cvt_pk_bf16(b[2], b[3]); return w; }
;     __device__ __forceinline__ void operator()(const f32x4 (&acc)[2][2][4][2], const Unit& u, int wr, int wc, int fr, int fq) const {
;         const int row0 = u.pm * BM + wr * 64 + fr, col0 = u.pn * BM + wc * 32 + 8 * fq;
;         const float* gp = gate + (size_t)(u.pm >> 3) * 12288 + col0;
;         f32x4 gv[2][2];
; #pragma unroll
;         for (int bj = 0; bj < 2; ++bj)
; #pragma unroll
;             for (int n = 0; n < 2; ++n) { gv[bj][n] = *(const f32x4*)(gp + bj * HALF + n * 4); if (cscale) gv[bj][n] = gv[bj][n] * *(const f32x4*)(cscale + col0 + bj * HALF + n * 4); }
;     ...
;             for (int ai = 0; ai < 2; ++ai) { u32x4 xw[4][2];
; #pragma unroll
;                 for (int m = 0; m < 4; ++m)
; #pragma unroll
;                     for (int bj = 0; bj < 2; ++bj) xw[m][bj] = *(const u32x4*)((const bf16_t*)xin + (size_t)(row0 + ai * HALF + m * 16) * 2048 + col0 + bj * HALF);
; #pragma unroll
;                 for (int m = 0; m < 4; ++m)
; #pragma unroll
;                     for (int bj = 0; bj < 2; ++bj) { const u32x4 w = xw[m][bj];
;                         const f32x4 x0 = (f32x4){__builtin_bit_cast(float, w.x << 16), __builtin_bit_cast(float, w.x & 0xffff0000u), __builtin_bit_cast(float, w.y << 16), __builtin_bit_cast(float, w.y & 0xffff0000u)};
;                         const f32x4 x1 = (f32x4){__builtin_bit_cast(float, w.z << 16), __builtin_bit_cast(float, w.z & 0xffff0000u), __builtin_bit_cast(float, w.w << 16), __builtin_bit_cast(float, w.w & 0xffff0000u)};
;                         *(u32x4*)(xout + (size_t)(row0 + ai * HALF + m * 16) * 2048 + col0 + bj * HALF) = pack8(x0 + gv[bj][0] * acc[ai][bj][m][0], x1 + gv[bj][1] * acc[ai][bj][m][1]); }
.LBB0_2393:
	v_mov_b32_e32 v84, v252
	s_lshl_b32 s0, s82, 8
	v_ashrrev_i32_e32 v82, 1, v84
	s_or_b32 s0, s0, s72
	v_and_b32_e32 v82, -8, v82
	v_add_u32_e32 v82, s0, v82
	s_ashr_i32 s0, s81, 3
	s_mul_hi_i32 s1, s0, 0xc000
	s_mul_i32 s0, s0, 0xc000
	s_add_u32 s0, s55, s0
	s_addc_u32 s1, s70, s1
	s_lshl_b32 s33, s81, 8
	s_add_i32 s33, s33, s71
	v_ashrrev_i32_e32 v83, 31, v82
	v_and_or_b32 v146, v84, 15, s33
	v_lshlrev_b64 v[180:181], 1, v[82:83]
	v_ashrrev_i32_e32 v147, 31, v146
	v_lshl_add_u64 v[182:183], s[60:61], 0, v[180:181]
	v_lshlrev_b64 v[184:185], 12, v[146:147]
	v_or_b32_e32 v148, 16, v146
	v_lshl_add_u64 v[84:85], v[182:183], 0, v[184:185]
	v_ashrrev_i32_e32 v149, 31, v148
	global_load_dwordx4 v[196:199], v[84:85], off
	global_load_dwordx4 v[200:203], v[84:85], off offset:256
	v_lshl_add_u64 v[86:87], v[82:83], 2, s[0:1]
	v_lshlrev_b64 v[190:191], 12, v[148:149]
	global_load_dwordx4 v[102:105], v[86:87], off
	global_load_dwordx4 v[98:101], v[86:87], off offset:16
	global_load_dwordx4 v[82:85], v[86:87], off offset:528
	s_nop 0
	global_load_dwordx4 v[86:89], v[86:87], off offset:512
	v_lshl_add_u64 v[148:149], v[182:183], 0, v[190:191]
	global_load_dwordx4 v[166:169], v[148:149], off
	global_load_dwordx4 v[154:157], v[148:149], off offset:256
	v_or_b32_e32 v148, 32, v146
	v_ashrrev_i32_e32 v149, 31, v148
	v_lshlrev_b64 v[188:189], 12, v[148:149]
	v_lshl_add_u64 v[148:149], v[182:183], 0, v[188:189]
	global_load_dwordx4 v[150:153], v[148:149], off
	v_or_b32_e32 v146, 48, v146
	v_ashrrev_i32_e32 v147, 31, v146
	v_lshlrev_b64 v[186:187], 12, v[146:147]
	v_lshl_add_u64 v[146:147], s[60:61], 0, v[184:185]
	v_lshl_add_u64 v[204:205], v[182:183], 0, v[186:187]
	v_lshl_add_u64 v[206:207], v[146:147], 0, v[180:181]
	global_load_dwordx4 v[162:165], v[148:149], off offset:256
	global_load_dwordx4 v[158:161], v[204:205], off
	s_nop 0
	global_load_dwordx4 v[146:149], v[204:205], off offset:256
	s_mov_b64 s[0:1], 0x80000
	s_and_b64 vcc, exec, s[8:9]
	s_mov_b64 s[8:9], -1
	s_waitcnt vmcnt(0)
	v_lshlrev_b32_e32 v204, 16, v196
	v_and_b32_e32 v205, 0xffff0000, v196
	v_lshlrev_b32_e32 v196, 16, v197
	v_and_b32_e32 v197, 0xffff0000, v197
	v_lshlrev_b32_e32 v208, 16, v198
	v_and_b32_e32 v209, 0xffff0000, v198
	v_lshlrev_b32_e32 v198, 16, v199
	v_and_b32_e32 v199, 0xffff0000, v199
	v_lshlrev_b32_e32 v210, 16, v200
	v_and_b32_e32 v211, 0xffff0000, v200
	v_lshlrev_b32_e32 v200, 16, v201
	v_and_b32_e32 v201, 0xffff0000, v201
	v_lshlrev_b32_e32 v212, 16, v202
	v_and_b32_e32 v213, 0xffff0000, v202
	v_lshlrev_b32_e32 v202, 16, v203
	v_and_b32_e32 v203, 0xffff0000, v203
	v_pk_fma_f32 v[144:145], v[144:145], v[104:105], v[196:197]
	v_pk_fma_f32 v[140:141], v[140:141], v[100:101], v[198:199]
	v_pk_fma_f32 v[136:137], v[136:137], v[88:89], v[200:201]
	v_pk_fma_f32 v[196:197], v[132:133], v[84:85], v[202:203]
	v_lshlrev_b32_e32 v200, 16, v166
	v_and_b32_e32 v201, 0xffff0000, v166
	v_lshlrev_b32_e32 v202, 16, v168
	v_and_b32_e32 v203, 0xffff0000, v168
	v_pk_fma_f32 v[142:143], v[142:143], v[102:103], v[204:205]
	v_pk_fma_f32 v[138:139], v[138:139], v[98:99], v[208:209]
	v_pk_fma_f32 v[134:135], v[134:135], v[86:87], v[210:211]
	v_pk_fma_f32 v[198:199], v[130:131], v[82:83], v[212:213]
	v_lshlrev_b32_e32 v168, 16, v169
	v_and_b32_e32 v169, 0xffff0000, v169
	v_cvt_pk_bf16_f32 v130, v142, v143
	v_cvt_pk_bf16_f32 v131, v144, v145
	v_cvt_pk_bf16_f32 v132, v138, v139
	v_cvt_pk_bf16_f32 v133, v140, v141
	v_pk_fma_f32 v[126:127], v[126:127], v[102:103], v[200:201]
	v_pk_fma_f32 v[140:141], v[122:123], v[98:99], v[202:203]
	global_store_dwordx4 v[206:207], v[130:133], off nt
	v_cvt_pk_bf16_f32 v122, v134, v135
	v_lshlrev_b32_e32 v166, 16, v167
	v_and_b32_e32 v167, 0xffff0000, v167
	v_pk_fma_f32 v[138:139], v[124:125], v[100:101], v[168:169]
	v_cvt_pk_bf16_f32 v123, v136, v137
	v_cvt_pk_bf16_f32 v124, v198, v199
	v_cvt_pk_bf16_f32 v125, v196, v197
	global_store_dwordx4 v[206:207], v[122:125], off offset:256 nt
	v_pk_fma_f32 v[128:129], v[128:129], v[104:105], v[166:167]
	v_lshlrev_b32_e32 v130, 16, v157
	v_cvt_pk_bf16_f32 v122, v126, v127
	v_lshl_add_u64 v[126:127], s[60:61], 0, v[190:191]
	v_cvt_pk_bf16_f32 v123, v128, v129
	v_cvt_pk_bf16_f32 v124, v140, v141
	v_cvt_pk_bf16_f32 v125, v138, v139
	v_lshl_add_u64 v[126:127], v[126:127], 0, v[180:181]
	global_store_dwordx4 v[126:127], v[122:125], off nt
	v_lshlrev_b32_e32 v128, 16, v156
	v_and_b32_e32 v129, 0xffff0000, v156
	v_lshlrev_b32_e32 v122, 16, v154
	v_and_b32_e32 v123, 0xffff0000, v154
	v_lshlrev_b32_e32 v124, 16, v155
	v_and_b32_e32 v125, 0xffff0000, v155
	v_and_b32_e32 v131, 0xffff0000, v157
	v_pk_fma_f32 v[120:121], v[120:121], v[88:89], v[124:125]
	v_pk_fma_f32 v[118:119], v[118:119], v[86:87], v[122:123]
	v_pk_fma_f32 v[122:123], v[116:117], v[84:85], v[130:131]
	v_pk_fma_f32 v[116:117], v[114:115], v[82:83], v[128:129]
	v_cvt_pk_bf16_f32 v114, v118, v119
	v_cvt_pk_bf16_f32 v115, v120, v121
	v_lshlrev_b32_e32 v118, 16, v152
	v_cvt_pk_bf16_f32 v116, v116, v117
	v_cvt_pk_bf16_f32 v117, v122, v123
	global_store_dwordx4 v[126:127], v[114:117], off offset:256 nt
	v_and_b32_e32 v119, 0xffff0000, v152
	v_lshlrev_b32_e32 v120, 16, v153
	v_lshlrev_b32_e32 v114, 16, v150
	v_and_b32_e32 v115, 0xffff0000, v150
	v_and_b32_e32 v121, 0xffff0000, v153
	v_pk_fma_f32 v[110:111], v[110:111], v[102:103], v[114:115]
	v_lshlrev_b32_e32 v116, 16, v151
	v_and_b32_e32 v117, 0xffff0000, v151
	v_pk_fma_f32 v[114:115], v[108:109], v[100:101], v[120:121]
	v_pk_fma_f32 v[108:109], v[106:107], v[98:99], v[118:119]
	v_cvt_pk_bf16_f32 v106, v110, v111
	v_lshl_add_u64 v[110:111], s[60:61], 0, v[188:189]
	v_pk_fma_f32 v[112:113], v[112:113], v[104:105], v[116:117]
; __device__ __forceinline__ u32x4 pack8(const f32x4& a, const f32x4& b) { u32x4 w; w.x = cvt_pk_bf16(a[0], a[1]); w.y = cvt_pk_bf16(a[2], a[3]); w.z = cvt_pk_bf16(b[0], b[1]); w.w = cvt_pk_bf16(b[2], b[3]); return w; }
;     __device__ __forceinline__ void operator()(const f32x4 (&acc)[2][2][4][2], const Unit& u, int wr, int wc, int fr, int fq) const {
;     ...
;             for (int ai = 0; ai < 2; ++ai) { u32x4 xw[4][2];
; #pragma unroll
;                 for (int m = 0; m < 4; ++m)
; #pragma unroll
;                     for (int bj = 0; bj < 2; ++bj) xw[m][bj] = *(const u32x4*)((const bf16_t*)xin + (size_t)(row0 + ai * HALF + m * 16) * 2048 + col0 + bj * HALF);
; #pragma unroll
;                 for (int m = 0; m < 4; ++m)
; #pragma unroll
;                     for (int bj = 0; bj < 2; ++bj) { const u32x4 w = xw[m][bj];
;                         const f32x4 x0 = (f32x4){__builtin_bit_cast(float, w.x << 16), __builtin_bit_cast(float, w.x & 0xffff0000u), __builtin_bit_cast(float, w.y << 16), __builtin_bit_cast(float, w.y & 0xffff0000u)};
;                         const f32x4 x1 = (f32x4){__builtin_bit_cast(float, w.z << 16), __builtin_bit_cast(float, w.z & 0xffff0000u), __builtin_bit_cast(float, w.w << 16), __builtin_bit_cast(float, w.w & 0xffff0000u)};
;                         *(u32x4*)(xout + (size_t)(row0 + ai * HALF + m * 16) * 2048 + col0 + bj * HALF) = pack8(x0 + gv[bj][0] * acc[ai][bj][m][0], x1 + gv[bj][1] * acc[ai][bj][m][1]); }
	v_lshl_add_u64 v[110:111], v[110:111], 0, v[180:181]
	v_cvt_pk_bf16_f32 v107, v112, v113
	v_cvt_pk_bf16_f32 v108, v108, v109
	v_cvt_pk_bf16_f32 v109, v114, v115
	global_store_dwordx4 v[110:111], v[106:109], off nt
	v_lshlrev_b32_e32 v112, 16, v164
	v_and_b32_e32 v113, 0xffff0000, v164
	v_lshlrev_b32_e32 v106, 16, v162
	v_and_b32_e32 v107, 0xffff0000, v162
	v_lshlrev_b32_e32 v108, 16, v163
	v_and_b32_e32 v109, 0xffff0000, v163
	v_lshlrev_b32_e32 v114, 16, v165
	v_and_b32_e32 v115, 0xffff0000, v165
	v_pk_fma_f32 v[96:97], v[96:97], v[88:89], v[108:109]
	v_pk_fma_f32 v[94:95], v[94:95], v[86:87], v[106:107]
	v_pk_fma_f32 v[106:107], v[92:93], v[84:85], v[114:115]
	v_pk_fma_f32 v[92:93], v[90:91], v[82:83], v[112:113]
	v_cvt_pk_bf16_f32 v90, v94, v95
	v_cvt_pk_bf16_f32 v91, v96, v97
	v_lshlrev_b32_e32 v94, 16, v160
	v_cvt_pk_bf16_f32 v92, v92, v93
	v_cvt_pk_bf16_f32 v93, v106, v107
	global_store_dwordx4 v[110:111], v[90:93], off offset:256 nt
	v_and_b32_e32 v95, 0xffff0000, v160
	v_lshlrev_b32_e32 v96, 16, v161
	v_lshlrev_b32_e32 v90, 16, v158
	v_and_b32_e32 v91, 0xffff0000, v158
	v_and_b32_e32 v97, 0xffff0000, v161
	v_pk_fma_f32 v[78:79], v[78:79], v[102:103], v[90:91]
	v_lshlrev_b32_e32 v92, 16, v159
	v_and_b32_e32 v93, 0xffff0000, v159
	v_pk_fma_f32 v[90:91], v[76:77], v[100:101], v[96:97]
	v_pk_fma_f32 v[76:77], v[74:75], v[98:99], v[94:95]
	v_cvt_pk_bf16_f32 v74, v78, v79
	v_lshl_add_u64 v[78:79], s[60:61], 0, v[186:187]
	v_pk_fma_f32 v[80:81], v[80:81], v[104:105], v[92:93]
	v_lshl_add_u64 v[78:79], v[78:79], 0, v[180:181]
	v_cvt_pk_bf16_f32 v75, v80, v81
	v_cvt_pk_bf16_f32 v76, v76, v77
	v_cvt_pk_bf16_f32 v77, v90, v91
	global_store_dwordx4 v[78:79], v[74:77], off nt
	v_lshlrev_b32_e32 v80, 16, v148
	v_and_b32_e32 v81, 0xffff0000, v148
	v_lshlrev_b32_e32 v74, 16, v146
	v_and_b32_e32 v75, 0xffff0000, v146
	v_lshlrev_b32_e32 v90, 16, v149
	v_and_b32_e32 v91, 0xffff0000, v149
	v_lshlrev_b32_e32 v76, 16, v147
	v_and_b32_e32 v77, 0xffff0000, v147
	v_pk_fma_f32 v[70:71], v[70:71], v[86:87], v[74:75]
	v_pk_fma_f32 v[74:75], v[68:69], v[84:85], v[90:91]
	v_pk_fma_f32 v[68:69], v[66:67], v[82:83], v[80:81]
	v_pk_fma_f32 v[72:73], v[72:73], v[88:89], v[76:77]
	v_cvt_pk_bf16_f32 v66, v70, v71
	v_lshl_add_u64 v[80:81], v[184:185], 0, s[0:1]
	v_cvt_pk_bf16_f32 v67, v72, v73
	v_cvt_pk_bf16_f32 v68, v68, v69
	v_cvt_pk_bf16_f32 v69, v74, v75
	global_store_dwordx4 v[78:79], v[66:69], off offset:256 nt
	s_mov_b64 s[0:1], 0x90000
	v_lshl_add_u64 v[118:119], v[184:185], 0, s[0:1]
	v_lshl_add_u64 v[66:67], v[182:183], 0, v[80:81]
	global_load_dwordx4 v[76:79], v[66:67], off
	global_load_dwordx4 v[90:93], v[66:67], off offset:256
	v_lshl_add_u64 v[66:67], v[182:183], 0, v[118:119]
	global_load_dwordx4 v[94:97], v[66:67], off
	global_load_dwordx4 v[106:109], v[66:67], off offset:256
	s_mov_b64 s[0:1], 0xa0000
	v_lshl_add_u64 v[120:121], v[184:185], 0, s[0:1]
	v_lshl_add_u64 v[66:67], v[182:183], 0, v[120:121]
	global_load_dwordx4 v[110:113], v[66:67], off
	global_load_dwordx4 v[114:117], v[66:67], off offset:256
	v_lshl_add_u64 v[74:75], v[184:185], 0, s[30:31]
	v_lshl_add_u64 v[66:67], v[182:183], 0, v[74:75]
	global_load_dwordx4 v[70:73], v[66:67], off
	s_nop 0
	global_load_dwordx4 v[66:69], v[66:67], off offset:256
	s_waitcnt vmcnt(7)
	v_lshlrev_b32_e32 v122, 16, v76
	v_and_b32_e32 v123, 0xffff0000, v76
	v_lshlrev_b32_e32 v76, 16, v77
	v_and_b32_e32 v77, 0xffff0000, v77
	v_lshlrev_b32_e32 v124, 16, v78
	v_and_b32_e32 v125, 0xffff0000, v78
	v_lshlrev_b32_e32 v78, 16, v79
	v_and_b32_e32 v79, 0xffff0000, v79
	v_pk_fma_f32 v[62:63], v[62:63], v[102:103], v[122:123]
	v_pk_fma_f32 v[64:65], v[64:65], v[104:105], v[76:77]
	v_pk_fma_f32 v[76:77], v[60:61], v[100:101], v[78:79]
	v_pk_fma_f32 v[60:61], v[58:59], v[98:99], v[124:125]
	v_cvt_pk_bf16_f32 v58, v62, v63
	v_lshl_add_u64 v[62:63], s[60:61], 0, v[80:81]
	v_cvt_pk_bf16_f32 v59, v64, v65
	v_cvt_pk_bf16_f32 v60, v60, v61
	v_cvt_pk_bf16_f32 v61, v76, v77
	v_lshl_add_u64 v[62:63], v[62:63], 0, v[180:181]
	global_store_dwordx4 v[62:63], v[58:61], off nt
	s_waitcnt vmcnt(7)
	v_lshlrev_b32_e32 v64, 16, v92
	v_and_b32_e32 v65, 0xffff0000, v92
	v_lshlrev_b32_e32 v58, 16, v90
	v_and_b32_e32 v59, 0xffff0000, v90
	v_lshlrev_b32_e32 v60, 16, v91
	v_and_b32_e32 v61, 0xffff0000, v91
	v_lshlrev_b32_e32 v76, 16, v93
	v_and_b32_e32 v77, 0xffff0000, v93
	v_pk_fma_f32 v[56:57], v[56:57], v[88:89], v[60:61]
	v_pk_fma_f32 v[54:55], v[54:55], v[86:87], v[58:59]
	v_pk_fma_f32 v[58:59], v[52:53], v[84:85], v[76:77]
	v_pk_fma_f32 v[52:53], v[50:51], v[82:83], v[64:65]
	v_cvt_pk_bf16_f32 v50, v54, v55
	v_cvt_pk_bf16_f32 v51, v56, v57
	s_waitcnt vmcnt(6)
; __device__ __forceinline__ u32x4 pack8(const f32x4& a, const f32x4& b) { u32x4 w; w.x = cvt_pk_bf16(a[0], a[1]); w.y = cvt_pk_bf16(a[2], a[3]); w.z = cvt_pk_bf16(b[0], b[1]); w.w = cvt_pk_bf16(b[2], b[3]); return w; }
; #define PG8_BAR __builtin_amdgcn_s_barrier()
;     __device__ __forceinline__ void operator()(const f32x4 (&acc)[2][2][4][2], const Unit& u, int wr, int wc, int fr, int fq) const {
;     ...
;             for (int ai = 0; ai < 2; ++ai) { u32x4 xw[4][2];
; #pragma unroll
;                 for (int m = 0; m < 4; ++m)
; #pragma unroll
;                     for (int bj = 0; bj < 2; ++bj) xw[m][bj] = *(const u32x4*)((const bf16_t*)xin + (size_t)(row0 + ai * HALF + m * 16) * 2048 + col0 + bj * HALF);
; #pragma unroll
;                 for (int m = 0; m < 4; ++m)
; #pragma unroll
;                     for (int bj = 0; bj < 2; ++bj) { const u32x4 w = xw[m][bj];
;                         const f32x4 x0 = (f32x4){__builtin_bit_cast(float, w.x << 16), __builtin_bit_cast(float, w.x & 0xffff0000u), __builtin_bit_cast(float, w.y << 16), __builtin_bit_cast(float, w.y & 0xffff0000u)};
;                         const f32x4 x1 = (f32x4){__builtin_bit_cast(float, w.z << 16), __builtin_bit_cast(float, w.z & 0xffff0000u), __builtin_bit_cast(float, w.w << 16), __builtin_bit_cast(float, w.w & 0xffff0000u)};
;                         *(u32x4*)(xout + (size_t)(row0 + ai * HALF + m * 16) * 2048 + col0 + bj * HALF) = pack8(x0 + gv[bj][0] * acc[ai][bj][m][0], x1 + gv[bj][1] * acc[ai][bj][m][1]); }
;                 asm volatile("" ::: "memory"); }
; template <class Epi, class Sched, bool ALIGN_EPI = true, bool SP2 = true, bool FULLLINE = false, bool NOSTAGE = false, bool FP8 = false>
; __device__ __forceinline__ void gemm_phase(PG8_LAS unsigned char* lds, const Gemm g, const Sched& S, const Epi& E) {
;     ...
;         if (!has_next) break;
; #pragma unroll
;         for (int a = 0; a < 2; ++a)
; #pragma unroll
;             for (int b = 0; b < 2; ++b)
; #pragma unroll
;                 for (int m = 0; m < 4; ++m)
; #pragma unroll
;                     for (int n = 0; n < 2; ++n) acc[a][b][m][n] = (f32x4){0.f, 0.f, 0.f, 0.f};
;         cur = nxt; cA = nA; cB = nB; ++ui;
;         if constexpr (ALIGN_EPI) { if (wr == 1) PG8_BAR; }
	v_lshlrev_b32_e32 v54, 16, v96
	v_cvt_pk_bf16_f32 v52, v52, v53
	v_cvt_pk_bf16_f32 v53, v58, v59
	global_store_dwordx4 v[62:63], v[50:53], off offset:256 nt
	v_and_b32_e32 v55, 0xffff0000, v96
	v_lshlrev_b32_e32 v56, 16, v97
	v_lshlrev_b32_e32 v50, 16, v94
	v_and_b32_e32 v51, 0xffff0000, v94
	v_and_b32_e32 v57, 0xffff0000, v97
	v_pk_fma_f32 v[46:47], v[46:47], v[102:103], v[50:51]
	v_lshlrev_b32_e32 v52, 16, v95
	v_and_b32_e32 v53, 0xffff0000, v95
	v_pk_fma_f32 v[50:51], v[44:45], v[100:101], v[56:57]
	v_pk_fma_f32 v[44:45], v[42:43], v[98:99], v[54:55]
	v_cvt_pk_bf16_f32 v42, v46, v47
	v_lshl_add_u64 v[46:47], s[60:61], 0, v[118:119]
	v_pk_fma_f32 v[48:49], v[48:49], v[104:105], v[52:53]
	v_lshl_add_u64 v[46:47], v[46:47], 0, v[180:181]
	v_cvt_pk_bf16_f32 v43, v48, v49
	v_cvt_pk_bf16_f32 v44, v44, v45
	v_cvt_pk_bf16_f32 v45, v50, v51
	global_store_dwordx4 v[46:47], v[42:45], off nt
	s_waitcnt vmcnt(7)
	v_lshlrev_b32_e32 v48, 16, v108
	v_and_b32_e32 v49, 0xffff0000, v108
	v_lshlrev_b32_e32 v42, 16, v106
	v_and_b32_e32 v43, 0xffff0000, v106
	v_lshlrev_b32_e32 v44, 16, v107
	v_and_b32_e32 v45, 0xffff0000, v107
	v_lshlrev_b32_e32 v50, 16, v109
	v_and_b32_e32 v51, 0xffff0000, v109
	v_pk_fma_f32 v[40:41], v[40:41], v[88:89], v[44:45]
	v_pk_fma_f32 v[38:39], v[38:39], v[86:87], v[42:43]
	v_pk_fma_f32 v[42:43], v[36:37], v[84:85], v[50:51]
	v_pk_fma_f32 v[36:37], v[34:35], v[82:83], v[48:49]
	v_cvt_pk_bf16_f32 v34, v38, v39
	v_cvt_pk_bf16_f32 v35, v40, v41
	s_waitcnt vmcnt(6)
	v_lshlrev_b32_e32 v38, 16, v112
	v_cvt_pk_bf16_f32 v36, v36, v37
	v_cvt_pk_bf16_f32 v37, v42, v43
	global_store_dwordx4 v[46:47], v[34:37], off offset:256 nt
	v_and_b32_e32 v39, 0xffff0000, v112
	v_lshlrev_b32_e32 v40, 16, v113
	v_lshlrev_b32_e32 v34, 16, v110
	v_and_b32_e32 v35, 0xffff0000, v110
	v_and_b32_e32 v41, 0xffff0000, v113
	v_pk_fma_f32 v[30:31], v[30:31], v[102:103], v[34:35]
	v_lshlrev_b32_e32 v36, 16, v111
	v_and_b32_e32 v37, 0xffff0000, v111
	v_pk_fma_f32 v[34:35], v[28:29], v[100:101], v[40:41]
	v_pk_fma_f32 v[28:29], v[26:27], v[98:99], v[38:39]
	v_cvt_pk_bf16_f32 v26, v30, v31
	v_lshl_add_u64 v[30:31], s[60:61], 0, v[120:121]
	v_pk_fma_f32 v[32:33], v[32:33], v[104:105], v[36:37]
	v_lshl_add_u64 v[30:31], v[30:31], 0, v[180:181]
	v_cvt_pk_bf16_f32 v27, v32, v33
	v_cvt_pk_bf16_f32 v28, v28, v29
	v_cvt_pk_bf16_f32 v29, v34, v35
	global_store_dwordx4 v[30:31], v[26:29], off nt
	s_waitcnt vmcnt(7)
	v_lshlrev_b32_e32 v32, 16, v116
	v_and_b32_e32 v33, 0xffff0000, v116
	v_lshlrev_b32_e32 v26, 16, v114
	v_and_b32_e32 v27, 0xffff0000, v114
	v_lshlrev_b32_e32 v28, 16, v115
	v_and_b32_e32 v29, 0xffff0000, v115
	v_lshlrev_b32_e32 v34, 16, v117
	v_and_b32_e32 v35, 0xffff0000, v117
	v_pk_fma_f32 v[24:25], v[24:25], v[88:89], v[28:29]
	v_pk_fma_f32 v[22:23], v[22:23], v[86:87], v[26:27]
	v_pk_fma_f32 v[26:27], v[20:21], v[84:85], v[34:35]
	v_pk_fma_f32 v[20:21], v[18:19], v[82:83], v[32:33]
	v_cvt_pk_bf16_f32 v18, v22, v23
	v_cvt_pk_bf16_f32 v19, v24, v25
	s_waitcnt vmcnt(6)
	v_lshlrev_b32_e32 v22, 16, v72
	v_cvt_pk_bf16_f32 v20, v20, v21
	v_cvt_pk_bf16_f32 v21, v26, v27
	global_store_dwordx4 v[30:31], v[18:21], off offset:256 nt
	v_and_b32_e32 v23, 0xffff0000, v72
	v_lshlrev_b32_e32 v24, 16, v73
	v_lshlrev_b32_e32 v18, 16, v70
	v_and_b32_e32 v19, 0xffff0000, v70
	v_and_b32_e32 v25, 0xffff0000, v73
	v_pk_fma_f32 v[14:15], v[14:15], v[102:103], v[18:19]
	v_lshlrev_b32_e32 v20, 16, v71
	v_and_b32_e32 v21, 0xffff0000, v71
	v_pk_fma_f32 v[18:19], v[12:13], v[100:101], v[24:25]
	v_pk_fma_f32 v[12:13], v[10:11], v[98:99], v[22:23]
	v_cvt_pk_bf16_f32 v10, v14, v15
	v_lshl_add_u64 v[14:15], s[60:61], 0, v[74:75]
	v_pk_fma_f32 v[16:17], v[16:17], v[104:105], v[20:21]
	v_lshl_add_u64 v[14:15], v[14:15], 0, v[180:181]
	v_cvt_pk_bf16_f32 v11, v16, v17
	v_cvt_pk_bf16_f32 v12, v12, v13
	v_cvt_pk_bf16_f32 v13, v18, v19
	global_store_dwordx4 v[14:15], v[10:13], off nt
	s_waitcnt vmcnt(7)
	v_lshlrev_b32_e32 v16, 16, v68
	v_and_b32_e32 v17, 0xffff0000, v68
	v_lshlrev_b32_e32 v10, 16, v66
	v_and_b32_e32 v11, 0xffff0000, v66
	v_lshlrev_b32_e32 v18, 16, v69
	v_and_b32_e32 v19, 0xffff0000, v69
	v_lshlrev_b32_e32 v12, 16, v67
	v_and_b32_e32 v13, 0xffff0000, v67
	v_pk_fma_f32 v[6:7], v[6:7], v[86:87], v[10:11]
	v_pk_fma_f32 v[10:11], v[4:5], v[84:85], v[18:19]
	v_pk_fma_f32 v[4:5], v[2:3], v[82:83], v[16:17]
	v_pk_fma_f32 v[8:9], v[8:9], v[88:89], v[12:13]
	v_cvt_pk_bf16_f32 v2, v6, v7
	s_nop 0
	v_cvt_pk_bf16_f32 v3, v8, v9
	v_cvt_pk_bf16_f32 v4, v4, v5
	v_cvt_pk_bf16_f32 v5, v10, v11
	global_store_dwordx4 v[14:15], v[2:5], off offset:256 nt
	s_cbranch_vccnz .LBB0_2378
	s_and_b64 vcc, exec, s[6:7]
	s_cbranch_vccnz .LBB0_2377
	s_barrier
	s_branch .LBB0_2377

; __device__ __forceinline__ u32x4 pack8(const f32x4& a, const f32x4& b) { u32x4 w; w.x = cvt_pk_bf16(a[0], a[1]); w.y = cvt_pk_bf16(a[2], a[3]); w.z = cvt_pk_bf16(b[0], b[1]); w.w = cvt_pk_bf16(b[2], b[3]); return w; }
;     __device__ __forceinline__ void operator()(const f32x4 (&acc)[2][2][4][2], const Unit& u, int wr, int wc, int fr, int fq) const {
;     ...
;             for (int ai = 0; ai < 2; ++ai) { u32x4 xw[4][2];
; #pragma unroll
;                 for (int m = 0; m < 4; ++m)
; #pragma unroll
;                     for (int bj = 0; bj < 2; ++bj) xw[m][bj] = *(const u32x4*)((const bf16_t*)xin + (size_t)(row0 + ai * HALF + m * 16) * 2048 + col0 + bj * HALF);
; #pragma unroll
;                 for (int m = 0; m < 4; ++m)
; #pragma unroll
;                     for (int bj = 0; bj < 2; ++bj) { const u32x4 w = xw[m][bj];
;                         const f32x4 x0 = (f32x4){__builtin_bit_cast(float, w.x << 16), __builtin_bit_cast(float, w.x & 0xffff0000u), __builtin_bit_cast(float, w.y << 16), __builtin_bit_cast(float, w.y & 0xffff0000u)};
;                         const f32x4 x1 = (f32x4){__builtin_bit_cast(float, w.z << 16), __builtin_bit_cast(float, w.z & 0xffff0000u), __builtin_bit_cast(float, w.w << 16), __builtin_bit_cast(float, w.w & 0xffff0000u)};
;                         *(u32x4*)(xout + (size_t)(row0 + ai * HALF + m * 16) * 2048 + col0 + bj * HALF) = pack8(x0 + gv[bj][0] * acc[ai][bj][m][0], x1 + gv[bj][1] * acc[ai][bj][m][1]); }
.LBB0_2693:
	s_lshl_b32 s0, s40, 8
	s_add_i32 s0, s0, s70
	v_and_or_b32 v166, v150, 15, s0
	v_lshlrev_b64 v[188:189], 1, v[146:147]
	v_ashrrev_i32_e32 v167, 31, v166
	v_lshl_add_u64 v[190:191], s[60:61], 0, v[188:189]
	v_lshlrev_b64 v[192:193], 12, v[166:167]
	v_lshl_add_u64 v[146:147], v[190:191], 0, v[192:193]
	global_load_dwordx4 v[170:173], v[146:147], off
	global_load_dwordx4 v[162:165], v[146:147], off offset:256
	v_or_b32_e32 v146, 16, v166
	v_ashrrev_i32_e32 v147, 31, v146
	v_lshlrev_b64 v[154:155], 12, v[146:147]
	v_lshl_add_u64 v[146:147], v[190:191], 0, v[154:155]
	global_load_dwordx4 v[158:161], v[146:147], off
	global_load_dwordx4 v[150:153], v[146:147], off offset:256
	v_or_b32_e32 v146, 32, v166
	v_ashrrev_i32_e32 v147, 31, v146
	v_lshlrev_b64 v[196:197], 12, v[146:147]
	v_lshl_add_u64 v[156:157], v[190:191], 0, v[196:197]
	global_load_dwordx4 v[146:149], v[156:157], off
	v_or_b32_e32 v166, 48, v166
	v_ashrrev_i32_e32 v167, 31, v166
	v_lshlrev_b64 v[194:195], 12, v[166:167]
	v_lshl_add_u64 v[166:167], s[60:61], 0, v[192:193]
	v_lshl_add_u64 v[204:205], v[190:191], 0, v[194:195]
	v_lshl_add_u64 v[198:199], v[166:167], 0, v[188:189]
	v_lshl_add_u64 v[206:207], s[60:61], 0, v[154:155]
	global_load_dwordx4 v[174:177], v[156:157], off offset:256
	global_load_dwordx4 v[166:169], v[204:205], off
	s_nop 0
	global_load_dwordx4 v[154:157], v[204:205], off offset:256
	v_lshl_add_u64 v[204:205], v[206:207], 0, v[188:189]
	s_mov_b64 s[0:1], 0x90000
	s_and_b64 vcc, exec, s[8:9]
	s_mov_b64 s[8:9], -1
	s_waitcnt vmcnt(0)
	v_lshlrev_b32_e32 v206, 16, v170
	v_and_b32_e32 v207, 0xffff0000, v170
	v_lshlrev_b32_e32 v170, 16, v171
	v_and_b32_e32 v171, 0xffff0000, v171
	v_lshlrev_b32_e32 v208, 16, v172
	v_and_b32_e32 v209, 0xffff0000, v172
	v_lshlrev_b32_e32 v172, 16, v173
	v_and_b32_e32 v173, 0xffff0000, v173
	v_lshlrev_b32_e32 v210, 16, v162
	v_and_b32_e32 v211, 0xffff0000, v162
	v_lshlrev_b32_e32 v162, 16, v163
	v_and_b32_e32 v163, 0xffff0000, v163
	v_lshlrev_b32_e32 v212, 16, v164
	v_and_b32_e32 v213, 0xffff0000, v164
	v_lshlrev_b32_e32 v164, 16, v165
	v_and_b32_e32 v165, 0xffff0000, v165
	v_pk_fma_f32 v[136:137], v[136:137], v[88:89], v[170:171]
	v_pk_fma_f32 v[170:171], v[132:133], v[104:105], v[172:173]
	v_pk_fma_f32 v[132:133], v[130:131], v[102:103], v[208:209]
	v_lshlrev_b32_e32 v172, 16, v150
	v_and_b32_e32 v173, 0xffff0000, v150
	v_lshlrev_b32_e32 v150, 16, v151
	v_and_b32_e32 v151, 0xffff0000, v151
	v_pk_fma_f32 v[134:135], v[134:135], v[86:87], v[206:207]
	v_pk_fma_f32 v[144:145], v[144:145], v[96:97], v[162:163]
	v_pk_fma_f32 v[142:143], v[142:143], v[94:95], v[210:211]
	v_pk_fma_f32 v[140:141], v[140:141], v[108:109], v[164:165]
	v_lshlrev_b32_e32 v162, 16, v158
	v_and_b32_e32 v163, 0xffff0000, v158
	v_lshlrev_b32_e32 v158, 16, v159
	v_and_b32_e32 v159, 0xffff0000, v159
	v_lshlrev_b32_e32 v164, 16, v160
	v_and_b32_e32 v165, 0xffff0000, v160
	v_cvt_pk_bf16_f32 v130, v134, v135
	v_cvt_pk_bf16_f32 v131, v136, v137
	v_cvt_pk_bf16_f32 v132, v132, v133
	v_cvt_pk_bf16_f32 v133, v170, v171
	v_pk_fma_f32 v[136:137], v[120:121], v[96:97], v[150:151]
	global_store_dwordx4 v[198:199], v[130:133], off nt
	v_cvt_pk_bf16_f32 v120, v142, v143
	v_cvt_pk_bf16_f32 v121, v144, v145
	v_pk_fma_f32 v[138:139], v[138:139], v[106:107], v[212:213]
	v_lshlrev_b32_e32 v160, 16, v161
	v_and_b32_e32 v161, 0xffff0000, v161
	v_lshlrev_b32_e32 v206, 16, v152
	v_and_b32_e32 v207, 0xffff0000, v152
	v_lshlrev_b32_e32 v152, 16, v153
	v_and_b32_e32 v153, 0xffff0000, v153
	v_pk_fma_f32 v[128:129], v[128:129], v[88:89], v[158:159]
	v_pk_fma_f32 v[126:127], v[126:127], v[86:87], v[162:163]
	v_pk_fma_f32 v[134:135], v[122:123], v[102:103], v[164:165]
	v_cvt_pk_bf16_f32 v122, v138, v139
	v_cvt_pk_bf16_f32 v123, v140, v141
	global_store_dwordx4 v[198:199], v[120:123], off offset:256 nt
	v_pk_fma_f32 v[124:125], v[124:125], v[104:105], v[160:161]
	v_pk_fma_f32 v[118:119], v[118:119], v[94:95], v[172:173]
	v_cvt_pk_bf16_f32 v120, v126, v127
	v_cvt_pk_bf16_f32 v121, v128, v129
	v_cvt_pk_bf16_f32 v122, v134, v135
	v_cvt_pk_bf16_f32 v123, v124, v125
	global_store_dwordx4 v[204:205], v[120:123], off nt
	s_nop 1
	v_pk_fma_f32 v[120:121], v[116:117], v[108:109], v[152:153]
	v_pk_fma_f32 v[116:117], v[114:115], v[106:107], v[206:207]
	v_cvt_pk_bf16_f32 v114, v118, v119
	v_cvt_pk_bf16_f32 v115, v136, v137
	v_lshlrev_b32_e32 v118, 16, v148
	v_cvt_pk_bf16_f32 v116, v116, v117
	v_cvt_pk_bf16_f32 v117, v120, v121
	global_store_dwordx4 v[204:205], v[114:117], off offset:256 nt
	v_and_b32_e32 v119, 0xffff0000, v148
	v_lshlrev_b32_e32 v120, 16, v149
	v_lshlrev_b32_e32 v114, 16, v146
	v_and_b32_e32 v115, 0xffff0000, v146
	v_and_b32_e32 v121, 0xffff0000, v149
	v_pk_fma_f32 v[110:111], v[110:111], v[86:87], v[114:115]
	v_lshlrev_b32_e32 v116, 16, v147
	v_and_b32_e32 v117, 0xffff0000, v147
	v_pk_fma_f32 v[114:115], v[100:101], v[104:105], v[120:121]
	v_pk_fma_f32 v[100:101], v[98:99], v[102:103], v[118:119]
	v_cvt_pk_bf16_f32 v98, v110, v111
	v_lshl_add_u64 v[110:111], s[60:61], 0, v[196:197]
	v_pk_fma_f32 v[112:113], v[112:113], v[88:89], v[116:117]
	v_lshl_add_u64 v[110:111], v[110:111], 0, v[188:189]
	v_cvt_pk_bf16_f32 v99, v112, v113
	v_cvt_pk_bf16_f32 v100, v100, v101
	v_cvt_pk_bf16_f32 v101, v114, v115
	global_store_dwordx4 v[110:111], v[98:101], off nt
	v_lshlrev_b32_e32 v112, 16, v176
	v_and_b32_e32 v113, 0xffff0000, v176
	v_lshlrev_b32_e32 v98, 16, v174
	v_and_b32_e32 v99, 0xffff0000, v174
	v_lshlrev_b32_e32 v100, 16, v175
	v_and_b32_e32 v101, 0xffff0000, v175
	v_lshlrev_b32_e32 v114, 16, v177
	v_and_b32_e32 v115, 0xffff0000, v177
	v_pk_fma_f32 v[92:93], v[92:93], v[96:97], v[100:101]
; __device__ __forceinline__ u32x4 pack8(const f32x4& a, const f32x4& b) { u32x4 w; w.x = cvt_pk_bf16(a[0], a[1]); w.y = cvt_pk_bf16(a[2], a[3]); w.z = cvt_pk_bf16(b[0], b[1]); w.w = cvt_pk_bf16(b[2], b[3]); return w; }
;     __device__ __forceinline__ void operator()(const f32x4 (&acc)[2][2][4][2], const Unit& u, int wr, int wc, int fr, int fq) const {
;     ...
;             for (int ai = 0; ai < 2; ++ai) { u32x4 xw[4][2];
; #pragma unroll
;                 for (int m = 0; m < 4; ++m)
; #pragma unroll
;                     for (int bj = 0; bj < 2; ++bj) xw[m][bj] = *(const u32x4*)((const bf16_t*)xin + (size_t)(row0 + ai * HALF + m * 16) * 2048 + col0 + bj * HALF);
; #pragma unroll
;                 for (int m = 0; m < 4; ++m)
; #pragma unroll
;                     for (int bj = 0; bj < 2; ++bj) { const u32x4 w = xw[m][bj];
;                         const f32x4 x0 = (f32x4){__builtin_bit_cast(float, w.x << 16), __builtin_bit_cast(float, w.x & 0xffff0000u), __builtin_bit_cast(float, w.y << 16), __builtin_bit_cast(float, w.y & 0xffff0000u)};
;                         const f32x4 x1 = (f32x4){__builtin_bit_cast(float, w.z << 16), __builtin_bit_cast(float, w.z & 0xffff0000u), __builtin_bit_cast(float, w.w << 16), __builtin_bit_cast(float, w.w & 0xffff0000u)};
;                         *(u32x4*)(xout + (size_t)(row0 + ai * HALF + m * 16) * 2048 + col0 + bj * HALF) = pack8(x0 + gv[bj][0] * acc[ai][bj][m][0], x1 + gv[bj][1] * acc[ai][bj][m][1]); }
	v_pk_fma_f32 v[90:91], v[90:91], v[94:95], v[98:99]
	v_pk_fma_f32 v[98:99], v[84:85], v[108:109], v[114:115]
	v_pk_fma_f32 v[84:85], v[82:83], v[106:107], v[112:113]
	v_cvt_pk_bf16_f32 v82, v90, v91
	v_cvt_pk_bf16_f32 v83, v92, v93
	v_lshlrev_b32_e32 v90, 16, v168
	v_cvt_pk_bf16_f32 v84, v84, v85
	v_cvt_pk_bf16_f32 v85, v98, v99
	global_store_dwordx4 v[110:111], v[82:85], off offset:256 nt
	v_and_b32_e32 v91, 0xffff0000, v168
	v_lshlrev_b32_e32 v92, 16, v169
	v_lshlrev_b32_e32 v82, 16, v166
	v_and_b32_e32 v83, 0xffff0000, v166
	v_and_b32_e32 v93, 0xffff0000, v169
	v_pk_fma_f32 v[78:79], v[78:79], v[86:87], v[82:83]
	v_lshlrev_b32_e32 v84, 16, v167
	v_and_b32_e32 v85, 0xffff0000, v167
	v_pk_fma_f32 v[82:83], v[76:77], v[104:105], v[92:93]
	v_pk_fma_f32 v[76:77], v[74:75], v[102:103], v[90:91]
	v_cvt_pk_bf16_f32 v74, v78, v79
	v_lshl_add_u64 v[78:79], s[60:61], 0, v[194:195]
	v_pk_fma_f32 v[80:81], v[80:81], v[88:89], v[84:85]
	v_lshl_add_u64 v[78:79], v[78:79], 0, v[188:189]
	v_cvt_pk_bf16_f32 v75, v80, v81
	v_cvt_pk_bf16_f32 v76, v76, v77
	v_cvt_pk_bf16_f32 v77, v82, v83
	global_store_dwordx4 v[78:79], v[74:77], off nt
	v_lshlrev_b32_e32 v80, 16, v156
	v_and_b32_e32 v81, 0xffff0000, v156
	v_lshlrev_b32_e32 v74, 16, v154
	v_and_b32_e32 v75, 0xffff0000, v154
	v_lshlrev_b32_e32 v82, 16, v157
	v_and_b32_e32 v83, 0xffff0000, v157
	v_lshlrev_b32_e32 v76, 16, v155
	v_and_b32_e32 v77, 0xffff0000, v155
	v_pk_fma_f32 v[70:71], v[70:71], v[94:95], v[74:75]
	v_pk_fma_f32 v[74:75], v[68:69], v[108:109], v[82:83]
	v_pk_fma_f32 v[68:69], v[66:67], v[106:107], v[80:81]
	v_pk_fma_f32 v[72:73], v[72:73], v[96:97], v[76:77]
	v_cvt_pk_bf16_f32 v66, v70, v71
	v_lshl_add_u64 v[84:85], v[192:193], 0, s[24:25]
	v_cvt_pk_bf16_f32 v67, v72, v73
	v_cvt_pk_bf16_f32 v68, v68, v69
	v_cvt_pk_bf16_f32 v69, v74, v75
	global_store_dwordx4 v[78:79], v[66:69], off offset:256 nt
	v_lshl_add_u64 v[118:119], v[192:193], 0, s[0:1]
	s_mov_b64 s[0:1], 0xa0000
	v_lshl_add_u64 v[66:67], v[190:191], 0, v[84:85]
	global_load_dwordx4 v[76:79], v[66:67], off
	global_load_dwordx4 v[80:83], v[66:67], off offset:256
	v_lshl_add_u64 v[66:67], v[190:191], 0, v[118:119]
	global_load_dwordx4 v[90:93], v[66:67], off
	global_load_dwordx4 v[98:101], v[66:67], off offset:256
	v_lshl_add_u64 v[120:121], v[192:193], 0, s[0:1]
	v_lshl_add_u64 v[66:67], v[190:191], 0, v[120:121]
	global_load_dwordx4 v[110:113], v[66:67], off
	global_load_dwordx4 v[114:117], v[66:67], off offset:256
	v_lshl_add_u64 v[74:75], v[192:193], 0, s[28:29]
	v_lshl_add_u64 v[66:67], v[190:191], 0, v[74:75]
	global_load_dwordx4 v[70:73], v[66:67], off
	s_nop 0
	global_load_dwordx4 v[66:69], v[66:67], off offset:256
	s_waitcnt vmcnt(7)
	v_lshlrev_b32_e32 v122, 16, v76
	v_and_b32_e32 v123, 0xffff0000, v76
	v_lshlrev_b32_e32 v76, 16, v77
	v_and_b32_e32 v77, 0xffff0000, v77
	v_lshlrev_b32_e32 v124, 16, v78
	v_and_b32_e32 v125, 0xffff0000, v78
	v_lshlrev_b32_e32 v78, 16, v79
	v_and_b32_e32 v79, 0xffff0000, v79
	v_pk_fma_f32 v[62:63], v[62:63], v[86:87], v[122:123]
	v_pk_fma_f32 v[64:65], v[64:65], v[88:89], v[76:77]
	v_pk_fma_f32 v[76:77], v[60:61], v[104:105], v[78:79]
	v_pk_fma_f32 v[60:61], v[58:59], v[102:103], v[124:125]
	v_cvt_pk_bf16_f32 v58, v62, v63
	v_lshl_add_u64 v[62:63], s[60:61], 0, v[84:85]
	v_cvt_pk_bf16_f32 v59, v64, v65
	v_cvt_pk_bf16_f32 v60, v60, v61
	v_cvt_pk_bf16_f32 v61, v76, v77
	v_lshl_add_u64 v[62:63], v[62:63], 0, v[188:189]
	global_store_dwordx4 v[62:63], v[58:61], off nt
	s_waitcnt vmcnt(7)
	v_lshlrev_b32_e32 v64, 16, v82
	v_and_b32_e32 v65, 0xffff0000, v82
	v_lshlrev_b32_e32 v58, 16, v80
	v_and_b32_e32 v59, 0xffff0000, v80
	v_lshlrev_b32_e32 v60, 16, v81
	v_and_b32_e32 v61, 0xffff0000, v81
	v_lshlrev_b32_e32 v76, 16, v83
	v_and_b32_e32 v77, 0xffff0000, v83
	v_pk_fma_f32 v[56:57], v[56:57], v[96:97], v[60:61]
	v_pk_fma_f32 v[54:55], v[54:55], v[94:95], v[58:59]
	v_pk_fma_f32 v[58:59], v[52:53], v[108:109], v[76:77]
	v_pk_fma_f32 v[52:53], v[50:51], v[106:107], v[64:65]
	v_cvt_pk_bf16_f32 v50, v54, v55
	v_cvt_pk_bf16_f32 v51, v56, v57
	s_waitcnt vmcnt(6)
; __device__ __forceinline__ u32x4 pack8(const f32x4& a, const f32x4& b) { u32x4 w; w.x = cvt_pk_bf16(a[0], a[1]); w.y = cvt_pk_bf16(a[2], a[3]); w.z = cvt_pk_bf16(b[0], b[1]); w.w = cvt_pk_bf16(b[2], b[3]); return w; }
; #define PG8_BAR __builtin_amdgcn_s_barrier()
;     __device__ __forceinline__ void operator()(const f32x4 (&acc)[2][2][4][2], const Unit& u, int wr, int wc, int fr, int fq) const {
;     ...
;             for (int ai = 0; ai < 2; ++ai) { u32x4 xw[4][2];
; #pragma unroll
;                 for (int m = 0; m < 4; ++m)
; #pragma unroll
;                     for (int bj = 0; bj < 2; ++bj) xw[m][bj] = *(const u32x4*)((const bf16_t*)xin + (size_t)(row0 + ai * HALF + m * 16) * 2048 + col0 + bj * HALF);
; #pragma unroll
;                 for (int m = 0; m < 4; ++m)
; #pragma unroll
;                     for (int bj = 0; bj < 2; ++bj) { const u32x4 w = xw[m][bj];
;                         const f32x4 x0 = (f32x4){__builtin_bit_cast(float, w.x << 16), __builtin_bit_cast(float, w.x & 0xffff0000u), __builtin_bit_cast(float, w.y << 16), __builtin_bit_cast(float, w.y & 0xffff0000u)};
;                         const f32x4 x1 = (f32x4){__builtin_bit_cast(float, w.z << 16), __builtin_bit_cast(float, w.z & 0xffff0000u), __builtin_bit_cast(float, w.w << 16), __builtin_bit_cast(float, w.w & 0xffff0000u)};
;                         *(u32x4*)(xout + (size_t)(row0 + ai * HALF + m * 16) * 2048 + col0 + bj * HALF) = pack8(x0 + gv[bj][0] * acc[ai][bj][m][0], x1 + gv[bj][1] * acc[ai][bj][m][1]); }
;                 asm volatile("" ::: "memory"); }
; template <class Epi, class Sched, bool ALIGN_EPI = true, bool SP2 = true, bool FULLLINE = false, bool NOSTAGE = false, bool FP8 = false>
; __device__ __forceinline__ void gemm_phase(PG8_LAS unsigned char* lds, const Gemm g, const Sched& S, const Epi& E) {
;     ...
;         if (!has_next) break;
; #pragma unroll
;         for (int a = 0; a < 2; ++a)
; #pragma unroll
;             for (int b = 0; b < 2; ++b)
; #pragma unroll
;                 for (int m = 0; m < 4; ++m)
; #pragma unroll
;                     for (int n = 0; n < 2; ++n) acc[a][b][m][n] = (f32x4){0.f, 0.f, 0.f, 0.f};
;         cur = nxt; cA = nA; cB = nB; ++ui;
;         if constexpr (ALIGN_EPI) { if (wr == 1) PG8_BAR; }
	v_lshlrev_b32_e32 v54, 16, v92
	v_cvt_pk_bf16_f32 v52, v52, v53
	v_cvt_pk_bf16_f32 v53, v58, v59
	global_store_dwordx4 v[62:63], v[50:53], off offset:256 nt
	v_and_b32_e32 v55, 0xffff0000, v92
	v_lshlrev_b32_e32 v56, 16, v93
	v_lshlrev_b32_e32 v50, 16, v90
	v_and_b32_e32 v51, 0xffff0000, v90
	v_and_b32_e32 v57, 0xffff0000, v93
	v_pk_fma_f32 v[46:47], v[46:47], v[86:87], v[50:51]
	v_lshlrev_b32_e32 v52, 16, v91
	v_and_b32_e32 v53, 0xffff0000, v91
	v_pk_fma_f32 v[50:51], v[44:45], v[104:105], v[56:57]
	v_pk_fma_f32 v[44:45], v[42:43], v[102:103], v[54:55]
	v_cvt_pk_bf16_f32 v42, v46, v47
	v_lshl_add_u64 v[46:47], s[60:61], 0, v[118:119]
	v_pk_fma_f32 v[48:49], v[48:49], v[88:89], v[52:53]
	v_lshl_add_u64 v[46:47], v[46:47], 0, v[188:189]
	v_cvt_pk_bf16_f32 v43, v48, v49
	v_cvt_pk_bf16_f32 v44, v44, v45
	v_cvt_pk_bf16_f32 v45, v50, v51
	global_store_dwordx4 v[46:47], v[42:45], off nt
	s_waitcnt vmcnt(7)
	v_lshlrev_b32_e32 v48, 16, v100
	v_and_b32_e32 v49, 0xffff0000, v100
	v_lshlrev_b32_e32 v42, 16, v98
	v_and_b32_e32 v43, 0xffff0000, v98
	v_lshlrev_b32_e32 v44, 16, v99
	v_and_b32_e32 v45, 0xffff0000, v99
	v_lshlrev_b32_e32 v50, 16, v101
	v_and_b32_e32 v51, 0xffff0000, v101
	v_pk_fma_f32 v[40:41], v[40:41], v[96:97], v[44:45]
	v_pk_fma_f32 v[38:39], v[38:39], v[94:95], v[42:43]
	v_pk_fma_f32 v[42:43], v[36:37], v[108:109], v[50:51]
	v_pk_fma_f32 v[36:37], v[34:35], v[106:107], v[48:49]
	v_cvt_pk_bf16_f32 v34, v38, v39
	v_cvt_pk_bf16_f32 v35, v40, v41
	s_waitcnt vmcnt(6)
	v_lshlrev_b32_e32 v38, 16, v112
	v_cvt_pk_bf16_f32 v36, v36, v37
	v_cvt_pk_bf16_f32 v37, v42, v43
	global_store_dwordx4 v[46:47], v[34:37], off offset:256 nt
	v_and_b32_e32 v39, 0xffff0000, v112
	v_lshlrev_b32_e32 v40, 16, v113
	v_lshlrev_b32_e32 v34, 16, v110
	v_and_b32_e32 v35, 0xffff0000, v110
	v_and_b32_e32 v41, 0xffff0000, v113
	v_pk_fma_f32 v[30:31], v[30:31], v[86:87], v[34:35]
	v_lshlrev_b32_e32 v36, 16, v111
	v_and_b32_e32 v37, 0xffff0000, v111
	v_pk_fma_f32 v[34:35], v[28:29], v[104:105], v[40:41]
	v_pk_fma_f32 v[28:29], v[26:27], v[102:103], v[38:39]
	v_cvt_pk_bf16_f32 v26, v30, v31
	v_lshl_add_u64 v[30:31], s[60:61], 0, v[120:121]
	v_pk_fma_f32 v[32:33], v[32:33], v[88:89], v[36:37]
	v_lshl_add_u64 v[30:31], v[30:31], 0, v[188:189]
	v_cvt_pk_bf16_f32 v27, v32, v33
	v_cvt_pk_bf16_f32 v28, v28, v29
	v_cvt_pk_bf16_f32 v29, v34, v35
	global_store_dwordx4 v[30:31], v[26:29], off nt
	s_waitcnt vmcnt(7)
	v_lshlrev_b32_e32 v32, 16, v116
	v_and_b32_e32 v33, 0xffff0000, v116
	v_lshlrev_b32_e32 v26, 16, v114
	v_and_b32_e32 v27, 0xffff0000, v114
	v_lshlrev_b32_e32 v28, 16, v115
	v_and_b32_e32 v29, 0xffff0000, v115
	v_lshlrev_b32_e32 v34, 16, v117
	v_and_b32_e32 v35, 0xffff0000, v117
	v_pk_fma_f32 v[24:25], v[24:25], v[96:97], v[28:29]
	v_pk_fma_f32 v[22:23], v[22:23], v[94:95], v[26:27]
	v_pk_fma_f32 v[26:27], v[20:21], v[108:109], v[34:35]
	v_pk_fma_f32 v[20:21], v[18:19], v[106:107], v[32:33]
	v_cvt_pk_bf16_f32 v18, v22, v23
	v_cvt_pk_bf16_f32 v19, v24, v25
	s_waitcnt vmcnt(6)
	v_lshlrev_b32_e32 v22, 16, v72
	v_cvt_pk_bf16_f32 v20, v20, v21
	v_cvt_pk_bf16_f32 v21, v26, v27
	global_store_dwordx4 v[30:31], v[18:21], off offset:256 nt
	v_and_b32_e32 v23, 0xffff0000, v72
	v_lshlrev_b32_e32 v24, 16, v73
	v_lshlrev_b32_e32 v18, 16, v70
	v_and_b32_e32 v19, 0xffff0000, v70
	v_and_b32_e32 v25, 0xffff0000, v73
	v_pk_fma_f32 v[14:15], v[14:15], v[86:87], v[18:19]
	v_lshlrev_b32_e32 v20, 16, v71
	v_and_b32_e32 v21, 0xffff0000, v71
	v_pk_fma_f32 v[18:19], v[12:13], v[104:105], v[24:25]
	v_pk_fma_f32 v[12:13], v[10:11], v[102:103], v[22:23]
	v_cvt_pk_bf16_f32 v10, v14, v15
	v_lshl_add_u64 v[14:15], s[60:61], 0, v[74:75]
	v_pk_fma_f32 v[16:17], v[16:17], v[88:89], v[20:21]
	v_lshl_add_u64 v[14:15], v[14:15], 0, v[188:189]
	v_cvt_pk_bf16_f32 v11, v16, v17
	v_cvt_pk_bf16_f32 v12, v12, v13
	v_cvt_pk_bf16_f32 v13, v18, v19
	global_store_dwordx4 v[14:15], v[10:13], off nt
	s_waitcnt vmcnt(7)
	v_lshlrev_b32_e32 v16, 16, v68
	v_and_b32_e32 v17, 0xffff0000, v68
	v_lshlrev_b32_e32 v10, 16, v66
	v_and_b32_e32 v11, 0xffff0000, v66
	v_lshlrev_b32_e32 v18, 16, v69
	v_and_b32_e32 v19, 0xffff0000, v69
	v_lshlrev_b32_e32 v12, 16, v67
	v_and_b32_e32 v13, 0xffff0000, v67
	v_pk_fma_f32 v[6:7], v[6:7], v[94:95], v[10:11]
	v_pk_fma_f32 v[10:11], v[4:5], v[108:109], v[18:19]
	v_pk_fma_f32 v[4:5], v[2:3], v[106:107], v[16:17]
	v_pk_fma_f32 v[8:9], v[8:9], v[96:97], v[12:13]
	v_cvt_pk_bf16_f32 v2, v6, v7
	s_nop 0
	v_cvt_pk_bf16_f32 v3, v8, v9
	v_cvt_pk_bf16_f32 v4, v4, v5
	v_cvt_pk_bf16_f32 v5, v10, v11
	global_store_dwordx4 v[14:15], v[2:5], off offset:256 nt
	s_cbranch_vccnz .LBB0_2672
	s_and_b64 vcc, exec, s[6:7]
	s_cbranch_vccnz .LBB0_2671
	s_barrier
	s_branch .LBB0_2671

; __device__ __forceinline__ u32x4 pack8(const f32x4& a, const f32x4& b) { u32x4 w; w.x = cvt_pk_bf16(a[0], a[1]); w.y = cvt_pk_bf16(a[2], a[3]); w.z = cvt_pk_bf16(b[0], b[1]); w.w = cvt_pk_bf16(b[2], b[3]); return w; }
;     __device__ __forceinline__ void operator()(const f32x4 (&acc)[2][2][4][2], const Unit& u, int wr, int wc, int fr, int fq) const {
;         const int row0 = u.pm * BM + wr * 64 + fr, col0 = u.pn * BM + wc * 32 + 8 * fq;
;         const float* gp = gate + (size_t)(u.pm >> 3) * 12288 + col0;
;         f32x4 gv[2][2];
; #pragma unroll
;         for (int bj = 0; bj < 2; ++bj)
; #pragma unroll
;             for (int n = 0; n < 2; ++n) { gv[bj][n] = *(const f32x4*)(gp + bj * HALF + n * 4); if (cscale) gv[bj][n] = gv[bj][n] * *(const f32x4*)(cscale + col0 + bj * HALF + n * 4); }
;     ...
;             for (int ai = 0; ai < 2; ++ai) { u32x4 xw[4][2];
; #pragma unroll
;                 for (int m = 0; m < 4; ++m)
; #pragma unroll
;                     for (int bj = 0; bj < 2; ++bj) xw[m][bj] = *(const u32x4*)((const bf16_t*)xin + (size_t)(row0 + ai * HALF + m * 16) * 2048 + col0 + bj * HALF);
; #pragma unroll
;                 for (int m = 0; m < 4; ++m)
; #pragma unroll
;                     for (int bj = 0; bj < 2; ++bj) { const u32x4 w = xw[m][bj];
;                         const f32x4 x0 = (f32x4){__builtin_bit_cast(float, w.x << 16), __builtin_bit_cast(float, w.x & 0xffff0000u), __builtin_bit_cast(float, w.y << 16), __builtin_bit_cast(float, w.y & 0xffff0000u)};
;                         const f32x4 x1 = (f32x4){__builtin_bit_cast(float, w.z << 16), __builtin_bit_cast(float, w.z & 0xffff0000u), __builtin_bit_cast(float, w.w << 16), __builtin_bit_cast(float, w.w & 0xffff0000u)};
;                         *(u32x4*)(xout + (size_t)(row0 + ai * HALF + m * 16) * 2048 + col0 + bj * HALF) = pack8(x0 + gv[bj][0] * acc[ai][bj][m][0], x1 + gv[bj][1] * acc[ai][bj][m][1]); }
.LBB0_2968:
	v_mov_b32_e32 v84, v252
	s_lshl_b32 s0, s80, 8
	v_ashrrev_i32_e32 v82, 1, v84
	s_or_b32 s0, s0, s70
	v_and_b32_e32 v82, -8, v82
	v_add_u32_e32 v82, s0, v82
	s_ashr_i32 s0, s79, 3
	s_mul_hi_i32 s1, s0, 0xc000
	s_mul_i32 s0, s0, 0xc000
	s_add_u32 s0, s67, s0
	s_addc_u32 s1, s68, s1
	s_lshl_b32 s33, s79, 8
	s_add_i32 s33, s33, s69
	v_ashrrev_i32_e32 v83, 31, v82
	v_and_or_b32 v146, v84, 15, s33
	v_lshlrev_b64 v[160:161], 1, v[82:83]
	v_ashrrev_i32_e32 v147, 31, v146
	v_lshl_add_u64 v[162:163], s[60:61], 0, v[160:161]
	v_lshlrev_b64 v[164:165], 12, v[146:147]
	v_or_b32_e32 v148, 16, v146
	v_lshl_add_u64 v[84:85], v[162:163], 0, v[164:165]
	v_ashrrev_i32_e32 v149, 31, v148
	global_load_dwordx4 v[172:175], v[84:85], off
	global_load_dwordx4 v[176:179], v[84:85], off offset:256
	v_lshl_add_u64 v[86:87], v[82:83], 2, s[0:1]
	v_lshlrev_b64 v[200:201], 12, v[148:149]
	global_load_dwordx4 v[102:105], v[86:87], off
	global_load_dwordx4 v[94:97], v[86:87], off offset:16
	global_load_dwordx4 v[82:85], v[86:87], off offset:528
	s_nop 0
	global_load_dwordx4 v[86:89], v[86:87], off offset:512
	v_lshl_add_u64 v[148:149], v[162:163], 0, v[200:201]
	global_load_dwordx4 v[180:183], v[148:149], off
	global_load_dwordx4 v[184:187], v[148:149], off offset:256
	v_or_b32_e32 v148, 32, v146
	v_ashrrev_i32_e32 v149, 31, v148
	v_lshlrev_b64 v[202:203], 12, v[148:149]
	v_lshl_add_u64 v[148:149], v[162:163], 0, v[202:203]
	global_load_dwordx4 v[188:191], v[148:149], off
	v_or_b32_e32 v146, 48, v146
	v_ashrrev_i32_e32 v147, 31, v146
	v_lshlrev_b64 v[166:167], 12, v[146:147]
	v_lshl_add_u64 v[146:147], s[60:61], 0, v[164:165]
	v_lshl_add_u64 v[204:205], v[162:163], 0, v[166:167]
	v_lshl_add_u64 v[206:207], v[146:147], 0, v[160:161]
	global_load_dwordx4 v[192:195], v[148:149], off offset:256
	global_load_dwordx4 v[196:199], v[204:205], off
	s_nop 0
	global_load_dwordx4 v[146:149], v[204:205], off offset:256
	s_mov_b64 s[0:1], 0x80000
	s_and_b64 vcc, exec, s[8:9]
	s_mov_b64 s[8:9], -1
	s_waitcnt vmcnt(0)
	v_lshlrev_b32_e32 v204, 16, v172
	v_and_b32_e32 v205, 0xffff0000, v172
	v_lshlrev_b32_e32 v172, 16, v173
	v_and_b32_e32 v173, 0xffff0000, v173
	v_lshlrev_b32_e32 v208, 16, v174
	v_and_b32_e32 v209, 0xffff0000, v174
	v_lshlrev_b32_e32 v174, 16, v175
	v_and_b32_e32 v175, 0xffff0000, v175
	v_lshlrev_b32_e32 v210, 16, v176
	v_and_b32_e32 v211, 0xffff0000, v176
	v_lshlrev_b32_e32 v176, 16, v177
	v_and_b32_e32 v177, 0xffff0000, v177
	v_lshlrev_b32_e32 v212, 16, v178
	v_and_b32_e32 v213, 0xffff0000, v178
	v_lshlrev_b32_e32 v178, 16, v179
	v_and_b32_e32 v179, 0xffff0000, v179
	v_pk_fma_f32 v[140:141], v[140:141], v[104:105], v[172:173]
	v_pk_fma_f32 v[136:137], v[136:137], v[96:97], v[174:175]
	v_pk_fma_f32 v[144:145], v[144:145], v[88:89], v[176:177]
	v_pk_fma_f32 v[172:173], v[132:133], v[84:85], v[178:179]
	v_lshlrev_b32_e32 v176, 16, v180
	v_and_b32_e32 v177, 0xffff0000, v180
	v_lshlrev_b32_e32 v178, 16, v181
	v_and_b32_e32 v179, 0xffff0000, v181
	v_lshlrev_b32_e32 v180, 16, v182
	v_and_b32_e32 v181, 0xffff0000, v182
	v_pk_fma_f32 v[138:139], v[138:139], v[102:103], v[204:205]
	v_pk_fma_f32 v[134:135], v[134:135], v[94:95], v[208:209]
	v_pk_fma_f32 v[142:143], v[142:143], v[86:87], v[210:211]
	v_pk_fma_f32 v[174:175], v[130:131], v[82:83], v[212:213]
	v_lshlrev_b32_e32 v182, 16, v183
	v_and_b32_e32 v183, 0xffff0000, v183
	v_cvt_pk_bf16_f32 v130, v138, v139
	v_cvt_pk_bf16_f32 v131, v140, v141
	v_cvt_pk_bf16_f32 v132, v134, v135
	v_cvt_pk_bf16_f32 v133, v136, v137
	v_pk_fma_f32 v[126:127], v[126:127], v[102:103], v[176:177]
	v_pk_fma_f32 v[136:137], v[122:123], v[94:95], v[180:181]
	global_store_dwordx4 v[206:207], v[130:133], off nt
	v_cvt_pk_bf16_f32 v122, v142, v143
	v_pk_fma_f32 v[134:135], v[124:125], v[96:97], v[182:183]
	v_cvt_pk_bf16_f32 v123, v144, v145
	v_cvt_pk_bf16_f32 v124, v174, v175
	v_cvt_pk_bf16_f32 v125, v172, v173
	global_store_dwordx4 v[206:207], v[122:125], off offset:256 nt
	v_pk_fma_f32 v[128:129], v[128:129], v[104:105], v[178:179]
	v_lshlrev_b32_e32 v130, 16, v187
	v_cvt_pk_bf16_f32 v122, v126, v127
	v_lshl_add_u64 v[126:127], s[60:61], 0, v[200:201]
	v_cvt_pk_bf16_f32 v123, v128, v129
	v_cvt_pk_bf16_f32 v124, v136, v137
	v_cvt_pk_bf16_f32 v125, v134, v135
	v_lshl_add_u64 v[126:127], v[126:127], 0, v[160:161]
	global_store_dwordx4 v[126:127], v[122:125], off nt
	v_lshlrev_b32_e32 v128, 16, v186
	v_and_b32_e32 v129, 0xffff0000, v186
	v_lshlrev_b32_e32 v122, 16, v184
	v_and_b32_e32 v123, 0xffff0000, v184
	v_lshlrev_b32_e32 v124, 16, v185
	v_and_b32_e32 v125, 0xffff0000, v185
	v_and_b32_e32 v131, 0xffff0000, v187
	v_pk_fma_f32 v[120:121], v[120:121], v[88:89], v[124:125]
	v_pk_fma_f32 v[118:119], v[118:119], v[86:87], v[122:123]
	v_pk_fma_f32 v[122:123], v[116:117], v[84:85], v[130:131]
	v_pk_fma_f32 v[116:117], v[114:115], v[82:83], v[128:129]
	v_cvt_pk_bf16_f32 v114, v118, v119
	v_cvt_pk_bf16_f32 v115, v120, v121
	v_lshlrev_b32_e32 v118, 16, v190
	v_cvt_pk_bf16_f32 v116, v116, v117
	v_cvt_pk_bf16_f32 v117, v122, v123
	global_store_dwordx4 v[126:127], v[114:117], off offset:256 nt
	v_and_b32_e32 v119, 0xffff0000, v190
	v_lshlrev_b32_e32 v120, 16, v191
	v_lshlrev_b32_e32 v114, 16, v188
	v_and_b32_e32 v115, 0xffff0000, v188
	v_and_b32_e32 v121, 0xffff0000, v191
	v_pk_fma_f32 v[110:111], v[110:111], v[102:103], v[114:115]
	v_lshlrev_b32_e32 v116, 16, v189
	v_and_b32_e32 v117, 0xffff0000, v189
	v_pk_fma_f32 v[114:115], v[108:109], v[96:97], v[120:121]
	v_pk_fma_f32 v[108:109], v[106:107], v[94:95], v[118:119]
	v_cvt_pk_bf16_f32 v106, v110, v111
	v_lshl_add_u64 v[110:111], s[60:61], 0, v[202:203]
	v_pk_fma_f32 v[112:113], v[112:113], v[104:105], v[116:117]
; __device__ __forceinline__ u32x4 pack8(const f32x4& a, const f32x4& b) { u32x4 w; w.x = cvt_pk_bf16(a[0], a[1]); w.y = cvt_pk_bf16(a[2], a[3]); w.z = cvt_pk_bf16(b[0], b[1]); w.w = cvt_pk_bf16(b[2], b[3]); return w; }
;     __device__ __forceinline__ void operator()(const f32x4 (&acc)[2][2][4][2], const Unit& u, int wr, int wc, int fr, int fq) const {
;     ...
;             for (int ai = 0; ai < 2; ++ai) { u32x4 xw[4][2];
; #pragma unroll
;                 for (int m = 0; m < 4; ++m)
; #pragma unroll
;                     for (int bj = 0; bj < 2; ++bj) xw[m][bj] = *(const u32x4*)((const bf16_t*)xin + (size_t)(row0 + ai * HALF + m * 16) * 2048 + col0 + bj * HALF);
; #pragma unroll
;                 for (int m = 0; m < 4; ++m)
; #pragma unroll
;                     for (int bj = 0; bj < 2; ++bj) { const u32x4 w = xw[m][bj];
;                         const f32x4 x0 = (f32x4){__builtin_bit_cast(float, w.x << 16), __builtin_bit_cast(float, w.x & 0xffff0000u), __builtin_bit_cast(float, w.y << 16), __builtin_bit_cast(float, w.y & 0xffff0000u)};
;                         const f32x4 x1 = (f32x4){__builtin_bit_cast(float, w.z << 16), __builtin_bit_cast(float, w.z & 0xffff0000u), __builtin_bit_cast(float, w.w << 16), __builtin_bit_cast(float, w.w & 0xffff0000u)};
;                         *(u32x4*)(xout + (size_t)(row0 + ai * HALF + m * 16) * 2048 + col0 + bj * HALF) = pack8(x0 + gv[bj][0] * acc[ai][bj][m][0], x1 + gv[bj][1] * acc[ai][bj][m][1]); }
	v_lshl_add_u64 v[110:111], v[110:111], 0, v[160:161]
	v_cvt_pk_bf16_f32 v107, v112, v113
	v_cvt_pk_bf16_f32 v108, v108, v109
	v_cvt_pk_bf16_f32 v109, v114, v115
	global_store_dwordx4 v[110:111], v[106:109], off nt
	v_lshlrev_b32_e32 v112, 16, v194
	v_and_b32_e32 v113, 0xffff0000, v194
	v_lshlrev_b32_e32 v106, 16, v192
	v_and_b32_e32 v107, 0xffff0000, v192
	v_lshlrev_b32_e32 v108, 16, v193
	v_and_b32_e32 v109, 0xffff0000, v193
	v_lshlrev_b32_e32 v114, 16, v195
	v_and_b32_e32 v115, 0xffff0000, v195
	v_pk_fma_f32 v[100:101], v[100:101], v[88:89], v[108:109]
	v_pk_fma_f32 v[98:99], v[98:99], v[86:87], v[106:107]
	v_pk_fma_f32 v[106:107], v[92:93], v[84:85], v[114:115]
	v_pk_fma_f32 v[92:93], v[90:91], v[82:83], v[112:113]
	v_cvt_pk_bf16_f32 v90, v98, v99
	v_cvt_pk_bf16_f32 v91, v100, v101
	v_lshlrev_b32_e32 v98, 16, v198
	v_cvt_pk_bf16_f32 v92, v92, v93
	v_cvt_pk_bf16_f32 v93, v106, v107
	global_store_dwordx4 v[110:111], v[90:93], off offset:256 nt
	v_and_b32_e32 v99, 0xffff0000, v198
	v_lshlrev_b32_e32 v100, 16, v199
	v_lshlrev_b32_e32 v90, 16, v196
	v_and_b32_e32 v91, 0xffff0000, v196
	v_and_b32_e32 v101, 0xffff0000, v199
	v_pk_fma_f32 v[78:79], v[78:79], v[102:103], v[90:91]
	v_lshlrev_b32_e32 v92, 16, v197
	v_and_b32_e32 v93, 0xffff0000, v197
	v_pk_fma_f32 v[90:91], v[76:77], v[96:97], v[100:101]
	v_pk_fma_f32 v[76:77], v[74:75], v[94:95], v[98:99]
	v_cvt_pk_bf16_f32 v74, v78, v79
	v_lshl_add_u64 v[78:79], s[60:61], 0, v[166:167]
	v_pk_fma_f32 v[80:81], v[80:81], v[104:105], v[92:93]
	v_lshl_add_u64 v[78:79], v[78:79], 0, v[160:161]
	v_cvt_pk_bf16_f32 v75, v80, v81
	v_cvt_pk_bf16_f32 v76, v76, v77
	v_cvt_pk_bf16_f32 v77, v90, v91
	global_store_dwordx4 v[78:79], v[74:77], off nt
	v_lshlrev_b32_e32 v80, 16, v148
	v_and_b32_e32 v81, 0xffff0000, v148
	v_lshlrev_b32_e32 v74, 16, v146
	v_and_b32_e32 v75, 0xffff0000, v146
	v_lshlrev_b32_e32 v90, 16, v149
	v_and_b32_e32 v91, 0xffff0000, v149
	v_lshlrev_b32_e32 v76, 16, v147
	v_and_b32_e32 v77, 0xffff0000, v147
	v_pk_fma_f32 v[70:71], v[70:71], v[86:87], v[74:75]
	v_pk_fma_f32 v[74:75], v[68:69], v[84:85], v[90:91]
	v_pk_fma_f32 v[68:69], v[66:67], v[82:83], v[80:81]
	v_pk_fma_f32 v[72:73], v[72:73], v[88:89], v[76:77]
	v_cvt_pk_bf16_f32 v66, v70, v71
	v_lshl_add_u64 v[80:81], v[164:165], 0, s[0:1]
	v_cvt_pk_bf16_f32 v67, v72, v73
	v_cvt_pk_bf16_f32 v68, v68, v69
	v_cvt_pk_bf16_f32 v69, v74, v75
	global_store_dwordx4 v[78:79], v[66:69], off offset:256 nt
	s_mov_b64 s[0:1], 0x90000
	v_lshl_add_u64 v[118:119], v[164:165], 0, s[0:1]
	v_lshl_add_u64 v[66:67], v[162:163], 0, v[80:81]
	global_load_dwordx4 v[76:79], v[66:67], off
	global_load_dwordx4 v[90:93], v[66:67], off offset:256
	v_lshl_add_u64 v[66:67], v[162:163], 0, v[118:119]
	global_load_dwordx4 v[98:101], v[66:67], off
	global_load_dwordx4 v[106:109], v[66:67], off offset:256
	s_mov_b64 s[0:1], 0xa0000
	v_lshl_add_u64 v[120:121], v[164:165], 0, s[0:1]
	v_lshl_add_u64 v[66:67], v[162:163], 0, v[120:121]
	global_load_dwordx4 v[110:113], v[66:67], off
	global_load_dwordx4 v[114:117], v[66:67], off offset:256
	v_lshl_add_u64 v[74:75], v[164:165], 0, s[30:31]
	v_lshl_add_u64 v[66:67], v[162:163], 0, v[74:75]
	global_load_dwordx4 v[70:73], v[66:67], off
	s_nop 0
	global_load_dwordx4 v[66:69], v[66:67], off offset:256
	s_waitcnt vmcnt(7)
	v_lshlrev_b32_e32 v122, 16, v76
	v_and_b32_e32 v123, 0xffff0000, v76
	v_lshlrev_b32_e32 v76, 16, v77
	v_and_b32_e32 v77, 0xffff0000, v77
	v_lshlrev_b32_e32 v124, 16, v78
	v_and_b32_e32 v125, 0xffff0000, v78
	v_lshlrev_b32_e32 v78, 16, v79
	v_and_b32_e32 v79, 0xffff0000, v79
	v_pk_fma_f32 v[62:63], v[62:63], v[102:103], v[122:123]
	v_pk_fma_f32 v[64:65], v[64:65], v[104:105], v[76:77]
	v_pk_fma_f32 v[76:77], v[60:61], v[96:97], v[78:79]
	v_pk_fma_f32 v[60:61], v[58:59], v[94:95], v[124:125]
	v_cvt_pk_bf16_f32 v58, v62, v63
	v_lshl_add_u64 v[62:63], s[60:61], 0, v[80:81]
	v_cvt_pk_bf16_f32 v59, v64, v65
	v_cvt_pk_bf16_f32 v60, v60, v61
	v_cvt_pk_bf16_f32 v61, v76, v77
	v_lshl_add_u64 v[62:63], v[62:63], 0, v[160:161]
	global_store_dwordx4 v[62:63], v[58:61], off nt
	s_waitcnt vmcnt(7)
	v_lshlrev_b32_e32 v64, 16, v92
	v_and_b32_e32 v65, 0xffff0000, v92
	v_lshlrev_b32_e32 v58, 16, v90
	v_and_b32_e32 v59, 0xffff0000, v90
	v_lshlrev_b32_e32 v60, 16, v91
	v_and_b32_e32 v61, 0xffff0000, v91
	v_lshlrev_b32_e32 v76, 16, v93
	v_and_b32_e32 v77, 0xffff0000, v93
	v_pk_fma_f32 v[56:57], v[56:57], v[88:89], v[60:61]
	v_pk_fma_f32 v[54:55], v[54:55], v[86:87], v[58:59]
	v_pk_fma_f32 v[58:59], v[52:53], v[84:85], v[76:77]
	v_pk_fma_f32 v[52:53], v[50:51], v[82:83], v[64:65]
	v_cvt_pk_bf16_f32 v50, v54, v55
	v_cvt_pk_bf16_f32 v51, v56, v57
	s_waitcnt vmcnt(6)
; __device__ __forceinline__ u32x4 pack8(const f32x4& a, const f32x4& b) { u32x4 w; w.x = cvt_pk_bf16(a[0], a[1]); w.y = cvt_pk_bf16(a[2], a[3]); w.z = cvt_pk_bf16(b[0], b[1]); w.w = cvt_pk_bf16(b[2], b[3]); return w; }
; #define PG8_BAR __builtin_amdgcn_s_barrier()
;     __device__ __forceinline__ void operator()(const f32x4 (&acc)[2][2][4][2], const Unit& u, int wr, int wc, int fr, int fq) const {
;     ...
;             for (int ai = 0; ai < 2; ++ai) { u32x4 xw[4][2];
; #pragma unroll
;                 for (int m = 0; m < 4; ++m)
; #pragma unroll
;                     for (int bj = 0; bj < 2; ++bj) xw[m][bj] = *(const u32x4*)((const bf16_t*)xin + (size_t)(row0 + ai * HALF + m * 16) * 2048 + col0 + bj * HALF);
; #pragma unroll
;                 for (int m = 0; m < 4; ++m)
; #pragma unroll
;                     for (int bj = 0; bj < 2; ++bj) { const u32x4 w = xw[m][bj];
;                         const f32x4 x0 = (f32x4){__builtin_bit_cast(float, w.x << 16), __builtin_bit_cast(float, w.x & 0xffff0000u), __builtin_bit_cast(float, w.y << 16), __builtin_bit_cast(float, w.y & 0xffff0000u)};
;                         const f32x4 x1 = (f32x4){__builtin_bit_cast(float, w.z << 16), __builtin_bit_cast(float, w.z & 0xffff0000u), __builtin_bit_cast(float, w.w << 16), __builtin_bit_cast(float, w.w & 0xffff0000u)};
;                         *(u32x4*)(xout + (size_t)(row0 + ai * HALF + m * 16) * 2048 + col0 + bj * HALF) = pack8(x0 + gv[bj][0] * acc[ai][bj][m][0], x1 + gv[bj][1] * acc[ai][bj][m][1]); }
;                 asm volatile("" ::: "memory"); }
; template <class Epi, class Sched, bool ALIGN_EPI = true, bool SP2 = true, bool FULLLINE = false, bool NOSTAGE = false, bool FP8 = false>
; __device__ __forceinline__ void gemm_phase(PG8_LAS unsigned char* lds, const Gemm g, const Sched& S, const Epi& E) {
;     ...
;         if (!has_next) break;
; #pragma unroll
;         for (int a = 0; a < 2; ++a)
; #pragma unroll
;             for (int b = 0; b < 2; ++b)
; #pragma unroll
;                 for (int m = 0; m < 4; ++m)
; #pragma unroll
;                     for (int n = 0; n < 2; ++n) acc[a][b][m][n] = (f32x4){0.f, 0.f, 0.f, 0.f};
;         cur = nxt; cA = nA; cB = nB; ++ui;
;         if constexpr (ALIGN_EPI) { if (wr == 1) PG8_BAR; }
	v_lshlrev_b32_e32 v54, 16, v100
	v_cvt_pk_bf16_f32 v52, v52, v53
	v_cvt_pk_bf16_f32 v53, v58, v59
	global_store_dwordx4 v[62:63], v[50:53], off offset:256 nt
	v_and_b32_e32 v55, 0xffff0000, v100
	v_lshlrev_b32_e32 v56, 16, v101
	v_lshlrev_b32_e32 v50, 16, v98
	v_and_b32_e32 v51, 0xffff0000, v98
	v_and_b32_e32 v57, 0xffff0000, v101
	v_pk_fma_f32 v[46:47], v[46:47], v[102:103], v[50:51]
	v_lshlrev_b32_e32 v52, 16, v99
	v_and_b32_e32 v53, 0xffff0000, v99
	v_pk_fma_f32 v[50:51], v[44:45], v[96:97], v[56:57]
	v_pk_fma_f32 v[44:45], v[42:43], v[94:95], v[54:55]
	v_cvt_pk_bf16_f32 v42, v46, v47
	v_lshl_add_u64 v[46:47], s[60:61], 0, v[118:119]
	v_pk_fma_f32 v[48:49], v[48:49], v[104:105], v[52:53]
	v_lshl_add_u64 v[46:47], v[46:47], 0, v[160:161]
	v_cvt_pk_bf16_f32 v43, v48, v49
	v_cvt_pk_bf16_f32 v44, v44, v45
	v_cvt_pk_bf16_f32 v45, v50, v51
	global_store_dwordx4 v[46:47], v[42:45], off nt
	s_waitcnt vmcnt(7)
	v_lshlrev_b32_e32 v48, 16, v108
	v_and_b32_e32 v49, 0xffff0000, v108
	v_lshlrev_b32_e32 v42, 16, v106
	v_and_b32_e32 v43, 0xffff0000, v106
	v_lshlrev_b32_e32 v44, 16, v107
	v_and_b32_e32 v45, 0xffff0000, v107
	v_lshlrev_b32_e32 v50, 16, v109
	v_and_b32_e32 v51, 0xffff0000, v109
	v_pk_fma_f32 v[40:41], v[40:41], v[88:89], v[44:45]
	v_pk_fma_f32 v[38:39], v[38:39], v[86:87], v[42:43]
	v_pk_fma_f32 v[42:43], v[36:37], v[84:85], v[50:51]
	v_pk_fma_f32 v[36:37], v[34:35], v[82:83], v[48:49]
	v_cvt_pk_bf16_f32 v34, v38, v39
	v_cvt_pk_bf16_f32 v35, v40, v41
	s_waitcnt vmcnt(6)
	v_lshlrev_b32_e32 v38, 16, v112
	v_cvt_pk_bf16_f32 v36, v36, v37
	v_cvt_pk_bf16_f32 v37, v42, v43
	global_store_dwordx4 v[46:47], v[34:37], off offset:256 nt
	v_and_b32_e32 v39, 0xffff0000, v112
	v_lshlrev_b32_e32 v40, 16, v113
	v_lshlrev_b32_e32 v34, 16, v110
	v_and_b32_e32 v35, 0xffff0000, v110
	v_and_b32_e32 v41, 0xffff0000, v113
	v_pk_fma_f32 v[30:31], v[30:31], v[102:103], v[34:35]
	v_lshlrev_b32_e32 v36, 16, v111
	v_and_b32_e32 v37, 0xffff0000, v111
	v_pk_fma_f32 v[34:35], v[28:29], v[96:97], v[40:41]
	v_pk_fma_f32 v[28:29], v[26:27], v[94:95], v[38:39]
	v_cvt_pk_bf16_f32 v26, v30, v31
	v_lshl_add_u64 v[30:31], s[60:61], 0, v[120:121]
	v_pk_fma_f32 v[32:33], v[32:33], v[104:105], v[36:37]
	v_lshl_add_u64 v[30:31], v[30:31], 0, v[160:161]
	v_cvt_pk_bf16_f32 v27, v32, v33
	v_cvt_pk_bf16_f32 v28, v28, v29
	v_cvt_pk_bf16_f32 v29, v34, v35
	global_store_dwordx4 v[30:31], v[26:29], off nt
	s_waitcnt vmcnt(7)
	v_lshlrev_b32_e32 v32, 16, v116
	v_and_b32_e32 v33, 0xffff0000, v116
	v_lshlrev_b32_e32 v26, 16, v114
	v_and_b32_e32 v27, 0xffff0000, v114
	v_lshlrev_b32_e32 v28, 16, v115
	v_and_b32_e32 v29, 0xffff0000, v115
	v_lshlrev_b32_e32 v34, 16, v117
	v_and_b32_e32 v35, 0xffff0000, v117
	v_pk_fma_f32 v[24:25], v[24:25], v[88:89], v[28:29]
	v_pk_fma_f32 v[22:23], v[22:23], v[86:87], v[26:27]
	v_pk_fma_f32 v[26:27], v[20:21], v[84:85], v[34:35]
	v_pk_fma_f32 v[20:21], v[18:19], v[82:83], v[32:33]
	v_cvt_pk_bf16_f32 v18, v22, v23
	v_cvt_pk_bf16_f32 v19, v24, v25
	s_waitcnt vmcnt(6)
	v_lshlrev_b32_e32 v22, 16, v72
	v_cvt_pk_bf16_f32 v20, v20, v21
	v_cvt_pk_bf16_f32 v21, v26, v27
	global_store_dwordx4 v[30:31], v[18:21], off offset:256 nt
	v_and_b32_e32 v23, 0xffff0000, v72
	v_lshlrev_b32_e32 v24, 16, v73
	v_lshlrev_b32_e32 v18, 16, v70
	v_and_b32_e32 v19, 0xffff0000, v70
	v_and_b32_e32 v25, 0xffff0000, v73
	v_pk_fma_f32 v[14:15], v[14:15], v[102:103], v[18:19]
	v_lshlrev_b32_e32 v20, 16, v71
	v_and_b32_e32 v21, 0xffff0000, v71
	v_pk_fma_f32 v[18:19], v[12:13], v[96:97], v[24:25]
	v_pk_fma_f32 v[12:13], v[10:11], v[94:95], v[22:23]
	v_cvt_pk_bf16_f32 v10, v14, v15
	v_lshl_add_u64 v[14:15], s[60:61], 0, v[74:75]
	v_pk_fma_f32 v[16:17], v[16:17], v[104:105], v[20:21]
	v_lshl_add_u64 v[14:15], v[14:15], 0, v[160:161]
	v_cvt_pk_bf16_f32 v11, v16, v17
	v_cvt_pk_bf16_f32 v12, v12, v13
	v_cvt_pk_bf16_f32 v13, v18, v19
	global_store_dwordx4 v[14:15], v[10:13], off nt
	s_waitcnt vmcnt(7)
	v_lshlrev_b32_e32 v16, 16, v68
	v_and_b32_e32 v17, 0xffff0000, v68
	v_lshlrev_b32_e32 v10, 16, v66
	v_and_b32_e32 v11, 0xffff0000, v66
	v_lshlrev_b32_e32 v18, 16, v69
	v_and_b32_e32 v19, 0xffff0000, v69
	v_lshlrev_b32_e32 v12, 16, v67
	v_and_b32_e32 v13, 0xffff0000, v67
	v_pk_fma_f32 v[6:7], v[6:7], v[86:87], v[10:11]
	v_pk_fma_f32 v[10:11], v[4:5], v[84:85], v[18:19]
	v_pk_fma_f32 v[4:5], v[2:3], v[82:83], v[16:17]
	v_pk_fma_f32 v[8:9], v[8:9], v[88:89], v[12:13]
	v_cvt_pk_bf16_f32 v2, v6, v7
	s_nop 0
	v_cvt_pk_bf16_f32 v3, v8, v9
	v_cvt_pk_bf16_f32 v4, v4, v5
	v_cvt_pk_bf16_f32 v5, v10, v11
	global_store_dwordx4 v[14:15], v[2:5], off offset:256 nt
	s_cbranch_vccnz .LBB0_2953
	s_and_b64 vcc, exec, s[6:7]
	s_cbranch_vccnz .LBB0_2952
	s_barrier
	s_branch .LBB0_2952
